# speedup vs baseline: 1.0122x; 1.0035x over previous
.LBB0_852:
	v_mul_f32_e32 v126, 0x3d93cd3a, v126
	v_mul_f32_e32 v127, 0x3d93cd3a, v127
	v_cvt_pk_bf16_f32 v126, v126, v127
	v_mul_f32_e32 v127, 0x3d93cd3a, v128
	v_mul_f32_e32 v128, 0x3d93cd3a, v129
	v_lshl_or_b32 v131, s34, 8, v217
	v_cvt_pk_bf16_f32 v127, v127, v128
	v_ashrrev_i32_e32 v128, 11, v130
	v_ashrrev_i32_e32 v132, 7, v131
	v_and_b32_e32 v128, -8, v128
	v_add_u32_e32 v128, v128, v132
	v_ashrrev_i32_e32 v129, 31, v128
	v_lshlrev_b64 v[128:129], 14, v[128:129]
	v_or_b32_e32 v128, v128, v136
	s_movk_i32 s2, 0x180
	v_mad_u64_u32 v[130:131], s[18:19], v128, s2, v[198:199]
	v_mul_f32_e32 v122, 0x3d93cd3a, v122
	v_mul_f32_e32 v123, 0x3d93cd3a, v123
	v_mul_f32_e32 v118, 0x3d93cd3a, v118
	v_mul_f32_e32 v119, 0x3d93cd3a, v119
	v_mul_f32_e32 v114, 0x3d93cd3a, v114
	v_mul_f32_e32 v115, 0x3d93cd3a, v115
	v_mad_i32_i24 v131, v129, s2, v131
	v_cvt_pk_bf16_f32 v122, v122, v123
	v_mul_f32_e32 v123, 0x3d93cd3a, v124
	v_cvt_pk_bf16_f32 v118, v118, v119
	v_mul_f32_e32 v119, 0x3d93cd3a, v120
	v_cvt_pk_bf16_f32 v114, v114, v115
	v_mul_f32_e32 v115, 0x3d93cd3a, v116
	v_mov_b32_e32 v150, v126
	v_mov_b32_e32 v151, v127
	v_mul_f32_e32 v124, 0x3d93cd3a, v125
	v_cvt_pk_bf16_f32 v123, v123, v124
	v_mov_b32_e32 v152, v122
	v_mov_b32_e32 v153, v123
	v_bfe_u32 v154, v182, 4, 1
	v_mul_u32_u24_e32 v154, 24, v154
	v_mov_b32_e32 v155, 0
	v_lshl_add_u64 v[156:157], v[130:131], 0, v[154:155]
	v_permlane16_swap_b32_e32 v150, v152
	v_permlane16_swap_b32_e32 v151, v153
	global_store_dwordx4 v[156:157], v[150:153], off
	v_mul_f32_e32 v120, 0x3d93cd3a, v121
	v_cvt_pk_bf16_f32 v119, v119, v120
	v_mov_b32_e32 v150, v118
	v_mov_b32_e32 v151, v119
	v_mul_f32_e32 v116, 0x3d93cd3a, v117
	v_cvt_pk_bf16_f32 v115, v115, v116
	v_mov_b32_e32 v152, v114
	v_mov_b32_e32 v153, v115
	v_bfe_u32 v154, v182, 4, 1
	v_mul_u32_u24_e32 v154, 24, v154
	v_mov_b32_e32 v155, 0
	v_lshl_add_u64 v[156:157], v[130:131], 0, v[154:155]
	v_permlane16_swap_b32_e32 v150, v152
	v_permlane16_swap_b32_e32 v151, v153
	global_store_dwordx4 v[156:157], v[150:153], off offset:64
	v_mul_f32_e32 v110, 0x3d93cd3a, v110
	v_mul_f32_e32 v111, 0x3d93cd3a, v111
	v_add_u32_e32 v114, s22, v210
	v_cvt_pk_bf16_f32 v110, v110, v111
	v_mul_f32_e32 v111, 0x3d93cd3a, v112
	v_mul_f32_e32 v112, 0x3d93cd3a, v113
	v_cvt_pk_bf16_f32 v111, v111, v112
	v_ashrrev_i32_e32 v112, 11, v114
	v_and_b32_e32 v112, -8, v112
	v_add_u32_e32 v112, v112, v132
	v_ashrrev_i32_e32 v113, 31, v112
	v_lshlrev_b64 v[112:113], 14, v[112:113]
	s_movk_i32 s18, 0x3f9f
	v_and_or_b32 v112, v114, s18, v112
	v_mad_u64_u32 v[114:115], s[18:19], v112, s2, v[198:199]
	v_mul_f32_e32 v106, 0x3d93cd3a, v106
	v_mul_f32_e32 v107, 0x3d93cd3a, v107
	v_mul_f32_e32 v102, 0x3d93cd3a, v102
	v_mul_f32_e32 v103, 0x3d93cd3a, v103
	v_mul_f32_e32 v98, 0x3d93cd3a, v98
	v_mul_f32_e32 v99, 0x3d93cd3a, v99
	v_mad_i32_i24 v115, v113, s2, v115
	v_cvt_pk_bf16_f32 v106, v106, v107
	v_mul_f32_e32 v107, 0x3d93cd3a, v108
	v_cvt_pk_bf16_f32 v102, v102, v103
	v_mul_f32_e32 v103, 0x3d93cd3a, v104
	v_cvt_pk_bf16_f32 v98, v98, v99
	v_mul_f32_e32 v99, 0x3d93cd3a, v100
	v_mov_b32_e32 v150, v110
	v_mov_b32_e32 v151, v111
	v_mul_f32_e32 v108, 0x3d93cd3a, v109
	v_cvt_pk_bf16_f32 v107, v107, v108
	v_mov_b32_e32 v152, v106
	v_mov_b32_e32 v153, v107
	v_bfe_u32 v154, v182, 4, 1
	v_mul_u32_u24_e32 v154, 24, v154
	v_mov_b32_e32 v155, 0
	v_lshl_add_u64 v[156:157], v[114:115], 0, v[154:155]
	v_permlane16_swap_b32_e32 v150, v152
	v_permlane16_swap_b32_e32 v151, v153
	global_store_dwordx4 v[156:157], v[150:153], off
	v_mul_f32_e32 v104, 0x3d93cd3a, v105
	v_cvt_pk_bf16_f32 v103, v103, v104
	v_mov_b32_e32 v150, v102
	v_mov_b32_e32 v151, v103
	v_mul_f32_e32 v100, 0x3d93cd3a, v101
	v_cvt_pk_bf16_f32 v99, v99, v100
	v_mov_b32_e32 v152, v98
	v_mov_b32_e32 v153, v99
	v_bfe_u32 v154, v182, 4, 1
	v_mul_u32_u24_e32 v154, 24, v154
	v_mov_b32_e32 v155, 0
	v_lshl_add_u64 v[156:157], v[114:115], 0, v[154:155]
	v_permlane16_swap_b32_e32 v150, v152
	v_permlane16_swap_b32_e32 v151, v153
	global_store_dwordx4 v[156:157], v[150:153], off offset:64
	v_mul_f32_e32 v94, 0x3d93cd3a, v94
	v_mul_f32_e32 v95, 0x3d93cd3a, v95
	v_add_u32_e32 v98, s22, v211
	v_cvt_pk_bf16_f32 v94, v94, v95
	v_mul_f32_e32 v95, 0x3d93cd3a, v96
	v_mul_f32_e32 v96, 0x3d93cd3a, v97
	v_cvt_pk_bf16_f32 v95, v95, v96
	v_ashrrev_i32_e32 v96, 11, v98
	v_and_b32_e32 v96, -8, v96
	v_add_u32_e32 v96, v96, v132
	v_ashrrev_i32_e32 v97, 31, v96
	v_lshlrev_b64 v[96:97], 14, v[96:97]
	s_movk_i32 s18, 0x3faf
	v_and_or_b32 v96, v98, s18, v96
	v_mad_u64_u32 v[98:99], s[18:19], v96, s2, v[198:199]
	v_mul_f32_e32 v90, 0x3d93cd3a, v90
	v_mul_f32_e32 v91, 0x3d93cd3a, v91
	v_mul_f32_e32 v86, 0x3d93cd3a, v86
	v_mul_f32_e32 v87, 0x3d93cd3a, v87
	v_mul_f32_e32 v82, 0x3d93cd3a, v82
	v_mul_f32_e32 v83, 0x3d93cd3a, v83
	v_mad_i32_i24 v99, v97, s2, v99
	v_cvt_pk_bf16_f32 v90, v90, v91
	v_mul_f32_e32 v91, 0x3d93cd3a, v92
	v_cvt_pk_bf16_f32 v86, v86, v87
	v_mul_f32_e32 v87, 0x3d93cd3a, v88
	v_cvt_pk_bf16_f32 v82, v82, v83
	v_mul_f32_e32 v83, 0x3d93cd3a, v84
	v_mov_b32_e32 v150, v94
	v_mov_b32_e32 v151, v95
	v_mul_f32_e32 v92, 0x3d93cd3a, v93
	v_cvt_pk_bf16_f32 v91, v91, v92
	v_mov_b32_e32 v152, v90
	v_mov_b32_e32 v153, v91
	v_bfe_u32 v154, v182, 4, 1
	v_mul_u32_u24_e32 v154, 24, v154
	v_mov_b32_e32 v155, 0
	v_lshl_add_u64 v[156:157], v[98:99], 0, v[154:155]
	v_permlane16_swap_b32_e32 v150, v152
	v_permlane16_swap_b32_e32 v151, v153
	global_store_dwordx4 v[156:157], v[150:153], off
	v_mul_f32_e32 v88, 0x3d93cd3a, v89
	v_cvt_pk_bf16_f32 v87, v87, v88
	v_mov_b32_e32 v150, v86
	v_mov_b32_e32 v151, v87
	v_mul_f32_e32 v84, 0x3d93cd3a, v85
	v_cvt_pk_bf16_f32 v83, v83, v84
	v_mov_b32_e32 v152, v82
	v_mov_b32_e32 v153, v83
	v_bfe_u32 v154, v182, 4, 1
	v_mul_u32_u24_e32 v154, 24, v154
	v_mov_b32_e32 v155, 0
	v_lshl_add_u64 v[156:157], v[98:99], 0, v[154:155]
	v_permlane16_swap_b32_e32 v150, v152
	v_permlane16_swap_b32_e32 v151, v153
	global_store_dwordx4 v[156:157], v[150:153], off offset:64
	v_mul_f32_e32 v78, 0x3d93cd3a, v78
	v_mul_f32_e32 v79, 0x3d93cd3a, v79
	v_add_u32_e32 v82, s22, v212
	v_cvt_pk_bf16_f32 v78, v78, v79
	v_mul_f32_e32 v79, 0x3d93cd3a, v80
	v_mul_f32_e32 v80, 0x3d93cd3a, v81
	v_cvt_pk_bf16_f32 v79, v79, v80
	v_ashrrev_i32_e32 v80, 11, v82
	v_and_b32_e32 v80, -8, v80
	v_add_u32_e32 v80, v80, v132
	v_ashrrev_i32_e32 v81, 31, v80
	v_lshlrev_b64 v[80:81], 14, v[80:81]
	s_movk_i32 s18, 0x3fbf
	v_and_or_b32 v80, v82, s18, v80
	v_mad_u64_u32 v[82:83], s[18:19], v80, s2, v[198:199]
	v_mul_f32_e32 v74, 0x3d93cd3a, v74
	v_mul_f32_e32 v75, 0x3d93cd3a, v75
	v_mul_f32_e32 v70, 0x3d93cd3a, v70
	v_mul_f32_e32 v71, 0x3d93cd3a, v71
	v_mul_f32_e32 v66, 0x3d93cd3a, v66
	v_mul_f32_e32 v67, 0x3d93cd3a, v67
	v_mad_i32_i24 v83, v81, s2, v83
	v_cvt_pk_bf16_f32 v74, v74, v75
	v_mul_f32_e32 v75, 0x3d93cd3a, v76
	v_cvt_pk_bf16_f32 v70, v70, v71
	v_mul_f32_e32 v71, 0x3d93cd3a, v72
	v_cvt_pk_bf16_f32 v66, v66, v67
	v_mul_f32_e32 v67, 0x3d93cd3a, v68
	v_mov_b32_e32 v150, v78
	v_mov_b32_e32 v151, v79
	v_mul_f32_e32 v76, 0x3d93cd3a, v77
	v_cvt_pk_bf16_f32 v75, v75, v76
	v_mov_b32_e32 v152, v74
	v_mov_b32_e32 v153, v75
	v_bfe_u32 v154, v182, 4, 1
	v_mul_u32_u24_e32 v154, 24, v154
	v_mov_b32_e32 v155, 0
	v_lshl_add_u64 v[156:157], v[82:83], 0, v[154:155]
	v_permlane16_swap_b32_e32 v150, v152
	v_permlane16_swap_b32_e32 v151, v153
	global_store_dwordx4 v[156:157], v[150:153], off
	v_mul_f32_e32 v72, 0x3d93cd3a, v73
	v_cvt_pk_bf16_f32 v71, v71, v72
	v_mov_b32_e32 v150, v70
	v_mov_b32_e32 v151, v71
	v_mul_f32_e32 v68, 0x3d93cd3a, v69
	v_cvt_pk_bf16_f32 v67, v67, v68
	v_mov_b32_e32 v152, v66
	v_mov_b32_e32 v153, v67
	v_bfe_u32 v154, v182, 4, 1
	v_mul_u32_u24_e32 v154, 24, v154
	v_mov_b32_e32 v155, 0
	v_lshl_add_u64 v[156:157], v[82:83], 0, v[154:155]
	v_permlane16_swap_b32_e32 v150, v152
	v_permlane16_swap_b32_e32 v151, v153
	global_store_dwordx4 v[156:157], v[150:153], off offset:64
	v_mul_f32_e32 v62, 0x3d93cd3a, v62
	v_mul_f32_e32 v63, 0x3d93cd3a, v63
	v_add_u32_e32 v66, s22, v213
	v_cvt_pk_bf16_f32 v62, v62, v63
	v_mul_f32_e32 v63, 0x3d93cd3a, v64
	v_mul_f32_e32 v64, 0x3d93cd3a, v65
	v_cvt_pk_bf16_f32 v63, v63, v64
	v_ashrrev_i32_e32 v64, 11, v66
	v_and_b32_e32 v64, -8, v64
	v_add_u32_e32 v64, v64, v132
	v_ashrrev_i32_e32 v65, 31, v64
	v_lshlrev_b64 v[64:65], 14, v[64:65]
	s_movk_i32 s18, 0x3fcf
	v_and_or_b32 v64, v66, s18, v64
	v_mad_u64_u32 v[66:67], s[18:19], v64, s2, v[198:199]
	v_mul_f32_e32 v58, 0x3d93cd3a, v58
	v_mul_f32_e32 v59, 0x3d93cd3a, v59
	v_mul_f32_e32 v54, 0x3d93cd3a, v54
	v_mul_f32_e32 v55, 0x3d93cd3a, v55
	v_mul_f32_e32 v50, 0x3d93cd3a, v50
	v_mul_f32_e32 v51, 0x3d93cd3a, v51
	v_mad_i32_i24 v67, v65, s2, v67
	v_cvt_pk_bf16_f32 v58, v58, v59
	v_mul_f32_e32 v59, 0x3d93cd3a, v60
	v_cvt_pk_bf16_f32 v54, v54, v55
	v_mul_f32_e32 v55, 0x3d93cd3a, v56
	v_cvt_pk_bf16_f32 v50, v50, v51
	v_mul_f32_e32 v51, 0x3d93cd3a, v52
	v_mov_b32_e32 v150, v62
	v_mov_b32_e32 v151, v63
	v_mul_f32_e32 v60, 0x3d93cd3a, v61
	v_cvt_pk_bf16_f32 v59, v59, v60
	v_mov_b32_e32 v152, v58
	v_mov_b32_e32 v153, v59
	v_bfe_u32 v154, v182, 4, 1
	v_mul_u32_u24_e32 v154, 24, v154
	v_mov_b32_e32 v155, 0
	v_lshl_add_u64 v[156:157], v[66:67], 0, v[154:155]
	v_permlane16_swap_b32_e32 v150, v152
	v_permlane16_swap_b32_e32 v151, v153
	global_store_dwordx4 v[156:157], v[150:153], off
	v_mul_f32_e32 v56, 0x3d93cd3a, v57
	v_cvt_pk_bf16_f32 v55, v55, v56
	v_mov_b32_e32 v150, v54
	v_mov_b32_e32 v151, v55
	v_mul_f32_e32 v52, 0x3d93cd3a, v53
	v_cvt_pk_bf16_f32 v51, v51, v52
	v_mov_b32_e32 v152, v50
	v_mov_b32_e32 v153, v51
	v_bfe_u32 v154, v182, 4, 1
	v_mul_u32_u24_e32 v154, 24, v154
	v_mov_b32_e32 v155, 0
	v_lshl_add_u64 v[156:157], v[66:67], 0, v[154:155]
	v_permlane16_swap_b32_e32 v150, v152
	v_permlane16_swap_b32_e32 v151, v153
	global_store_dwordx4 v[156:157], v[150:153], off offset:64
	v_mul_f32_e32 v46, 0x3d93cd3a, v46
	v_mul_f32_e32 v47, 0x3d93cd3a, v47
	v_add_u32_e32 v50, s22, v214
	v_cvt_pk_bf16_f32 v46, v46, v47
	v_mul_f32_e32 v47, 0x3d93cd3a, v48
	v_mul_f32_e32 v48, 0x3d93cd3a, v49
	v_cvt_pk_bf16_f32 v47, v47, v48
	v_ashrrev_i32_e32 v48, 11, v50
	v_and_b32_e32 v48, -8, v48
	v_add_u32_e32 v48, v48, v132
	v_ashrrev_i32_e32 v49, 31, v48
	v_lshlrev_b64 v[48:49], 14, v[48:49]
	s_movk_i32 s18, 0x3fdf
	v_and_or_b32 v48, v50, s18, v48
	v_mad_u64_u32 v[50:51], s[18:19], v48, s2, v[198:199]
	v_mul_f32_e32 v42, 0x3d93cd3a, v42
	v_mul_f32_e32 v43, 0x3d93cd3a, v43
	v_mul_f32_e32 v38, 0x3d93cd3a, v38
	v_mul_f32_e32 v39, 0x3d93cd3a, v39
	v_mul_f32_e32 v34, 0x3d93cd3a, v34
	v_mul_f32_e32 v35, 0x3d93cd3a, v35
	v_mad_i32_i24 v51, v49, s2, v51
	v_cvt_pk_bf16_f32 v42, v42, v43
	v_mul_f32_e32 v43, 0x3d93cd3a, v44
	v_cvt_pk_bf16_f32 v38, v38, v39
	v_mul_f32_e32 v39, 0x3d93cd3a, v40
	v_cvt_pk_bf16_f32 v34, v34, v35
	v_mul_f32_e32 v35, 0x3d93cd3a, v36
	v_mov_b32_e32 v150, v46
	v_mov_b32_e32 v151, v47
	v_mul_f32_e32 v44, 0x3d93cd3a, v45
	v_cvt_pk_bf16_f32 v43, v43, v44
	v_mov_b32_e32 v152, v42
	v_mov_b32_e32 v153, v43
	v_bfe_u32 v154, v182, 4, 1
	v_mul_u32_u24_e32 v154, 24, v154
	v_mov_b32_e32 v155, 0
	v_lshl_add_u64 v[156:157], v[50:51], 0, v[154:155]
	v_permlane16_swap_b32_e32 v150, v152
	v_permlane16_swap_b32_e32 v151, v153
	global_store_dwordx4 v[156:157], v[150:153], off
	v_mul_f32_e32 v40, 0x3d93cd3a, v41
	v_cvt_pk_bf16_f32 v39, v39, v40
	v_mov_b32_e32 v150, v38
	v_mov_b32_e32 v151, v39
	v_mul_f32_e32 v36, 0x3d93cd3a, v37
	v_cvt_pk_bf16_f32 v35, v35, v36
	v_mov_b32_e32 v152, v34
	v_mov_b32_e32 v153, v35
	v_bfe_u32 v154, v182, 4, 1
	v_mul_u32_u24_e32 v154, 24, v154
	v_mov_b32_e32 v155, 0
	v_lshl_add_u64 v[156:157], v[50:51], 0, v[154:155]
	v_permlane16_swap_b32_e32 v150, v152
	v_permlane16_swap_b32_e32 v151, v153
	global_store_dwordx4 v[156:157], v[150:153], off offset:64
	v_mul_f32_e32 v30, 0x3d93cd3a, v30
	v_mul_f32_e32 v31, 0x3d93cd3a, v31
	v_add_u32_e32 v34, s22, v215
	v_cvt_pk_bf16_f32 v30, v30, v31
	v_mul_f32_e32 v31, 0x3d93cd3a, v32
	v_mul_f32_e32 v32, 0x3d93cd3a, v33
	v_cvt_pk_bf16_f32 v31, v31, v32
	v_ashrrev_i32_e32 v32, 11, v34
	v_and_b32_e32 v32, -8, v32
	v_add_u32_e32 v32, v32, v132
	v_ashrrev_i32_e32 v33, 31, v32
	v_lshlrev_b64 v[32:33], 14, v[32:33]
	s_movk_i32 s18, 0x3fef
	v_and_or_b32 v32, v34, s18, v32
	v_mad_u64_u32 v[34:35], s[18:19], v32, s2, v[198:199]
	v_mul_f32_e32 v26, 0x3d93cd3a, v26
	v_mul_f32_e32 v27, 0x3d93cd3a, v27
	v_mul_f32_e32 v22, 0x3d93cd3a, v22
	v_mul_f32_e32 v23, 0x3d93cd3a, v23
	v_mul_f32_e32 v18, 0x3d93cd3a, v18
	v_mul_f32_e32 v19, 0x3d93cd3a, v19
	v_mad_i32_i24 v35, v33, s2, v35
	v_cvt_pk_bf16_f32 v26, v26, v27
	v_mul_f32_e32 v27, 0x3d93cd3a, v28
	v_cvt_pk_bf16_f32 v22, v22, v23
	v_mul_f32_e32 v23, 0x3d93cd3a, v24
	v_cvt_pk_bf16_f32 v18, v18, v19
	v_mul_f32_e32 v19, 0x3d93cd3a, v20
	v_mov_b32_e32 v150, v30
	v_mov_b32_e32 v151, v31
	v_mul_f32_e32 v28, 0x3d93cd3a, v29
	v_cvt_pk_bf16_f32 v27, v27, v28
	v_mov_b32_e32 v152, v26
	v_mov_b32_e32 v153, v27
	v_bfe_u32 v154, v182, 4, 1
	v_mul_u32_u24_e32 v154, 24, v154
	v_mov_b32_e32 v155, 0
	v_lshl_add_u64 v[156:157], v[34:35], 0, v[154:155]
	v_permlane16_swap_b32_e32 v150, v152
	v_permlane16_swap_b32_e32 v151, v153
	global_store_dwordx4 v[156:157], v[150:153], off
	v_mul_f32_e32 v24, 0x3d93cd3a, v25
	v_cvt_pk_bf16_f32 v23, v23, v24
	v_mov_b32_e32 v150, v22
	v_mov_b32_e32 v151, v23
	v_mul_f32_e32 v20, 0x3d93cd3a, v21
	v_cvt_pk_bf16_f32 v19, v19, v20
	v_mov_b32_e32 v152, v18
	v_mov_b32_e32 v153, v19
	v_bfe_u32 v154, v182, 4, 1
	v_mul_u32_u24_e32 v154, 24, v154
	v_mov_b32_e32 v155, 0
	v_lshl_add_u64 v[156:157], v[34:35], 0, v[154:155]
	v_permlane16_swap_b32_e32 v150, v152
	v_permlane16_swap_b32_e32 v151, v153
	global_store_dwordx4 v[156:157], v[150:153], off offset:64
	v_mul_f32_e32 v14, 0x3d93cd3a, v14
	v_mul_f32_e32 v15, 0x3d93cd3a, v15
	v_add_u32_e32 v18, s22, v216
	v_cvt_pk_bf16_f32 v14, v14, v15
	v_mul_f32_e32 v15, 0x3d93cd3a, v16
	v_mul_f32_e32 v16, 0x3d93cd3a, v17
	v_cvt_pk_bf16_f32 v15, v15, v16
	v_ashrrev_i32_e32 v16, 11, v18
	v_and_b32_e32 v16, -8, v16
	v_add_u32_e32 v16, v16, v132
	v_ashrrev_i32_e32 v17, 31, v16
	v_lshlrev_b64 v[16:17], 14, v[16:17]
	s_movk_i32 s18, 0x3fff
	v_and_or_b32 v16, v18, s18, v16
	v_mad_u64_u32 v[18:19], s[18:19], v16, s2, v[198:199]
	v_mul_f32_e32 v10, 0x3d93cd3a, v10
	v_mul_f32_e32 v11, 0x3d93cd3a, v11
	v_mul_f32_e32 v6, 0x3d93cd3a, v6
	v_mul_f32_e32 v7, 0x3d93cd3a, v7
	v_mul_f32_e32 v2, 0x3d93cd3a, v2
	v_mul_f32_e32 v3, 0x3d93cd3a, v3
	v_mad_i32_i24 v19, v17, s2, v19
	v_cvt_pk_bf16_f32 v10, v10, v11
	v_mul_f32_e32 v11, 0x3d93cd3a, v12
	v_cvt_pk_bf16_f32 v6, v6, v7
	v_mul_f32_e32 v7, 0x3d93cd3a, v8
	v_cvt_pk_bf16_f32 v2, v2, v3
	v_mul_f32_e32 v3, 0x3d93cd3a, v4
	v_mov_b32_e32 v150, v14
	v_mov_b32_e32 v151, v15
	v_mul_f32_e32 v12, 0x3d93cd3a, v13
	v_cvt_pk_bf16_f32 v11, v11, v12
	v_mov_b32_e32 v152, v10
	v_mov_b32_e32 v153, v11
	v_bfe_u32 v154, v182, 4, 1
	v_mul_u32_u24_e32 v154, 24, v154
	v_mov_b32_e32 v155, 0
	v_lshl_add_u64 v[156:157], v[18:19], 0, v[154:155]
	v_permlane16_swap_b32_e32 v150, v152
	v_permlane16_swap_b32_e32 v151, v153
	global_store_dwordx4 v[156:157], v[150:153], off
	v_mul_f32_e32 v8, 0x3d93cd3a, v9
	v_cvt_pk_bf16_f32 v7, v7, v8
	v_mov_b32_e32 v150, v6
	v_mov_b32_e32 v151, v7
	v_mul_f32_e32 v4, 0x3d93cd3a, v5
	v_cvt_pk_bf16_f32 v3, v3, v4
	v_mov_b32_e32 v152, v2
	v_mov_b32_e32 v153, v3
	v_bfe_u32 v154, v182, 4, 1
	v_mul_u32_u24_e32 v154, 24, v154
	v_mov_b32_e32 v155, 0
	v_lshl_add_u64 v[156:157], v[18:19], 0, v[154:155]
	v_permlane16_swap_b32_e32 v150, v152
	v_permlane16_swap_b32_e32 v151, v153
	global_store_dwordx4 v[156:157], v[150:153], off offset:64
	s_andn2_b64 vcc, exec, s[16:17]
	s_mov_b64 s[16:17], -1
	s_cbranch_vccnz .LBB0_827

.LBB0_1189:
	s_ashr_i32 s27, s26, 31
	s_lshl_b64 s[12:13], s[26:27], 26
	s_add_u32 s2, s92, s12
	s_addc_u32 s26, s93, s13
	s_ashr_i32 s25, s24, 31
	s_lshl_b64 s[12:13], s[24:25], 19
	s_add_u32 s2, s2, s12
	s_addc_u32 s12, s26, s13
	s_lshl_b32 s13, s41, 1
	s_add_u32 s24, s2, s13
	s_addc_u32 s25, s12, 0
	v_lshl_add_u64 v[128:129], s[24:25], 0, v[196:197]
	v_cvt_pk_bf16_f32 v126, v130, v131
	v_cvt_pk_bf16_f32 v127, v132, v133
	v_lshl_add_u64 v[130:131], v[128:129], 0, v[0:1]
	s_cmp_gt_i32 s40, 1
	s_mov_b64 s[12:13], -1
	v_mov_b32_e32 v140, v126
	v_mov_b32_e32 v141, v127
	s_cbranch_scc0 .LBB0_1191
	global_load_dwordx4 v[126:129], v134, s[22:23] offset:64
	v_mul_f32_e32 v133, 0xbfb8aa3b, v122
	v_exp_f32_e32 v133, v133
	s_mov_b32 s2, 0x3f317217
	s_mov_b32 s26, 0x7f800000
	v_add_f32_e32 v133, 1.0, v133
	v_rcp_f32_e32 v133, v133
	s_waitcnt vmcnt(0)
	v_sub_f32_e32 v132, 1.0, v126
	v_fma_f32 v126, v133, v132, v126
	v_cmp_gt_f32_e32 vcc, s7, v126
	v_mul_f32_e32 v133, 0xbfb8aa3b, v123
	v_exp_f32_e32 v133, v133
	v_cndmask_b32_e64 v132, 0, 32, vcc
	v_ldexp_f32 v126, v126, v132
	v_log_f32_e32 v126, v126
	v_add_f32_e32 v133, 1.0, v133
	v_rcp_f32_e32 v133, v133
	v_mul_f32_e32 v132, 0x3f317217, v126
	v_fma_f32 v132, v126, s2, -v132
	v_fmac_f32_e32 v132, 0x3377d1cf, v126
	v_fmac_f32_e32 v132, 0x3f317217, v126
	v_cmp_lt_f32_e64 s[12:13], |v126|, s26
	s_nop 1
	v_cndmask_b32_e64 v126, v126, v132, s[12:13]
	v_cndmask_b32_e32 v132, 0, v226, vcc
	v_sub_f32_e32 v126, v126, v132
	v_sub_f32_e32 v132, 1.0, v127
	v_fma_f32 v127, v133, v132, v127
	v_cmp_gt_f32_e32 vcc, s7, v127
	v_mul_f32_e32 v133, 0xbfb8aa3b, v124
	v_exp_f32_e32 v133, v133
	v_cndmask_b32_e64 v132, 0, 32, vcc
	v_ldexp_f32 v127, v127, v132
	v_log_f32_e32 v127, v127
	v_add_f32_e32 v133, 1.0, v133
	v_rcp_f32_e32 v133, v133
	v_mul_f32_e32 v132, 0x3f317217, v127
	v_fma_f32 v132, v127, s2, -v132
	v_fmac_f32_e32 v132, 0x3377d1cf, v127
	v_fmac_f32_e32 v132, 0x3f317217, v127
	v_cmp_lt_f32_e64 s[12:13], |v127|, s26
	s_nop 1
	v_cndmask_b32_e64 v127, v127, v132, s[12:13]
	v_cndmask_b32_e32 v132, 0, v226, vcc
	v_sub_f32_e32 v127, v127, v132
	v_sub_f32_e32 v132, 1.0, v128
	v_fma_f32 v128, v133, v132, v128
	v_cmp_gt_f32_e32 vcc, s7, v128
	v_mul_f32_e32 v133, 0xbfb8aa3b, v125
	v_exp_f32_e32 v133, v133
	v_cndmask_b32_e64 v132, 0, 32, vcc
	v_ldexp_f32 v128, v128, v132
	v_log_f32_e32 v128, v128
	v_add_f32_e32 v133, 1.0, v133
	v_rcp_f32_e32 v133, v133
	v_mul_f32_e32 v132, 0x3f317217, v128
	v_fma_f32 v132, v128, s2, -v132
	v_fmac_f32_e32 v132, 0x3377d1cf, v128
	v_fmac_f32_e32 v132, 0x3f317217, v128
	v_cmp_lt_f32_e64 s[12:13], |v128|, s26
	s_nop 1
	v_cndmask_b32_e64 v128, v128, v132, s[12:13]
	v_cndmask_b32_e32 v132, 0, v226, vcc
	v_sub_f32_e32 v128, v128, v132
	v_sub_f32_e32 v132, 1.0, v129
	v_fmac_f32_e32 v129, v133, v132
	v_cmp_gt_f32_e32 vcc, s7, v129
	s_nop 1
	v_cndmask_b32_e64 v132, 0, 32, vcc
	v_ldexp_f32 v129, v129, v132
	v_log_f32_e32 v129, v129
	s_nop 0
	v_mul_f32_e32 v132, 0x3f317217, v129
	v_fma_f32 v132, v129, s2, -v132
	v_fmac_f32_e32 v132, 0x3377d1cf, v129
	v_fmac_f32_e32 v132, 0x3f317217, v129
	v_cmp_lt_f32_e64 s[12:13], |v129|, s26
	s_nop 1
	v_cndmask_b32_e64 v129, v129, v132, s[12:13]
	v_cndmask_b32_e32 v132, 0, v226, vcc
	v_sub_f32_e32 v129, v129, v132
	s_mov_b64 s[12:13], 0

.LBB0_1195:
	v_cvt_pk_bf16_f32 v122, v126, v127
	v_cvt_pk_bf16_f32 v123, v128, v129
	s_cmp_gt_i32 s40, 1
	s_mov_b64 s[12:13], -1
	v_mov_b32_e32 v142, v122
	v_mov_b32_e32 v143, v123
	v_bfe_u32 v144, v182, 4, 1
	v_mul_u32_u24_e32 v144, 24, v144
	v_mov_b32_e32 v145, 0
	v_lshl_add_u64 v[146:147], v[130:131], 0, v[144:145]
	v_permlane16_swap_b32_e32 v140, v142
	v_permlane16_swap_b32_e32 v141, v143
	global_store_dwordx4 v[146:147], v[140:143], off
	s_cbranch_scc0 .LBB0_1197
	global_load_dwordx4 v[122:125], v134, s[22:23] offset:128
	v_mul_f32_e32 v127, 0xbfb8aa3b, v118
	v_exp_f32_e32 v127, v127
	s_mov_b32 s2, 0x3f317217
	s_mov_b32 s26, 0x7f800000
	v_add_f32_e32 v127, 1.0, v127
	v_rcp_f32_e32 v127, v127
	s_waitcnt vmcnt(0)
	v_sub_f32_e32 v126, 1.0, v122
	v_fma_f32 v122, v127, v126, v122
	v_cmp_gt_f32_e32 vcc, s7, v122
	v_mul_f32_e32 v127, 0xbfb8aa3b, v119
	v_exp_f32_e32 v127, v127
	v_cndmask_b32_e64 v126, 0, 32, vcc
	v_ldexp_f32 v122, v122, v126
	v_log_f32_e32 v122, v122
	v_add_f32_e32 v127, 1.0, v127
	v_rcp_f32_e32 v127, v127
	v_mul_f32_e32 v126, 0x3f317217, v122
	v_fma_f32 v126, v122, s2, -v126
	v_fmac_f32_e32 v126, 0x3377d1cf, v122
	v_fmac_f32_e32 v126, 0x3f317217, v122
	v_cmp_lt_f32_e64 s[12:13], |v122|, s26
	s_nop 1
	v_cndmask_b32_e64 v122, v122, v126, s[12:13]
	v_cndmask_b32_e32 v126, 0, v226, vcc
	v_sub_f32_e32 v122, v122, v126
	v_sub_f32_e32 v126, 1.0, v123
	v_fma_f32 v123, v127, v126, v123
	v_cmp_gt_f32_e32 vcc, s7, v123
	v_mul_f32_e32 v127, 0xbfb8aa3b, v120
	v_exp_f32_e32 v127, v127
	v_cndmask_b32_e64 v126, 0, 32, vcc
	v_ldexp_f32 v123, v123, v126
	v_log_f32_e32 v123, v123
	v_add_f32_e32 v127, 1.0, v127
	v_rcp_f32_e32 v127, v127
	v_mul_f32_e32 v126, 0x3f317217, v123
	v_fma_f32 v126, v123, s2, -v126
	v_fmac_f32_e32 v126, 0x3377d1cf, v123
	v_fmac_f32_e32 v126, 0x3f317217, v123
	v_cmp_lt_f32_e64 s[12:13], |v123|, s26
	s_nop 1
	v_cndmask_b32_e64 v123, v123, v126, s[12:13]
	v_cndmask_b32_e32 v126, 0, v226, vcc
	v_sub_f32_e32 v123, v123, v126
	v_sub_f32_e32 v126, 1.0, v124
	v_fma_f32 v124, v127, v126, v124
	v_cmp_gt_f32_e32 vcc, s7, v124
	v_mul_f32_e32 v127, 0xbfb8aa3b, v121
	v_exp_f32_e32 v127, v127
	v_cndmask_b32_e64 v126, 0, 32, vcc
	v_ldexp_f32 v124, v124, v126
	v_log_f32_e32 v124, v124
	v_add_f32_e32 v127, 1.0, v127
	v_rcp_f32_e32 v127, v127
	v_mul_f32_e32 v126, 0x3f317217, v124
	v_fma_f32 v126, v124, s2, -v126
	v_fmac_f32_e32 v126, 0x3377d1cf, v124
	v_fmac_f32_e32 v126, 0x3f317217, v124
	v_cmp_lt_f32_e64 s[12:13], |v124|, s26
	s_nop 1
	v_cndmask_b32_e64 v124, v124, v126, s[12:13]
	v_cndmask_b32_e32 v126, 0, v226, vcc
	v_sub_f32_e32 v124, v124, v126
	v_sub_f32_e32 v126, 1.0, v125
	v_fmac_f32_e32 v125, v127, v126
	v_cmp_gt_f32_e32 vcc, s7, v125
	s_nop 1
	v_cndmask_b32_e64 v126, 0, 32, vcc
	v_ldexp_f32 v125, v125, v126
	v_log_f32_e32 v125, v125
	s_nop 0
	v_mul_f32_e32 v126, 0x3f317217, v125
	v_fma_f32 v126, v125, s2, -v126
	v_fmac_f32_e32 v126, 0x3377d1cf, v125
	v_fmac_f32_e32 v126, 0x3f317217, v125
	v_cmp_lt_f32_e64 s[12:13], |v125|, s26
	s_nop 1
	v_cndmask_b32_e64 v125, v125, v126, s[12:13]
	v_cndmask_b32_e32 v126, 0, v226, vcc
	v_sub_f32_e32 v125, v125, v126
	s_mov_b64 s[12:13], 0

.LBB0_1201:
	v_cvt_pk_bf16_f32 v118, v122, v123
	v_cvt_pk_bf16_f32 v119, v124, v125
	s_cmp_gt_i32 s40, 1
	s_mov_b64 s[12:13], -1
	v_mov_b32_e32 v140, v118
	v_mov_b32_e32 v141, v119
	s_cbranch_scc0 .LBB0_1203
	global_load_dwordx4 v[118:121], v134, s[22:23] offset:192
	v_mul_f32_e32 v123, 0xbfb8aa3b, v114
	v_exp_f32_e32 v123, v123
	s_mov_b32 s2, 0x3f317217
	s_mov_b32 s26, 0x7f800000
	v_add_f32_e32 v123, 1.0, v123
	v_rcp_f32_e32 v123, v123
	s_waitcnt vmcnt(0)
	v_sub_f32_e32 v122, 1.0, v118
	v_fma_f32 v118, v123, v122, v118
	v_cmp_gt_f32_e32 vcc, s7, v118
	v_mul_f32_e32 v123, 0xbfb8aa3b, v115
	v_exp_f32_e32 v123, v123
	v_cndmask_b32_e64 v122, 0, 32, vcc
	v_ldexp_f32 v118, v118, v122
	v_log_f32_e32 v118, v118
	v_add_f32_e32 v123, 1.0, v123
	v_rcp_f32_e32 v123, v123
	v_mul_f32_e32 v122, 0x3f317217, v118
	v_fma_f32 v122, v118, s2, -v122
	v_fmac_f32_e32 v122, 0x3377d1cf, v118
	v_fmac_f32_e32 v122, 0x3f317217, v118
	v_cmp_lt_f32_e64 s[12:13], |v118|, s26
	s_nop 1
	v_cndmask_b32_e64 v118, v118, v122, s[12:13]
	v_cndmask_b32_e32 v122, 0, v226, vcc
	v_sub_f32_e32 v118, v118, v122
	v_sub_f32_e32 v122, 1.0, v119
	v_fma_f32 v119, v123, v122, v119
	v_cmp_gt_f32_e32 vcc, s7, v119
	v_mul_f32_e32 v123, 0xbfb8aa3b, v116
	v_exp_f32_e32 v123, v123
	v_cndmask_b32_e64 v122, 0, 32, vcc
	v_ldexp_f32 v119, v119, v122
	v_log_f32_e32 v119, v119
	v_add_f32_e32 v123, 1.0, v123
	v_rcp_f32_e32 v123, v123
	v_mul_f32_e32 v122, 0x3f317217, v119
	v_fma_f32 v122, v119, s2, -v122
	v_fmac_f32_e32 v122, 0x3377d1cf, v119
	v_fmac_f32_e32 v122, 0x3f317217, v119
	v_cmp_lt_f32_e64 s[12:13], |v119|, s26
	s_nop 1
	v_cndmask_b32_e64 v119, v119, v122, s[12:13]
	v_cndmask_b32_e32 v122, 0, v226, vcc
	v_sub_f32_e32 v119, v119, v122
	v_sub_f32_e32 v122, 1.0, v120
	v_fma_f32 v120, v123, v122, v120
	v_cmp_gt_f32_e32 vcc, s7, v120
	v_mul_f32_e32 v123, 0xbfb8aa3b, v117
	v_exp_f32_e32 v123, v123
	v_cndmask_b32_e64 v122, 0, 32, vcc
	v_ldexp_f32 v120, v120, v122
	v_log_f32_e32 v120, v120
	v_add_f32_e32 v123, 1.0, v123
	v_rcp_f32_e32 v123, v123
	v_mul_f32_e32 v122, 0x3f317217, v120
	v_fma_f32 v122, v120, s2, -v122
	v_fmac_f32_e32 v122, 0x3377d1cf, v120
	v_fmac_f32_e32 v122, 0x3f317217, v120
	v_cmp_lt_f32_e64 s[12:13], |v120|, s26
	s_nop 1
	v_cndmask_b32_e64 v120, v120, v122, s[12:13]
	v_cndmask_b32_e32 v122, 0, v226, vcc
	v_sub_f32_e32 v120, v120, v122
	v_sub_f32_e32 v122, 1.0, v121
	v_fmac_f32_e32 v121, v123, v122
	v_cmp_gt_f32_e32 vcc, s7, v121
	s_nop 1
	v_cndmask_b32_e64 v122, 0, 32, vcc
	v_ldexp_f32 v121, v121, v122
	v_log_f32_e32 v121, v121
	s_nop 0
	v_mul_f32_e32 v122, 0x3f317217, v121
	v_fma_f32 v122, v121, s2, -v122
	v_fmac_f32_e32 v122, 0x3377d1cf, v121
	v_fmac_f32_e32 v122, 0x3f317217, v121
	v_cmp_lt_f32_e64 s[12:13], |v121|, s26
	s_nop 1
	v_cndmask_b32_e64 v121, v121, v122, s[12:13]
	v_cndmask_b32_e32 v122, 0, v226, vcc
	v_sub_f32_e32 v121, v121, v122
	s_mov_b64 s[12:13], 0

.LBB0_1207:
	v_cvt_pk_bf16_f32 v114, v118, v119
	v_cvt_pk_bf16_f32 v115, v120, v121
	v_mov_b32_e32 v142, v114
	v_mov_b32_e32 v143, v115
	v_bfe_u32 v144, v182, 4, 1
	v_mul_u32_u24_e32 v144, 24, v144
	v_mov_b32_e32 v145, 0
	v_lshl_add_u64 v[146:147], v[130:131], 0, v[144:145]
	v_permlane16_swap_b32_e32 v140, v142
	v_permlane16_swap_b32_e32 v141, v143
	global_store_dwordx4 v[146:147], v[140:143], off offset:64
	s_cmp_gt_i32 s40, 1
	s_mov_b64 s[12:13], -1
	s_cbranch_scc0 .LBB0_1209
	global_load_dwordx4 v[114:117], v134, s[22:23]
	v_mul_f32_e32 v119, 0xbfb8aa3b, v110
	v_exp_f32_e32 v119, v119
	s_mov_b32 s2, 0x3f317217
	s_mov_b32 s26, 0x7f800000
	v_add_f32_e32 v119, 1.0, v119
	v_rcp_f32_e32 v119, v119
	s_waitcnt vmcnt(0)
	v_sub_f32_e32 v118, 1.0, v114
	v_fma_f32 v114, v119, v118, v114
	v_cmp_gt_f32_e32 vcc, s7, v114
	v_mul_f32_e32 v119, 0xbfb8aa3b, v111
	v_exp_f32_e32 v119, v119
	v_cndmask_b32_e64 v118, 0, 32, vcc
	v_ldexp_f32 v114, v114, v118
	v_log_f32_e32 v114, v114
	v_add_f32_e32 v119, 1.0, v119
	v_rcp_f32_e32 v119, v119
	v_mul_f32_e32 v118, 0x3f317217, v114
	v_fma_f32 v118, v114, s2, -v118
	v_fmac_f32_e32 v118, 0x3377d1cf, v114
	v_fmac_f32_e32 v118, 0x3f317217, v114
	v_cmp_lt_f32_e64 s[12:13], |v114|, s26
	s_nop 1
	v_cndmask_b32_e64 v114, v114, v118, s[12:13]
	v_cndmask_b32_e32 v118, 0, v226, vcc
	v_sub_f32_e32 v114, v114, v118
	v_sub_f32_e32 v118, 1.0, v115
	v_fma_f32 v115, v119, v118, v115
	v_cmp_gt_f32_e32 vcc, s7, v115
	v_mul_f32_e32 v119, 0xbfb8aa3b, v112
	v_exp_f32_e32 v119, v119
	v_cndmask_b32_e64 v118, 0, 32, vcc
	v_ldexp_f32 v115, v115, v118
	v_log_f32_e32 v115, v115
	v_add_f32_e32 v119, 1.0, v119
	v_rcp_f32_e32 v119, v119
	v_mul_f32_e32 v118, 0x3f317217, v115
	v_fma_f32 v118, v115, s2, -v118
	v_fmac_f32_e32 v118, 0x3377d1cf, v115
	v_fmac_f32_e32 v118, 0x3f317217, v115
	v_cmp_lt_f32_e64 s[12:13], |v115|, s26
	s_nop 1
	v_cndmask_b32_e64 v115, v115, v118, s[12:13]
	v_cndmask_b32_e32 v118, 0, v226, vcc
	v_sub_f32_e32 v115, v115, v118
	v_sub_f32_e32 v118, 1.0, v116
	v_fma_f32 v116, v119, v118, v116
	v_cmp_gt_f32_e32 vcc, s7, v116
	v_mul_f32_e32 v119, 0xbfb8aa3b, v113
	v_exp_f32_e32 v119, v119
	v_cndmask_b32_e64 v118, 0, 32, vcc
	v_ldexp_f32 v116, v116, v118
	v_log_f32_e32 v116, v116
	v_add_f32_e32 v119, 1.0, v119
	v_rcp_f32_e32 v119, v119
	v_mul_f32_e32 v118, 0x3f317217, v116
	v_fma_f32 v118, v116, s2, -v118
	v_fmac_f32_e32 v118, 0x3377d1cf, v116
	v_fmac_f32_e32 v118, 0x3f317217, v116
	v_cmp_lt_f32_e64 s[12:13], |v116|, s26
	s_nop 1
	v_cndmask_b32_e64 v116, v116, v118, s[12:13]
	v_cndmask_b32_e32 v118, 0, v226, vcc
	v_sub_f32_e32 v116, v116, v118
	v_sub_f32_e32 v118, 1.0, v117
	v_fmac_f32_e32 v117, v119, v118
	v_cmp_gt_f32_e32 vcc, s7, v117
	s_nop 1
	v_cndmask_b32_e64 v118, 0, 32, vcc
	v_ldexp_f32 v117, v117, v118
	v_log_f32_e32 v117, v117
	s_nop 0
	v_mul_f32_e32 v118, 0x3f317217, v117
	v_fma_f32 v118, v117, s2, -v118
	v_fmac_f32_e32 v118, 0x3377d1cf, v117
	v_fmac_f32_e32 v118, 0x3f317217, v117
	v_cmp_lt_f32_e64 s[12:13], |v117|, s26
	s_nop 1
	v_cndmask_b32_e64 v117, v117, v118, s[12:13]
	v_cndmask_b32_e32 v118, 0, v226, vcc
	v_sub_f32_e32 v117, v117, v118
	s_mov_b64 s[12:13], 0

.LBB0_1213:
	v_lshl_add_u64 v[112:113], s[24:25], 0, v[198:199]
	v_cvt_pk_bf16_f32 v110, v114, v115
	v_cvt_pk_bf16_f32 v111, v116, v117
	v_lshl_add_u64 v[114:115], v[112:113], 0, v[0:1]
	s_cmp_gt_i32 s40, 1
	s_mov_b64 s[12:13], -1
	v_mov_b32_e32 v140, v110
	v_mov_b32_e32 v141, v111
	s_cbranch_scc0 .LBB0_1215
	global_load_dwordx4 v[110:113], v134, s[22:23] offset:64
	v_mul_f32_e32 v117, 0xbfb8aa3b, v106
	v_exp_f32_e32 v117, v117
	s_mov_b32 s2, 0x3f317217
	s_mov_b32 s26, 0x7f800000
	v_add_f32_e32 v117, 1.0, v117
	v_rcp_f32_e32 v117, v117
	s_waitcnt vmcnt(0)
	v_sub_f32_e32 v116, 1.0, v110
	v_fma_f32 v110, v117, v116, v110
	v_cmp_gt_f32_e32 vcc, s7, v110
	v_mul_f32_e32 v117, 0xbfb8aa3b, v107
	v_exp_f32_e32 v117, v117
	v_cndmask_b32_e64 v116, 0, 32, vcc
	v_ldexp_f32 v110, v110, v116
	v_log_f32_e32 v110, v110
	v_add_f32_e32 v117, 1.0, v117
	v_rcp_f32_e32 v117, v117
	v_mul_f32_e32 v116, 0x3f317217, v110
	v_fma_f32 v116, v110, s2, -v116
	v_fmac_f32_e32 v116, 0x3377d1cf, v110
	v_fmac_f32_e32 v116, 0x3f317217, v110
	v_cmp_lt_f32_e64 s[12:13], |v110|, s26
	s_nop 1
	v_cndmask_b32_e64 v110, v110, v116, s[12:13]
	v_cndmask_b32_e32 v116, 0, v226, vcc
	v_sub_f32_e32 v110, v110, v116
	v_sub_f32_e32 v116, 1.0, v111
	v_fma_f32 v111, v117, v116, v111
	v_cmp_gt_f32_e32 vcc, s7, v111
	v_mul_f32_e32 v117, 0xbfb8aa3b, v108
	v_exp_f32_e32 v117, v117
	v_cndmask_b32_e64 v116, 0, 32, vcc
	v_ldexp_f32 v111, v111, v116
	v_log_f32_e32 v111, v111
	v_add_f32_e32 v117, 1.0, v117
	v_rcp_f32_e32 v117, v117
	v_mul_f32_e32 v116, 0x3f317217, v111
	v_fma_f32 v116, v111, s2, -v116
	v_fmac_f32_e32 v116, 0x3377d1cf, v111
	v_fmac_f32_e32 v116, 0x3f317217, v111
	v_cmp_lt_f32_e64 s[12:13], |v111|, s26
	s_nop 1
	v_cndmask_b32_e64 v111, v111, v116, s[12:13]
	v_cndmask_b32_e32 v116, 0, v226, vcc
	v_sub_f32_e32 v111, v111, v116
	v_sub_f32_e32 v116, 1.0, v112
	v_fma_f32 v112, v117, v116, v112
	v_cmp_gt_f32_e32 vcc, s7, v112
	v_mul_f32_e32 v117, 0xbfb8aa3b, v109
	v_exp_f32_e32 v117, v117
	v_cndmask_b32_e64 v116, 0, 32, vcc
	v_ldexp_f32 v112, v112, v116
	v_log_f32_e32 v112, v112
	v_add_f32_e32 v117, 1.0, v117
	v_rcp_f32_e32 v117, v117
	v_mul_f32_e32 v116, 0x3f317217, v112
	v_fma_f32 v116, v112, s2, -v116
	v_fmac_f32_e32 v116, 0x3377d1cf, v112
	v_fmac_f32_e32 v116, 0x3f317217, v112
	v_cmp_lt_f32_e64 s[12:13], |v112|, s26
	s_nop 1
	v_cndmask_b32_e64 v112, v112, v116, s[12:13]
	v_cndmask_b32_e32 v116, 0, v226, vcc
	v_sub_f32_e32 v112, v112, v116
	v_sub_f32_e32 v116, 1.0, v113
	v_fmac_f32_e32 v113, v117, v116
	v_cmp_gt_f32_e32 vcc, s7, v113
	s_nop 1
	v_cndmask_b32_e64 v116, 0, 32, vcc
	v_ldexp_f32 v113, v113, v116
	v_log_f32_e32 v113, v113
	s_nop 0
	v_mul_f32_e32 v116, 0x3f317217, v113
	v_fma_f32 v116, v113, s2, -v116
	v_fmac_f32_e32 v116, 0x3377d1cf, v113
	v_fmac_f32_e32 v116, 0x3f317217, v113
	v_cmp_lt_f32_e64 s[12:13], |v113|, s26
	s_nop 1
	v_cndmask_b32_e64 v113, v113, v116, s[12:13]
	v_cndmask_b32_e32 v116, 0, v226, vcc
	v_sub_f32_e32 v113, v113, v116
	s_mov_b64 s[12:13], 0

.LBB0_1219:
	v_cvt_pk_bf16_f32 v106, v110, v111
	v_cvt_pk_bf16_f32 v107, v112, v113
	s_cmp_gt_i32 s40, 1
	s_mov_b64 s[12:13], -1
	v_mov_b32_e32 v142, v106
	v_mov_b32_e32 v143, v107
	v_bfe_u32 v144, v182, 4, 1
	v_mul_u32_u24_e32 v144, 24, v144
	v_mov_b32_e32 v145, 0
	v_lshl_add_u64 v[146:147], v[114:115], 0, v[144:145]
	v_permlane16_swap_b32_e32 v140, v142
	v_permlane16_swap_b32_e32 v141, v143
	global_store_dwordx4 v[146:147], v[140:143], off
	s_cbranch_scc0 .LBB0_1221
	global_load_dwordx4 v[106:109], v134, s[22:23] offset:128
	v_mul_f32_e32 v111, 0xbfb8aa3b, v102
	v_exp_f32_e32 v111, v111
	s_mov_b32 s2, 0x3f317217
	s_mov_b32 s26, 0x7f800000
	v_add_f32_e32 v111, 1.0, v111
	v_rcp_f32_e32 v111, v111
	s_waitcnt vmcnt(0)
	v_sub_f32_e32 v110, 1.0, v106
	v_fma_f32 v106, v111, v110, v106
	v_cmp_gt_f32_e32 vcc, s7, v106
	v_mul_f32_e32 v111, 0xbfb8aa3b, v103
	v_exp_f32_e32 v111, v111
	v_cndmask_b32_e64 v110, 0, 32, vcc
	v_ldexp_f32 v106, v106, v110
	v_log_f32_e32 v106, v106
	v_add_f32_e32 v111, 1.0, v111
	v_rcp_f32_e32 v111, v111
	v_mul_f32_e32 v110, 0x3f317217, v106
	v_fma_f32 v110, v106, s2, -v110
	v_fmac_f32_e32 v110, 0x3377d1cf, v106
	v_fmac_f32_e32 v110, 0x3f317217, v106
	v_cmp_lt_f32_e64 s[12:13], |v106|, s26
	s_nop 1
	v_cndmask_b32_e64 v106, v106, v110, s[12:13]
	v_cndmask_b32_e32 v110, 0, v226, vcc
	v_sub_f32_e32 v106, v106, v110
	v_sub_f32_e32 v110, 1.0, v107
	v_fma_f32 v107, v111, v110, v107
	v_cmp_gt_f32_e32 vcc, s7, v107
	v_mul_f32_e32 v111, 0xbfb8aa3b, v104
	v_exp_f32_e32 v111, v111
	v_cndmask_b32_e64 v110, 0, 32, vcc
	v_ldexp_f32 v107, v107, v110
	v_log_f32_e32 v107, v107
	v_add_f32_e32 v111, 1.0, v111
	v_rcp_f32_e32 v111, v111
	v_mul_f32_e32 v110, 0x3f317217, v107
	v_fma_f32 v110, v107, s2, -v110
	v_fmac_f32_e32 v110, 0x3377d1cf, v107
	v_fmac_f32_e32 v110, 0x3f317217, v107
	v_cmp_lt_f32_e64 s[12:13], |v107|, s26
	s_nop 1
	v_cndmask_b32_e64 v107, v107, v110, s[12:13]
	v_cndmask_b32_e32 v110, 0, v226, vcc
	v_sub_f32_e32 v107, v107, v110
	v_sub_f32_e32 v110, 1.0, v108
	v_fma_f32 v108, v111, v110, v108
	v_cmp_gt_f32_e32 vcc, s7, v108
	v_mul_f32_e32 v111, 0xbfb8aa3b, v105
	v_exp_f32_e32 v111, v111
	v_cndmask_b32_e64 v110, 0, 32, vcc
	v_ldexp_f32 v108, v108, v110
	v_log_f32_e32 v108, v108
	v_add_f32_e32 v111, 1.0, v111
	v_rcp_f32_e32 v111, v111
	v_mul_f32_e32 v110, 0x3f317217, v108
	v_fma_f32 v110, v108, s2, -v110
	v_fmac_f32_e32 v110, 0x3377d1cf, v108
	v_fmac_f32_e32 v110, 0x3f317217, v108
	v_cmp_lt_f32_e64 s[12:13], |v108|, s26
	s_nop 1
	v_cndmask_b32_e64 v108, v108, v110, s[12:13]
	v_cndmask_b32_e32 v110, 0, v226, vcc
	v_sub_f32_e32 v108, v108, v110
	v_sub_f32_e32 v110, 1.0, v109
	v_fmac_f32_e32 v109, v111, v110
	v_cmp_gt_f32_e32 vcc, s7, v109
	s_nop 1
	v_cndmask_b32_e64 v110, 0, 32, vcc
	v_ldexp_f32 v109, v109, v110
	v_log_f32_e32 v109, v109
	s_nop 0
	v_mul_f32_e32 v110, 0x3f317217, v109
	v_fma_f32 v110, v109, s2, -v110
	v_fmac_f32_e32 v110, 0x3377d1cf, v109
	v_fmac_f32_e32 v110, 0x3f317217, v109
	v_cmp_lt_f32_e64 s[12:13], |v109|, s26
	s_nop 1
	v_cndmask_b32_e64 v109, v109, v110, s[12:13]
	v_cndmask_b32_e32 v110, 0, v226, vcc
	v_sub_f32_e32 v109, v109, v110
	s_mov_b64 s[12:13], 0

.LBB0_1225:
	v_cvt_pk_bf16_f32 v102, v106, v107
	v_cvt_pk_bf16_f32 v103, v108, v109
	s_cmp_gt_i32 s40, 1
	s_mov_b64 s[12:13], -1
	v_mov_b32_e32 v140, v102
	v_mov_b32_e32 v141, v103
	s_cbranch_scc0 .LBB0_1227
	global_load_dwordx4 v[102:105], v134, s[22:23] offset:192
	v_mul_f32_e32 v107, 0xbfb8aa3b, v98
	v_exp_f32_e32 v107, v107
	s_mov_b32 s2, 0x3f317217
	s_mov_b32 s26, 0x7f800000
	v_add_f32_e32 v107, 1.0, v107
	v_rcp_f32_e32 v107, v107
	s_waitcnt vmcnt(0)
	v_sub_f32_e32 v106, 1.0, v102
	v_fma_f32 v102, v107, v106, v102
	v_cmp_gt_f32_e32 vcc, s7, v102
	v_mul_f32_e32 v107, 0xbfb8aa3b, v99
	v_exp_f32_e32 v107, v107
	v_cndmask_b32_e64 v106, 0, 32, vcc
	v_ldexp_f32 v102, v102, v106
	v_log_f32_e32 v102, v102
	v_add_f32_e32 v107, 1.0, v107
	v_rcp_f32_e32 v107, v107
	v_mul_f32_e32 v106, 0x3f317217, v102
	v_fma_f32 v106, v102, s2, -v106
	v_fmac_f32_e32 v106, 0x3377d1cf, v102
	v_fmac_f32_e32 v106, 0x3f317217, v102
	v_cmp_lt_f32_e64 s[12:13], |v102|, s26
	s_nop 1
	v_cndmask_b32_e64 v102, v102, v106, s[12:13]
	v_cndmask_b32_e32 v106, 0, v226, vcc
	v_sub_f32_e32 v102, v102, v106
	v_sub_f32_e32 v106, 1.0, v103
	v_fma_f32 v103, v107, v106, v103
	v_cmp_gt_f32_e32 vcc, s7, v103
	v_mul_f32_e32 v107, 0xbfb8aa3b, v100
	v_exp_f32_e32 v107, v107
	v_cndmask_b32_e64 v106, 0, 32, vcc
	v_ldexp_f32 v103, v103, v106
	v_log_f32_e32 v103, v103
	v_add_f32_e32 v107, 1.0, v107
	v_rcp_f32_e32 v107, v107
	v_mul_f32_e32 v106, 0x3f317217, v103
	v_fma_f32 v106, v103, s2, -v106
	v_fmac_f32_e32 v106, 0x3377d1cf, v103
	v_fmac_f32_e32 v106, 0x3f317217, v103
	v_cmp_lt_f32_e64 s[12:13], |v103|, s26
	s_nop 1
	v_cndmask_b32_e64 v103, v103, v106, s[12:13]
	v_cndmask_b32_e32 v106, 0, v226, vcc
	v_sub_f32_e32 v103, v103, v106
	v_sub_f32_e32 v106, 1.0, v104
	v_fma_f32 v104, v107, v106, v104
	v_cmp_gt_f32_e32 vcc, s7, v104
	v_mul_f32_e32 v107, 0xbfb8aa3b, v101
	v_exp_f32_e32 v107, v107
	v_cndmask_b32_e64 v106, 0, 32, vcc
	v_ldexp_f32 v104, v104, v106
	v_log_f32_e32 v104, v104
	v_add_f32_e32 v107, 1.0, v107
	v_rcp_f32_e32 v107, v107
	v_mul_f32_e32 v106, 0x3f317217, v104
	v_fma_f32 v106, v104, s2, -v106
	v_fmac_f32_e32 v106, 0x3377d1cf, v104
	v_fmac_f32_e32 v106, 0x3f317217, v104
	v_cmp_lt_f32_e64 s[12:13], |v104|, s26
	s_nop 1
	v_cndmask_b32_e64 v104, v104, v106, s[12:13]
	v_cndmask_b32_e32 v106, 0, v226, vcc
	v_sub_f32_e32 v104, v104, v106
	v_sub_f32_e32 v106, 1.0, v105
	v_fmac_f32_e32 v105, v107, v106
	v_cmp_gt_f32_e32 vcc, s7, v105
	s_nop 1
	v_cndmask_b32_e64 v106, 0, 32, vcc
	v_ldexp_f32 v105, v105, v106
	v_log_f32_e32 v105, v105
	s_nop 0
	v_mul_f32_e32 v106, 0x3f317217, v105
	v_fma_f32 v106, v105, s2, -v106
	v_fmac_f32_e32 v106, 0x3377d1cf, v105
	v_fmac_f32_e32 v106, 0x3f317217, v105
	v_cmp_lt_f32_e64 s[12:13], |v105|, s26
	s_nop 1
	v_cndmask_b32_e64 v105, v105, v106, s[12:13]
	v_cndmask_b32_e32 v106, 0, v226, vcc
	v_sub_f32_e32 v105, v105, v106
	s_mov_b64 s[12:13], 0

.LBB0_1231:
	v_cvt_pk_bf16_f32 v98, v102, v103
	v_cvt_pk_bf16_f32 v99, v104, v105
	v_mov_b32_e32 v142, v98
	v_mov_b32_e32 v143, v99
	v_bfe_u32 v144, v182, 4, 1
	v_mul_u32_u24_e32 v144, 24, v144
	v_mov_b32_e32 v145, 0
	v_lshl_add_u64 v[146:147], v[114:115], 0, v[144:145]
	v_permlane16_swap_b32_e32 v140, v142
	v_permlane16_swap_b32_e32 v141, v143
	global_store_dwordx4 v[146:147], v[140:143], off offset:64
	s_cmp_gt_i32 s40, 1
	s_mov_b64 s[12:13], -1
	s_cbranch_scc0 .LBB0_1233
	global_load_dwordx4 v[98:101], v134, s[22:23]
	v_mul_f32_e32 v103, 0xbfb8aa3b, v94
	v_exp_f32_e32 v103, v103
	s_mov_b32 s2, 0x3f317217
	s_mov_b32 s26, 0x7f800000
	v_add_f32_e32 v103, 1.0, v103
	v_rcp_f32_e32 v103, v103
	s_waitcnt vmcnt(0)
	v_sub_f32_e32 v102, 1.0, v98
	v_fma_f32 v98, v103, v102, v98
	v_cmp_gt_f32_e32 vcc, s7, v98
	v_mul_f32_e32 v103, 0xbfb8aa3b, v95
	v_exp_f32_e32 v103, v103
	v_cndmask_b32_e64 v102, 0, 32, vcc
	v_ldexp_f32 v98, v98, v102
	v_log_f32_e32 v98, v98
	v_add_f32_e32 v103, 1.0, v103
	v_rcp_f32_e32 v103, v103
	v_mul_f32_e32 v102, 0x3f317217, v98
	v_fma_f32 v102, v98, s2, -v102
	v_fmac_f32_e32 v102, 0x3377d1cf, v98
	v_fmac_f32_e32 v102, 0x3f317217, v98
	v_cmp_lt_f32_e64 s[12:13], |v98|, s26
	s_nop 1
	v_cndmask_b32_e64 v98, v98, v102, s[12:13]
	v_cndmask_b32_e32 v102, 0, v226, vcc
	v_sub_f32_e32 v98, v98, v102
	v_sub_f32_e32 v102, 1.0, v99
	v_fma_f32 v99, v103, v102, v99
	v_cmp_gt_f32_e32 vcc, s7, v99
	v_mul_f32_e32 v103, 0xbfb8aa3b, v96
	v_exp_f32_e32 v103, v103
	v_cndmask_b32_e64 v102, 0, 32, vcc
	v_ldexp_f32 v99, v99, v102
	v_log_f32_e32 v99, v99
	v_add_f32_e32 v103, 1.0, v103
	v_rcp_f32_e32 v103, v103
	v_mul_f32_e32 v102, 0x3f317217, v99
	v_fma_f32 v102, v99, s2, -v102
	v_fmac_f32_e32 v102, 0x3377d1cf, v99
	v_fmac_f32_e32 v102, 0x3f317217, v99
	v_cmp_lt_f32_e64 s[12:13], |v99|, s26
	s_nop 1
	v_cndmask_b32_e64 v99, v99, v102, s[12:13]
	v_cndmask_b32_e32 v102, 0, v226, vcc
	v_sub_f32_e32 v99, v99, v102
	v_sub_f32_e32 v102, 1.0, v100
	v_fma_f32 v100, v103, v102, v100
	v_cmp_gt_f32_e32 vcc, s7, v100
	v_mul_f32_e32 v103, 0xbfb8aa3b, v97
	v_exp_f32_e32 v103, v103
	v_cndmask_b32_e64 v102, 0, 32, vcc
	v_ldexp_f32 v100, v100, v102
	v_log_f32_e32 v100, v100
	v_add_f32_e32 v103, 1.0, v103
	v_rcp_f32_e32 v103, v103
	v_mul_f32_e32 v102, 0x3f317217, v100
	v_fma_f32 v102, v100, s2, -v102
	v_fmac_f32_e32 v102, 0x3377d1cf, v100
	v_fmac_f32_e32 v102, 0x3f317217, v100
	v_cmp_lt_f32_e64 s[12:13], |v100|, s26
	s_nop 1
	v_cndmask_b32_e64 v100, v100, v102, s[12:13]
	v_cndmask_b32_e32 v102, 0, v226, vcc
	v_sub_f32_e32 v100, v100, v102
	v_sub_f32_e32 v102, 1.0, v101
	v_fmac_f32_e32 v101, v103, v102
	v_cmp_gt_f32_e32 vcc, s7, v101
	s_nop 1
	v_cndmask_b32_e64 v102, 0, 32, vcc
	v_ldexp_f32 v101, v101, v102
	v_log_f32_e32 v101, v101
	s_nop 0
	v_mul_f32_e32 v102, 0x3f317217, v101
	v_fma_f32 v102, v101, s2, -v102
	v_fmac_f32_e32 v102, 0x3377d1cf, v101
	v_fmac_f32_e32 v102, 0x3f317217, v101
	v_cmp_lt_f32_e64 s[12:13], |v101|, s26
	s_nop 1
	v_cndmask_b32_e64 v101, v101, v102, s[12:13]
	v_cndmask_b32_e32 v102, 0, v226, vcc
	v_sub_f32_e32 v101, v101, v102
	s_mov_b64 s[12:13], 0

.LBB0_1237:
	v_lshl_add_u64 v[96:97], s[24:25], 0, v[200:201]
	v_cvt_pk_bf16_f32 v94, v98, v99
	v_cvt_pk_bf16_f32 v95, v100, v101
	v_lshl_add_u64 v[98:99], v[96:97], 0, v[0:1]
	s_cmp_gt_i32 s40, 1
	s_mov_b64 s[12:13], -1
	v_mov_b32_e32 v140, v94
	v_mov_b32_e32 v141, v95
	s_cbranch_scc0 .LBB0_1239
	global_load_dwordx4 v[94:97], v134, s[22:23] offset:64
	v_mul_f32_e32 v101, 0xbfb8aa3b, v90
	v_exp_f32_e32 v101, v101
	s_mov_b32 s2, 0x3f317217
	s_mov_b32 s26, 0x7f800000
	v_add_f32_e32 v101, 1.0, v101
	v_rcp_f32_e32 v101, v101
	s_waitcnt vmcnt(0)
	v_sub_f32_e32 v100, 1.0, v94
	v_fma_f32 v94, v101, v100, v94
	v_cmp_gt_f32_e32 vcc, s7, v94
	v_mul_f32_e32 v101, 0xbfb8aa3b, v91
	v_exp_f32_e32 v101, v101
	v_cndmask_b32_e64 v100, 0, 32, vcc
	v_ldexp_f32 v94, v94, v100
	v_log_f32_e32 v94, v94
	v_add_f32_e32 v101, 1.0, v101
	v_rcp_f32_e32 v101, v101
	v_mul_f32_e32 v100, 0x3f317217, v94
	v_fma_f32 v100, v94, s2, -v100
	v_fmac_f32_e32 v100, 0x3377d1cf, v94
	v_fmac_f32_e32 v100, 0x3f317217, v94
	v_cmp_lt_f32_e64 s[12:13], |v94|, s26
	s_nop 1
	v_cndmask_b32_e64 v94, v94, v100, s[12:13]
	v_cndmask_b32_e32 v100, 0, v226, vcc
	v_sub_f32_e32 v94, v94, v100
	v_sub_f32_e32 v100, 1.0, v95
	v_fma_f32 v95, v101, v100, v95
	v_cmp_gt_f32_e32 vcc, s7, v95
	v_mul_f32_e32 v101, 0xbfb8aa3b, v92
	v_exp_f32_e32 v101, v101
	v_cndmask_b32_e64 v100, 0, 32, vcc
	v_ldexp_f32 v95, v95, v100
	v_log_f32_e32 v95, v95
	v_add_f32_e32 v101, 1.0, v101
	v_rcp_f32_e32 v101, v101
	v_mul_f32_e32 v100, 0x3f317217, v95
	v_fma_f32 v100, v95, s2, -v100
	v_fmac_f32_e32 v100, 0x3377d1cf, v95
	v_fmac_f32_e32 v100, 0x3f317217, v95
	v_cmp_lt_f32_e64 s[12:13], |v95|, s26
	s_nop 1
	v_cndmask_b32_e64 v95, v95, v100, s[12:13]
	v_cndmask_b32_e32 v100, 0, v226, vcc
	v_sub_f32_e32 v95, v95, v100
	v_sub_f32_e32 v100, 1.0, v96
	v_fma_f32 v96, v101, v100, v96
	v_cmp_gt_f32_e32 vcc, s7, v96
	v_mul_f32_e32 v101, 0xbfb8aa3b, v93
	v_exp_f32_e32 v101, v101
	v_cndmask_b32_e64 v100, 0, 32, vcc
	v_ldexp_f32 v96, v96, v100
	v_log_f32_e32 v96, v96
	v_add_f32_e32 v101, 1.0, v101
	v_rcp_f32_e32 v101, v101
	v_mul_f32_e32 v100, 0x3f317217, v96
	v_fma_f32 v100, v96, s2, -v100
	v_fmac_f32_e32 v100, 0x3377d1cf, v96
	v_fmac_f32_e32 v100, 0x3f317217, v96
	v_cmp_lt_f32_e64 s[12:13], |v96|, s26
	s_nop 1
	v_cndmask_b32_e64 v96, v96, v100, s[12:13]
	v_cndmask_b32_e32 v100, 0, v226, vcc
	v_sub_f32_e32 v96, v96, v100
	v_sub_f32_e32 v100, 1.0, v97
	v_fmac_f32_e32 v97, v101, v100
	v_cmp_gt_f32_e32 vcc, s7, v97
	s_nop 1
	v_cndmask_b32_e64 v100, 0, 32, vcc
	v_ldexp_f32 v97, v97, v100
	v_log_f32_e32 v97, v97
	s_nop 0
	v_mul_f32_e32 v100, 0x3f317217, v97
	v_fma_f32 v100, v97, s2, -v100
	v_fmac_f32_e32 v100, 0x3377d1cf, v97
	v_fmac_f32_e32 v100, 0x3f317217, v97
	v_cmp_lt_f32_e64 s[12:13], |v97|, s26
	s_nop 1
	v_cndmask_b32_e64 v97, v97, v100, s[12:13]
	v_cndmask_b32_e32 v100, 0, v226, vcc
	v_sub_f32_e32 v97, v97, v100
	s_mov_b64 s[12:13], 0

.LBB0_1243:
	v_cvt_pk_bf16_f32 v90, v94, v95
	v_cvt_pk_bf16_f32 v91, v96, v97
	s_cmp_gt_i32 s40, 1
	s_mov_b64 s[12:13], -1
	v_mov_b32_e32 v142, v90
	v_mov_b32_e32 v143, v91
	v_bfe_u32 v144, v182, 4, 1
	v_mul_u32_u24_e32 v144, 24, v144
	v_mov_b32_e32 v145, 0
	v_lshl_add_u64 v[146:147], v[98:99], 0, v[144:145]
	v_permlane16_swap_b32_e32 v140, v142
	v_permlane16_swap_b32_e32 v141, v143
	global_store_dwordx4 v[146:147], v[140:143], off
	s_cbranch_scc0 .LBB0_1245
	global_load_dwordx4 v[90:93], v134, s[22:23] offset:128
	v_mul_f32_e32 v95, 0xbfb8aa3b, v86
	v_exp_f32_e32 v95, v95
	s_mov_b32 s2, 0x3f317217
	s_mov_b32 s26, 0x7f800000
	v_add_f32_e32 v95, 1.0, v95
	v_rcp_f32_e32 v95, v95
	s_waitcnt vmcnt(0)
	v_sub_f32_e32 v94, 1.0, v90
	v_fma_f32 v90, v95, v94, v90
	v_cmp_gt_f32_e32 vcc, s7, v90
	v_mul_f32_e32 v95, 0xbfb8aa3b, v87
	v_exp_f32_e32 v95, v95
	v_cndmask_b32_e64 v94, 0, 32, vcc
	v_ldexp_f32 v90, v90, v94
	v_log_f32_e32 v90, v90
	v_add_f32_e32 v95, 1.0, v95
	v_rcp_f32_e32 v95, v95
	v_mul_f32_e32 v94, 0x3f317217, v90
	v_fma_f32 v94, v90, s2, -v94
	v_fmac_f32_e32 v94, 0x3377d1cf, v90
	v_fmac_f32_e32 v94, 0x3f317217, v90
	v_cmp_lt_f32_e64 s[12:13], |v90|, s26
	s_nop 1
	v_cndmask_b32_e64 v90, v90, v94, s[12:13]
	v_cndmask_b32_e32 v94, 0, v226, vcc
	v_sub_f32_e32 v90, v90, v94
	v_sub_f32_e32 v94, 1.0, v91
	v_fma_f32 v91, v95, v94, v91
	v_cmp_gt_f32_e32 vcc, s7, v91
	v_mul_f32_e32 v95, 0xbfb8aa3b, v88
	v_exp_f32_e32 v95, v95
	v_cndmask_b32_e64 v94, 0, 32, vcc
	v_ldexp_f32 v91, v91, v94
	v_log_f32_e32 v91, v91
	v_add_f32_e32 v95, 1.0, v95
	v_rcp_f32_e32 v95, v95
	v_mul_f32_e32 v94, 0x3f317217, v91
	v_fma_f32 v94, v91, s2, -v94
	v_fmac_f32_e32 v94, 0x3377d1cf, v91
	v_fmac_f32_e32 v94, 0x3f317217, v91
	v_cmp_lt_f32_e64 s[12:13], |v91|, s26
	s_nop 1
	v_cndmask_b32_e64 v91, v91, v94, s[12:13]
	v_cndmask_b32_e32 v94, 0, v226, vcc
	v_sub_f32_e32 v91, v91, v94
	v_sub_f32_e32 v94, 1.0, v92
	v_fma_f32 v92, v95, v94, v92
	v_cmp_gt_f32_e32 vcc, s7, v92
	v_mul_f32_e32 v95, 0xbfb8aa3b, v89
	v_exp_f32_e32 v95, v95
	v_cndmask_b32_e64 v94, 0, 32, vcc
	v_ldexp_f32 v92, v92, v94
	v_log_f32_e32 v92, v92
	v_add_f32_e32 v95, 1.0, v95
	v_rcp_f32_e32 v95, v95
	v_mul_f32_e32 v94, 0x3f317217, v92
	v_fma_f32 v94, v92, s2, -v94
	v_fmac_f32_e32 v94, 0x3377d1cf, v92
	v_fmac_f32_e32 v94, 0x3f317217, v92
	v_cmp_lt_f32_e64 s[12:13], |v92|, s26
	s_nop 1
	v_cndmask_b32_e64 v92, v92, v94, s[12:13]
	v_cndmask_b32_e32 v94, 0, v226, vcc
	v_sub_f32_e32 v92, v92, v94
	v_sub_f32_e32 v94, 1.0, v93
	v_fmac_f32_e32 v93, v95, v94
	v_cmp_gt_f32_e32 vcc, s7, v93
	s_nop 1
	v_cndmask_b32_e64 v94, 0, 32, vcc
	v_ldexp_f32 v93, v93, v94
	v_log_f32_e32 v93, v93
	s_nop 0
	v_mul_f32_e32 v94, 0x3f317217, v93
	v_fma_f32 v94, v93, s2, -v94
	v_fmac_f32_e32 v94, 0x3377d1cf, v93
	v_fmac_f32_e32 v94, 0x3f317217, v93
	v_cmp_lt_f32_e64 s[12:13], |v93|, s26
	s_nop 1
	v_cndmask_b32_e64 v93, v93, v94, s[12:13]
	v_cndmask_b32_e32 v94, 0, v226, vcc
	v_sub_f32_e32 v93, v93, v94
	s_mov_b64 s[12:13], 0

.LBB0_1249:
	v_cvt_pk_bf16_f32 v86, v90, v91
	v_cvt_pk_bf16_f32 v87, v92, v93
	s_cmp_gt_i32 s40, 1
	s_mov_b64 s[12:13], -1
	v_mov_b32_e32 v140, v86
	v_mov_b32_e32 v141, v87
	s_cbranch_scc0 .LBB0_1251
	global_load_dwordx4 v[86:89], v134, s[22:23] offset:192
	v_mul_f32_e32 v91, 0xbfb8aa3b, v82
	v_exp_f32_e32 v91, v91
	s_mov_b32 s2, 0x3f317217
	s_mov_b32 s26, 0x7f800000
	v_add_f32_e32 v91, 1.0, v91
	v_rcp_f32_e32 v91, v91
	s_waitcnt vmcnt(0)
	v_sub_f32_e32 v90, 1.0, v86
	v_fma_f32 v86, v91, v90, v86
	v_cmp_gt_f32_e32 vcc, s7, v86
	v_mul_f32_e32 v91, 0xbfb8aa3b, v83
	v_exp_f32_e32 v91, v91
	v_cndmask_b32_e64 v90, 0, 32, vcc
	v_ldexp_f32 v86, v86, v90
	v_log_f32_e32 v86, v86
	v_add_f32_e32 v91, 1.0, v91
	v_rcp_f32_e32 v91, v91
	v_mul_f32_e32 v90, 0x3f317217, v86
	v_fma_f32 v90, v86, s2, -v90
	v_fmac_f32_e32 v90, 0x3377d1cf, v86
	v_fmac_f32_e32 v90, 0x3f317217, v86
	v_cmp_lt_f32_e64 s[12:13], |v86|, s26
	s_nop 1
	v_cndmask_b32_e64 v86, v86, v90, s[12:13]
	v_cndmask_b32_e32 v90, 0, v226, vcc
	v_sub_f32_e32 v86, v86, v90
	v_sub_f32_e32 v90, 1.0, v87
	v_fma_f32 v87, v91, v90, v87
	v_cmp_gt_f32_e32 vcc, s7, v87
	v_mul_f32_e32 v91, 0xbfb8aa3b, v84
	v_exp_f32_e32 v91, v91
	v_cndmask_b32_e64 v90, 0, 32, vcc
	v_ldexp_f32 v87, v87, v90
	v_log_f32_e32 v87, v87
	v_add_f32_e32 v91, 1.0, v91
	v_rcp_f32_e32 v91, v91
	v_mul_f32_e32 v90, 0x3f317217, v87
	v_fma_f32 v90, v87, s2, -v90
	v_fmac_f32_e32 v90, 0x3377d1cf, v87
	v_fmac_f32_e32 v90, 0x3f317217, v87
	v_cmp_lt_f32_e64 s[12:13], |v87|, s26
	s_nop 1
	v_cndmask_b32_e64 v87, v87, v90, s[12:13]
	v_cndmask_b32_e32 v90, 0, v226, vcc
	v_sub_f32_e32 v87, v87, v90
	v_sub_f32_e32 v90, 1.0, v88
	v_fma_f32 v88, v91, v90, v88
	v_cmp_gt_f32_e32 vcc, s7, v88
	v_mul_f32_e32 v91, 0xbfb8aa3b, v85
	v_exp_f32_e32 v91, v91
	v_cndmask_b32_e64 v90, 0, 32, vcc
	v_ldexp_f32 v88, v88, v90
	v_log_f32_e32 v88, v88
	v_add_f32_e32 v91, 1.0, v91
	v_rcp_f32_e32 v91, v91
	v_mul_f32_e32 v90, 0x3f317217, v88
	v_fma_f32 v90, v88, s2, -v90
	v_fmac_f32_e32 v90, 0x3377d1cf, v88
	v_fmac_f32_e32 v90, 0x3f317217, v88
	v_cmp_lt_f32_e64 s[12:13], |v88|, s26
	s_nop 1
	v_cndmask_b32_e64 v88, v88, v90, s[12:13]
	v_cndmask_b32_e32 v90, 0, v226, vcc
	v_sub_f32_e32 v88, v88, v90
	v_sub_f32_e32 v90, 1.0, v89
	v_fmac_f32_e32 v89, v91, v90
	v_cmp_gt_f32_e32 vcc, s7, v89
	s_nop 1
	v_cndmask_b32_e64 v90, 0, 32, vcc
	v_ldexp_f32 v89, v89, v90
	v_log_f32_e32 v89, v89
	s_nop 0
	v_mul_f32_e32 v90, 0x3f317217, v89
	v_fma_f32 v90, v89, s2, -v90
	v_fmac_f32_e32 v90, 0x3377d1cf, v89
	v_fmac_f32_e32 v90, 0x3f317217, v89
	v_cmp_lt_f32_e64 s[12:13], |v89|, s26
	s_nop 1
	v_cndmask_b32_e64 v89, v89, v90, s[12:13]
	v_cndmask_b32_e32 v90, 0, v226, vcc
	v_sub_f32_e32 v89, v89, v90
	s_mov_b64 s[12:13], 0

.LBB0_1255:
	v_cvt_pk_bf16_f32 v82, v86, v87
	v_cvt_pk_bf16_f32 v83, v88, v89
	v_mov_b32_e32 v142, v82
	v_mov_b32_e32 v143, v83
	v_bfe_u32 v144, v182, 4, 1
	v_mul_u32_u24_e32 v144, 24, v144
	v_mov_b32_e32 v145, 0
	v_lshl_add_u64 v[146:147], v[98:99], 0, v[144:145]
	v_permlane16_swap_b32_e32 v140, v142
	v_permlane16_swap_b32_e32 v141, v143
	global_store_dwordx4 v[146:147], v[140:143], off offset:64
	s_cmp_gt_i32 s40, 1
	s_mov_b64 s[12:13], -1
	s_cbranch_scc0 .LBB0_1257
	global_load_dwordx4 v[82:85], v134, s[22:23]
	v_mul_f32_e32 v87, 0xbfb8aa3b, v78
	v_exp_f32_e32 v87, v87
	s_mov_b32 s2, 0x3f317217
	s_mov_b32 s26, 0x7f800000
	v_add_f32_e32 v87, 1.0, v87
	v_rcp_f32_e32 v87, v87
	s_waitcnt vmcnt(0)
	v_sub_f32_e32 v86, 1.0, v82
	v_fma_f32 v82, v87, v86, v82
	v_cmp_gt_f32_e32 vcc, s7, v82
	v_mul_f32_e32 v87, 0xbfb8aa3b, v79
	v_exp_f32_e32 v87, v87
	v_cndmask_b32_e64 v86, 0, 32, vcc
	v_ldexp_f32 v82, v82, v86
	v_log_f32_e32 v82, v82
	v_add_f32_e32 v87, 1.0, v87
	v_rcp_f32_e32 v87, v87
	v_mul_f32_e32 v86, 0x3f317217, v82
	v_fma_f32 v86, v82, s2, -v86
	v_fmac_f32_e32 v86, 0x3377d1cf, v82
	v_fmac_f32_e32 v86, 0x3f317217, v82
	v_cmp_lt_f32_e64 s[12:13], |v82|, s26
	s_nop 1
	v_cndmask_b32_e64 v82, v82, v86, s[12:13]
	v_cndmask_b32_e32 v86, 0, v226, vcc
	v_sub_f32_e32 v82, v82, v86
	v_sub_f32_e32 v86, 1.0, v83
	v_fma_f32 v83, v87, v86, v83
	v_cmp_gt_f32_e32 vcc, s7, v83
	v_mul_f32_e32 v87, 0xbfb8aa3b, v80
	v_exp_f32_e32 v87, v87
	v_cndmask_b32_e64 v86, 0, 32, vcc
	v_ldexp_f32 v83, v83, v86
	v_log_f32_e32 v83, v83
	v_add_f32_e32 v87, 1.0, v87
	v_rcp_f32_e32 v87, v87
	v_mul_f32_e32 v86, 0x3f317217, v83
	v_fma_f32 v86, v83, s2, -v86
	v_fmac_f32_e32 v86, 0x3377d1cf, v83
	v_fmac_f32_e32 v86, 0x3f317217, v83
	v_cmp_lt_f32_e64 s[12:13], |v83|, s26
	s_nop 1
	v_cndmask_b32_e64 v83, v83, v86, s[12:13]
	v_cndmask_b32_e32 v86, 0, v226, vcc
	v_sub_f32_e32 v83, v83, v86
	v_sub_f32_e32 v86, 1.0, v84
	v_fma_f32 v84, v87, v86, v84
	v_cmp_gt_f32_e32 vcc, s7, v84
	v_mul_f32_e32 v87, 0xbfb8aa3b, v81
	v_exp_f32_e32 v87, v87
	v_cndmask_b32_e64 v86, 0, 32, vcc
	v_ldexp_f32 v84, v84, v86
	v_log_f32_e32 v84, v84
	v_add_f32_e32 v87, 1.0, v87
	v_rcp_f32_e32 v87, v87
	v_mul_f32_e32 v86, 0x3f317217, v84
	v_fma_f32 v86, v84, s2, -v86
	v_fmac_f32_e32 v86, 0x3377d1cf, v84
	v_fmac_f32_e32 v86, 0x3f317217, v84
	v_cmp_lt_f32_e64 s[12:13], |v84|, s26
	s_nop 1
	v_cndmask_b32_e64 v84, v84, v86, s[12:13]
	v_cndmask_b32_e32 v86, 0, v226, vcc
	v_sub_f32_e32 v84, v84, v86
	v_sub_f32_e32 v86, 1.0, v85
	v_fmac_f32_e32 v85, v87, v86
	v_cmp_gt_f32_e32 vcc, s7, v85
	s_nop 1
	v_cndmask_b32_e64 v86, 0, 32, vcc
	v_ldexp_f32 v85, v85, v86
	v_log_f32_e32 v85, v85
	s_nop 0
	v_mul_f32_e32 v86, 0x3f317217, v85
	v_fma_f32 v86, v85, s2, -v86
	v_fmac_f32_e32 v86, 0x3377d1cf, v85
	v_fmac_f32_e32 v86, 0x3f317217, v85
	v_cmp_lt_f32_e64 s[12:13], |v85|, s26
	s_nop 1
	v_cndmask_b32_e64 v85, v85, v86, s[12:13]
	v_cndmask_b32_e32 v86, 0, v226, vcc
	v_sub_f32_e32 v85, v85, v86
	s_mov_b64 s[12:13], 0

.LBB0_1261:
	v_lshl_add_u64 v[80:81], s[24:25], 0, v[202:203]
	v_cvt_pk_bf16_f32 v78, v82, v83
	v_cvt_pk_bf16_f32 v79, v84, v85
	v_lshl_add_u64 v[82:83], v[80:81], 0, v[0:1]
	s_cmp_gt_i32 s40, 1
	s_mov_b64 s[12:13], -1
	v_mov_b32_e32 v140, v78
	v_mov_b32_e32 v141, v79
	s_cbranch_scc0 .LBB0_1263
	global_load_dwordx4 v[78:81], v134, s[22:23] offset:64
	v_mul_f32_e32 v85, 0xbfb8aa3b, v74
	v_exp_f32_e32 v85, v85
	s_mov_b32 s2, 0x3f317217
	s_mov_b32 s26, 0x7f800000
	v_add_f32_e32 v85, 1.0, v85
	v_rcp_f32_e32 v85, v85
	s_waitcnt vmcnt(0)
	v_sub_f32_e32 v84, 1.0, v78
	v_fma_f32 v78, v85, v84, v78
	v_cmp_gt_f32_e32 vcc, s7, v78
	v_mul_f32_e32 v85, 0xbfb8aa3b, v75
	v_exp_f32_e32 v85, v85
	v_cndmask_b32_e64 v84, 0, 32, vcc
	v_ldexp_f32 v78, v78, v84
	v_log_f32_e32 v78, v78
	v_add_f32_e32 v85, 1.0, v85
	v_rcp_f32_e32 v85, v85
	v_mul_f32_e32 v84, 0x3f317217, v78
	v_fma_f32 v84, v78, s2, -v84
	v_fmac_f32_e32 v84, 0x3377d1cf, v78
	v_fmac_f32_e32 v84, 0x3f317217, v78
	v_cmp_lt_f32_e64 s[12:13], |v78|, s26
	s_nop 1
	v_cndmask_b32_e64 v78, v78, v84, s[12:13]
	v_cndmask_b32_e32 v84, 0, v226, vcc
	v_sub_f32_e32 v78, v78, v84
	v_sub_f32_e32 v84, 1.0, v79
	v_fma_f32 v79, v85, v84, v79
	v_cmp_gt_f32_e32 vcc, s7, v79
	v_mul_f32_e32 v85, 0xbfb8aa3b, v76
	v_exp_f32_e32 v85, v85
	v_cndmask_b32_e64 v84, 0, 32, vcc
	v_ldexp_f32 v79, v79, v84
	v_log_f32_e32 v79, v79
	v_add_f32_e32 v85, 1.0, v85
	v_rcp_f32_e32 v85, v85
	v_mul_f32_e32 v84, 0x3f317217, v79
	v_fma_f32 v84, v79, s2, -v84
	v_fmac_f32_e32 v84, 0x3377d1cf, v79
	v_fmac_f32_e32 v84, 0x3f317217, v79
	v_cmp_lt_f32_e64 s[12:13], |v79|, s26
	s_nop 1
	v_cndmask_b32_e64 v79, v79, v84, s[12:13]
	v_cndmask_b32_e32 v84, 0, v226, vcc
	v_sub_f32_e32 v79, v79, v84
	v_sub_f32_e32 v84, 1.0, v80
	v_fma_f32 v80, v85, v84, v80
	v_cmp_gt_f32_e32 vcc, s7, v80
	v_mul_f32_e32 v85, 0xbfb8aa3b, v77
	v_exp_f32_e32 v85, v85
	v_cndmask_b32_e64 v84, 0, 32, vcc
	v_ldexp_f32 v80, v80, v84
	v_log_f32_e32 v80, v80
	v_add_f32_e32 v85, 1.0, v85
	v_rcp_f32_e32 v85, v85
	v_mul_f32_e32 v84, 0x3f317217, v80
	v_fma_f32 v84, v80, s2, -v84
	v_fmac_f32_e32 v84, 0x3377d1cf, v80
	v_fmac_f32_e32 v84, 0x3f317217, v80
	v_cmp_lt_f32_e64 s[12:13], |v80|, s26
	s_nop 1
	v_cndmask_b32_e64 v80, v80, v84, s[12:13]
	v_cndmask_b32_e32 v84, 0, v226, vcc
	v_sub_f32_e32 v80, v80, v84
	v_sub_f32_e32 v84, 1.0, v81
	v_fmac_f32_e32 v81, v85, v84
	v_cmp_gt_f32_e32 vcc, s7, v81
	s_nop 1
	v_cndmask_b32_e64 v84, 0, 32, vcc
	v_ldexp_f32 v81, v81, v84
	v_log_f32_e32 v81, v81
	s_nop 0
	v_mul_f32_e32 v84, 0x3f317217, v81
	v_fma_f32 v84, v81, s2, -v84
	v_fmac_f32_e32 v84, 0x3377d1cf, v81
	v_fmac_f32_e32 v84, 0x3f317217, v81
	v_cmp_lt_f32_e64 s[12:13], |v81|, s26
	s_nop 1
	v_cndmask_b32_e64 v81, v81, v84, s[12:13]
	v_cndmask_b32_e32 v84, 0, v226, vcc
	v_sub_f32_e32 v81, v81, v84
	s_mov_b64 s[12:13], 0

.LBB0_1267:
	v_cvt_pk_bf16_f32 v74, v78, v79
	v_cvt_pk_bf16_f32 v75, v80, v81
	s_cmp_gt_i32 s40, 1
	s_mov_b64 s[12:13], -1
	v_mov_b32_e32 v142, v74
	v_mov_b32_e32 v143, v75
	v_bfe_u32 v144, v182, 4, 1
	v_mul_u32_u24_e32 v144, 24, v144
	v_mov_b32_e32 v145, 0
	v_lshl_add_u64 v[146:147], v[82:83], 0, v[144:145]
	v_permlane16_swap_b32_e32 v140, v142
	v_permlane16_swap_b32_e32 v141, v143
	global_store_dwordx4 v[146:147], v[140:143], off
	s_cbranch_scc0 .LBB0_1269
	global_load_dwordx4 v[74:77], v134, s[22:23] offset:128
	v_mul_f32_e32 v79, 0xbfb8aa3b, v70
	v_exp_f32_e32 v79, v79
	s_mov_b32 s2, 0x3f317217
	s_mov_b32 s26, 0x7f800000
	v_add_f32_e32 v79, 1.0, v79
	v_rcp_f32_e32 v79, v79
	s_waitcnt vmcnt(0)
	v_sub_f32_e32 v78, 1.0, v74
	v_fma_f32 v74, v79, v78, v74
	v_cmp_gt_f32_e32 vcc, s7, v74
	v_mul_f32_e32 v79, 0xbfb8aa3b, v71
	v_exp_f32_e32 v79, v79
	v_cndmask_b32_e64 v78, 0, 32, vcc
	v_ldexp_f32 v74, v74, v78
	v_log_f32_e32 v74, v74
	v_add_f32_e32 v79, 1.0, v79
	v_rcp_f32_e32 v79, v79
	v_mul_f32_e32 v78, 0x3f317217, v74
	v_fma_f32 v78, v74, s2, -v78
	v_fmac_f32_e32 v78, 0x3377d1cf, v74
	v_fmac_f32_e32 v78, 0x3f317217, v74
	v_cmp_lt_f32_e64 s[12:13], |v74|, s26
	s_nop 1
	v_cndmask_b32_e64 v74, v74, v78, s[12:13]
	v_cndmask_b32_e32 v78, 0, v226, vcc
	v_sub_f32_e32 v74, v74, v78
	v_sub_f32_e32 v78, 1.0, v75
	v_fma_f32 v75, v79, v78, v75
	v_cmp_gt_f32_e32 vcc, s7, v75
	v_mul_f32_e32 v79, 0xbfb8aa3b, v72
	v_exp_f32_e32 v79, v79
	v_cndmask_b32_e64 v78, 0, 32, vcc
	v_ldexp_f32 v75, v75, v78
	v_log_f32_e32 v75, v75
	v_add_f32_e32 v79, 1.0, v79
	v_rcp_f32_e32 v79, v79
	v_mul_f32_e32 v78, 0x3f317217, v75
	v_fma_f32 v78, v75, s2, -v78
	v_fmac_f32_e32 v78, 0x3377d1cf, v75
	v_fmac_f32_e32 v78, 0x3f317217, v75
	v_cmp_lt_f32_e64 s[12:13], |v75|, s26
	s_nop 1
	v_cndmask_b32_e64 v75, v75, v78, s[12:13]
	v_cndmask_b32_e32 v78, 0, v226, vcc
	v_sub_f32_e32 v75, v75, v78
	v_sub_f32_e32 v78, 1.0, v76
	v_fma_f32 v76, v79, v78, v76
	v_cmp_gt_f32_e32 vcc, s7, v76
	v_mul_f32_e32 v79, 0xbfb8aa3b, v73
	v_exp_f32_e32 v79, v79
	v_cndmask_b32_e64 v78, 0, 32, vcc
	v_ldexp_f32 v76, v76, v78
	v_log_f32_e32 v76, v76
	v_add_f32_e32 v79, 1.0, v79
	v_rcp_f32_e32 v79, v79
	v_mul_f32_e32 v78, 0x3f317217, v76
	v_fma_f32 v78, v76, s2, -v78
	v_fmac_f32_e32 v78, 0x3377d1cf, v76
	v_fmac_f32_e32 v78, 0x3f317217, v76
	v_cmp_lt_f32_e64 s[12:13], |v76|, s26
	s_nop 1
	v_cndmask_b32_e64 v76, v76, v78, s[12:13]
	v_cndmask_b32_e32 v78, 0, v226, vcc
	v_sub_f32_e32 v76, v76, v78
	v_sub_f32_e32 v78, 1.0, v77
	v_fmac_f32_e32 v77, v79, v78
	v_cmp_gt_f32_e32 vcc, s7, v77
	s_nop 1
	v_cndmask_b32_e64 v78, 0, 32, vcc
	v_ldexp_f32 v77, v77, v78
	v_log_f32_e32 v77, v77
	s_nop 0
	v_mul_f32_e32 v78, 0x3f317217, v77
	v_fma_f32 v78, v77, s2, -v78
	v_fmac_f32_e32 v78, 0x3377d1cf, v77
	v_fmac_f32_e32 v78, 0x3f317217, v77
	v_cmp_lt_f32_e64 s[12:13], |v77|, s26
	s_nop 1
	v_cndmask_b32_e64 v77, v77, v78, s[12:13]
	v_cndmask_b32_e32 v78, 0, v226, vcc
	v_sub_f32_e32 v77, v77, v78
	s_mov_b64 s[12:13], 0

.LBB0_1273:
	v_cvt_pk_bf16_f32 v70, v74, v75
	v_cvt_pk_bf16_f32 v71, v76, v77
	s_cmp_gt_i32 s40, 1
	s_mov_b64 s[12:13], -1
	v_mov_b32_e32 v140, v70
	v_mov_b32_e32 v141, v71
	s_cbranch_scc0 .LBB0_1275
	global_load_dwordx4 v[70:73], v134, s[22:23] offset:192
	v_mul_f32_e32 v75, 0xbfb8aa3b, v66
	v_exp_f32_e32 v75, v75
	s_mov_b32 s2, 0x3f317217
	s_mov_b32 s26, 0x7f800000
	v_add_f32_e32 v75, 1.0, v75
	v_rcp_f32_e32 v75, v75
	s_waitcnt vmcnt(0)
	v_sub_f32_e32 v74, 1.0, v70
	v_fma_f32 v70, v75, v74, v70
	v_cmp_gt_f32_e32 vcc, s7, v70
	v_mul_f32_e32 v75, 0xbfb8aa3b, v67
	v_exp_f32_e32 v75, v75
	v_cndmask_b32_e64 v74, 0, 32, vcc
	v_ldexp_f32 v70, v70, v74
	v_log_f32_e32 v70, v70
	v_add_f32_e32 v75, 1.0, v75
	v_rcp_f32_e32 v75, v75
	v_mul_f32_e32 v74, 0x3f317217, v70
	v_fma_f32 v74, v70, s2, -v74
	v_fmac_f32_e32 v74, 0x3377d1cf, v70
	v_fmac_f32_e32 v74, 0x3f317217, v70
	v_cmp_lt_f32_e64 s[12:13], |v70|, s26
	s_nop 1
	v_cndmask_b32_e64 v70, v70, v74, s[12:13]
	v_cndmask_b32_e32 v74, 0, v226, vcc
	v_sub_f32_e32 v70, v70, v74
	v_sub_f32_e32 v74, 1.0, v71
	v_fma_f32 v71, v75, v74, v71
	v_cmp_gt_f32_e32 vcc, s7, v71
	v_mul_f32_e32 v75, 0xbfb8aa3b, v68
	v_exp_f32_e32 v75, v75
	v_cndmask_b32_e64 v74, 0, 32, vcc
	v_ldexp_f32 v71, v71, v74
	v_log_f32_e32 v71, v71
	v_add_f32_e32 v75, 1.0, v75
	v_rcp_f32_e32 v75, v75
	v_mul_f32_e32 v74, 0x3f317217, v71
	v_fma_f32 v74, v71, s2, -v74
	v_fmac_f32_e32 v74, 0x3377d1cf, v71
	v_fmac_f32_e32 v74, 0x3f317217, v71
	v_cmp_lt_f32_e64 s[12:13], |v71|, s26
	s_nop 1
	v_cndmask_b32_e64 v71, v71, v74, s[12:13]
	v_cndmask_b32_e32 v74, 0, v226, vcc
	v_sub_f32_e32 v71, v71, v74
	v_sub_f32_e32 v74, 1.0, v72
	v_fma_f32 v72, v75, v74, v72
	v_cmp_gt_f32_e32 vcc, s7, v72
	v_mul_f32_e32 v75, 0xbfb8aa3b, v69
	v_exp_f32_e32 v75, v75
	v_cndmask_b32_e64 v74, 0, 32, vcc
	v_ldexp_f32 v72, v72, v74
	v_log_f32_e32 v72, v72
	v_add_f32_e32 v75, 1.0, v75
	v_rcp_f32_e32 v75, v75
	v_mul_f32_e32 v74, 0x3f317217, v72
	v_fma_f32 v74, v72, s2, -v74
	v_fmac_f32_e32 v74, 0x3377d1cf, v72
	v_fmac_f32_e32 v74, 0x3f317217, v72
	v_cmp_lt_f32_e64 s[12:13], |v72|, s26
	s_nop 1
	v_cndmask_b32_e64 v72, v72, v74, s[12:13]
	v_cndmask_b32_e32 v74, 0, v226, vcc
	v_sub_f32_e32 v72, v72, v74
	v_sub_f32_e32 v74, 1.0, v73
	v_fmac_f32_e32 v73, v75, v74
	v_cmp_gt_f32_e32 vcc, s7, v73
	s_nop 1
	v_cndmask_b32_e64 v74, 0, 32, vcc
	v_ldexp_f32 v73, v73, v74
	v_log_f32_e32 v73, v73
	s_nop 0
	v_mul_f32_e32 v74, 0x3f317217, v73
	v_fma_f32 v74, v73, s2, -v74
	v_fmac_f32_e32 v74, 0x3377d1cf, v73
	v_fmac_f32_e32 v74, 0x3f317217, v73
	v_cmp_lt_f32_e64 s[12:13], |v73|, s26
	s_nop 1
	v_cndmask_b32_e64 v73, v73, v74, s[12:13]
	v_cndmask_b32_e32 v74, 0, v226, vcc
	v_sub_f32_e32 v73, v73, v74
	s_mov_b64 s[12:13], 0

.LBB0_1279:
	v_cvt_pk_bf16_f32 v66, v70, v71
	v_cvt_pk_bf16_f32 v67, v72, v73
	v_mov_b32_e32 v142, v66
	v_mov_b32_e32 v143, v67
	v_bfe_u32 v144, v182, 4, 1
	v_mul_u32_u24_e32 v144, 24, v144
	v_mov_b32_e32 v145, 0
	v_lshl_add_u64 v[146:147], v[82:83], 0, v[144:145]
	v_permlane16_swap_b32_e32 v140, v142
	v_permlane16_swap_b32_e32 v141, v143
	global_store_dwordx4 v[146:147], v[140:143], off offset:64
	s_cmp_gt_i32 s40, 1
	s_mov_b64 s[12:13], -1
	s_cbranch_scc0 .LBB0_1281
	global_load_dwordx4 v[66:69], v134, s[22:23]
	v_mul_f32_e32 v71, 0xbfb8aa3b, v62
	v_exp_f32_e32 v71, v71
	s_mov_b32 s2, 0x3f317217
	s_mov_b32 s26, 0x7f800000
	v_add_f32_e32 v71, 1.0, v71
	v_rcp_f32_e32 v71, v71
	s_waitcnt vmcnt(0)
	v_sub_f32_e32 v70, 1.0, v66
	v_fma_f32 v66, v71, v70, v66
	v_cmp_gt_f32_e32 vcc, s7, v66
	v_mul_f32_e32 v71, 0xbfb8aa3b, v63
	v_exp_f32_e32 v71, v71
	v_cndmask_b32_e64 v70, 0, 32, vcc
	v_ldexp_f32 v66, v66, v70
	v_log_f32_e32 v66, v66
	v_add_f32_e32 v71, 1.0, v71
	v_rcp_f32_e32 v71, v71
	v_mul_f32_e32 v70, 0x3f317217, v66
	v_fma_f32 v70, v66, s2, -v70
	v_fmac_f32_e32 v70, 0x3377d1cf, v66
	v_fmac_f32_e32 v70, 0x3f317217, v66
	v_cmp_lt_f32_e64 s[12:13], |v66|, s26
	s_nop 1
	v_cndmask_b32_e64 v66, v66, v70, s[12:13]
	v_cndmask_b32_e32 v70, 0, v226, vcc
	v_sub_f32_e32 v66, v66, v70
	v_sub_f32_e32 v70, 1.0, v67
	v_fma_f32 v67, v71, v70, v67
	v_cmp_gt_f32_e32 vcc, s7, v67
	v_mul_f32_e32 v71, 0xbfb8aa3b, v64
	v_exp_f32_e32 v71, v71
	v_cndmask_b32_e64 v70, 0, 32, vcc
	v_ldexp_f32 v67, v67, v70
	v_log_f32_e32 v67, v67
	v_add_f32_e32 v71, 1.0, v71
	v_rcp_f32_e32 v71, v71
	v_mul_f32_e32 v70, 0x3f317217, v67
	v_fma_f32 v70, v67, s2, -v70
	v_fmac_f32_e32 v70, 0x3377d1cf, v67
	v_fmac_f32_e32 v70, 0x3f317217, v67
	v_cmp_lt_f32_e64 s[12:13], |v67|, s26
	s_nop 1
	v_cndmask_b32_e64 v67, v67, v70, s[12:13]
	v_cndmask_b32_e32 v70, 0, v226, vcc
	v_sub_f32_e32 v67, v67, v70
	v_sub_f32_e32 v70, 1.0, v68
	v_fma_f32 v68, v71, v70, v68
	v_cmp_gt_f32_e32 vcc, s7, v68
	v_mul_f32_e32 v71, 0xbfb8aa3b, v65
	v_exp_f32_e32 v71, v71
	v_cndmask_b32_e64 v70, 0, 32, vcc
	v_ldexp_f32 v68, v68, v70
	v_log_f32_e32 v68, v68
	v_add_f32_e32 v71, 1.0, v71
	v_rcp_f32_e32 v71, v71
	v_mul_f32_e32 v70, 0x3f317217, v68
	v_fma_f32 v70, v68, s2, -v70
	v_fmac_f32_e32 v70, 0x3377d1cf, v68
	v_fmac_f32_e32 v70, 0x3f317217, v68
	v_cmp_lt_f32_e64 s[12:13], |v68|, s26
	s_nop 1
	v_cndmask_b32_e64 v68, v68, v70, s[12:13]
	v_cndmask_b32_e32 v70, 0, v226, vcc
	v_sub_f32_e32 v68, v68, v70
	v_sub_f32_e32 v70, 1.0, v69
	v_fmac_f32_e32 v69, v71, v70
	v_cmp_gt_f32_e32 vcc, s7, v69
	s_nop 1
	v_cndmask_b32_e64 v70, 0, 32, vcc
	v_ldexp_f32 v69, v69, v70
	v_log_f32_e32 v69, v69
	s_nop 0
	v_mul_f32_e32 v70, 0x3f317217, v69
	v_fma_f32 v70, v69, s2, -v70
	v_fmac_f32_e32 v70, 0x3377d1cf, v69
	v_fmac_f32_e32 v70, 0x3f317217, v69
	v_cmp_lt_f32_e64 s[12:13], |v69|, s26
	s_nop 1
	v_cndmask_b32_e64 v69, v69, v70, s[12:13]
	v_cndmask_b32_e32 v70, 0, v226, vcc
	v_sub_f32_e32 v69, v69, v70
	s_mov_b64 s[12:13], 0

.LBB0_1285:
	v_lshl_add_u64 v[64:65], s[24:25], 0, v[204:205]
	v_cvt_pk_bf16_f32 v62, v66, v67
	v_cvt_pk_bf16_f32 v63, v68, v69
	v_lshl_add_u64 v[66:67], v[64:65], 0, v[0:1]
	s_cmp_gt_i32 s40, 1
	s_mov_b64 s[12:13], -1
	v_mov_b32_e32 v140, v62
	v_mov_b32_e32 v141, v63
	s_cbranch_scc0 .LBB0_1287
	global_load_dwordx4 v[62:65], v134, s[22:23] offset:64
	v_mul_f32_e32 v69, 0xbfb8aa3b, v58
	v_exp_f32_e32 v69, v69
	s_mov_b32 s2, 0x3f317217
	s_mov_b32 s26, 0x7f800000
	v_add_f32_e32 v69, 1.0, v69
	v_rcp_f32_e32 v69, v69
	s_waitcnt vmcnt(0)
	v_sub_f32_e32 v68, 1.0, v62
	v_fma_f32 v62, v69, v68, v62
	v_cmp_gt_f32_e32 vcc, s7, v62
	v_mul_f32_e32 v69, 0xbfb8aa3b, v59
	v_exp_f32_e32 v69, v69
	v_cndmask_b32_e64 v68, 0, 32, vcc
	v_ldexp_f32 v62, v62, v68
	v_log_f32_e32 v62, v62
	v_add_f32_e32 v69, 1.0, v69
	v_rcp_f32_e32 v69, v69
	v_mul_f32_e32 v68, 0x3f317217, v62
	v_fma_f32 v68, v62, s2, -v68
	v_fmac_f32_e32 v68, 0x3377d1cf, v62
	v_fmac_f32_e32 v68, 0x3f317217, v62
	v_cmp_lt_f32_e64 s[12:13], |v62|, s26
	s_nop 1
	v_cndmask_b32_e64 v62, v62, v68, s[12:13]
	v_cndmask_b32_e32 v68, 0, v226, vcc
	v_sub_f32_e32 v62, v62, v68
	v_sub_f32_e32 v68, 1.0, v63
	v_fma_f32 v63, v69, v68, v63
	v_cmp_gt_f32_e32 vcc, s7, v63
	v_mul_f32_e32 v69, 0xbfb8aa3b, v60
	v_exp_f32_e32 v69, v69
	v_cndmask_b32_e64 v68, 0, 32, vcc
	v_ldexp_f32 v63, v63, v68
	v_log_f32_e32 v63, v63
	v_add_f32_e32 v69, 1.0, v69
	v_rcp_f32_e32 v69, v69
	v_mul_f32_e32 v68, 0x3f317217, v63
	v_fma_f32 v68, v63, s2, -v68
	v_fmac_f32_e32 v68, 0x3377d1cf, v63
	v_fmac_f32_e32 v68, 0x3f317217, v63
	v_cmp_lt_f32_e64 s[12:13], |v63|, s26
	s_nop 1
	v_cndmask_b32_e64 v63, v63, v68, s[12:13]
	v_cndmask_b32_e32 v68, 0, v226, vcc
	v_sub_f32_e32 v63, v63, v68
	v_sub_f32_e32 v68, 1.0, v64
	v_fma_f32 v64, v69, v68, v64
	v_cmp_gt_f32_e32 vcc, s7, v64
	v_mul_f32_e32 v69, 0xbfb8aa3b, v61
	v_exp_f32_e32 v69, v69
	v_cndmask_b32_e64 v68, 0, 32, vcc
	v_ldexp_f32 v64, v64, v68
	v_log_f32_e32 v64, v64
	v_add_f32_e32 v69, 1.0, v69
	v_rcp_f32_e32 v69, v69
	v_mul_f32_e32 v68, 0x3f317217, v64
	v_fma_f32 v68, v64, s2, -v68
	v_fmac_f32_e32 v68, 0x3377d1cf, v64
	v_fmac_f32_e32 v68, 0x3f317217, v64
	v_cmp_lt_f32_e64 s[12:13], |v64|, s26
	s_nop 1
	v_cndmask_b32_e64 v64, v64, v68, s[12:13]
	v_cndmask_b32_e32 v68, 0, v226, vcc
	v_sub_f32_e32 v64, v64, v68
	v_sub_f32_e32 v68, 1.0, v65
	v_fmac_f32_e32 v65, v69, v68
	v_cmp_gt_f32_e32 vcc, s7, v65
	s_nop 1
	v_cndmask_b32_e64 v68, 0, 32, vcc
	v_ldexp_f32 v65, v65, v68
	v_log_f32_e32 v65, v65
	s_nop 0
	v_mul_f32_e32 v68, 0x3f317217, v65
	v_fma_f32 v68, v65, s2, -v68
	v_fmac_f32_e32 v68, 0x3377d1cf, v65
	v_fmac_f32_e32 v68, 0x3f317217, v65
	v_cmp_lt_f32_e64 s[12:13], |v65|, s26
	s_nop 1
	v_cndmask_b32_e64 v65, v65, v68, s[12:13]
	v_cndmask_b32_e32 v68, 0, v226, vcc
	v_sub_f32_e32 v65, v65, v68
	s_mov_b64 s[12:13], 0

.LBB0_1291:
	v_cvt_pk_bf16_f32 v58, v62, v63
	v_cvt_pk_bf16_f32 v59, v64, v65
	s_cmp_gt_i32 s40, 1
	s_mov_b64 s[12:13], -1
	v_mov_b32_e32 v142, v58
	v_mov_b32_e32 v143, v59
	v_bfe_u32 v144, v182, 4, 1
	v_mul_u32_u24_e32 v144, 24, v144
	v_mov_b32_e32 v145, 0
	v_lshl_add_u64 v[146:147], v[66:67], 0, v[144:145]
	v_permlane16_swap_b32_e32 v140, v142
	v_permlane16_swap_b32_e32 v141, v143
	global_store_dwordx4 v[146:147], v[140:143], off
	s_cbranch_scc0 .LBB0_1293
	global_load_dwordx4 v[58:61], v134, s[22:23] offset:128
	v_mul_f32_e32 v63, 0xbfb8aa3b, v54
	v_exp_f32_e32 v63, v63
	s_mov_b32 s2, 0x3f317217
	s_mov_b32 s26, 0x7f800000
	v_add_f32_e32 v63, 1.0, v63
	v_rcp_f32_e32 v63, v63
	s_waitcnt vmcnt(0)
	v_sub_f32_e32 v62, 1.0, v58
	v_fma_f32 v58, v63, v62, v58
	v_cmp_gt_f32_e32 vcc, s7, v58
	v_mul_f32_e32 v63, 0xbfb8aa3b, v55
	v_exp_f32_e32 v63, v63
	v_cndmask_b32_e64 v62, 0, 32, vcc
	v_ldexp_f32 v58, v58, v62
	v_log_f32_e32 v58, v58
	v_add_f32_e32 v63, 1.0, v63
	v_rcp_f32_e32 v63, v63
	v_mul_f32_e32 v62, 0x3f317217, v58
	v_fma_f32 v62, v58, s2, -v62
	v_fmac_f32_e32 v62, 0x3377d1cf, v58
	v_fmac_f32_e32 v62, 0x3f317217, v58
	v_cmp_lt_f32_e64 s[12:13], |v58|, s26
	s_nop 1
	v_cndmask_b32_e64 v58, v58, v62, s[12:13]
	v_cndmask_b32_e32 v62, 0, v226, vcc
	v_sub_f32_e32 v58, v58, v62
	v_sub_f32_e32 v62, 1.0, v59
	v_fma_f32 v59, v63, v62, v59
	v_cmp_gt_f32_e32 vcc, s7, v59
	v_mul_f32_e32 v63, 0xbfb8aa3b, v56
	v_exp_f32_e32 v63, v63
	v_cndmask_b32_e64 v62, 0, 32, vcc
	v_ldexp_f32 v59, v59, v62
	v_log_f32_e32 v59, v59
	v_add_f32_e32 v63, 1.0, v63
	v_rcp_f32_e32 v63, v63
	v_mul_f32_e32 v62, 0x3f317217, v59
	v_fma_f32 v62, v59, s2, -v62
	v_fmac_f32_e32 v62, 0x3377d1cf, v59
	v_fmac_f32_e32 v62, 0x3f317217, v59
	v_cmp_lt_f32_e64 s[12:13], |v59|, s26
	s_nop 1
	v_cndmask_b32_e64 v59, v59, v62, s[12:13]
	v_cndmask_b32_e32 v62, 0, v226, vcc
	v_sub_f32_e32 v59, v59, v62
	v_sub_f32_e32 v62, 1.0, v60
	v_fma_f32 v60, v63, v62, v60
	v_cmp_gt_f32_e32 vcc, s7, v60
	v_mul_f32_e32 v63, 0xbfb8aa3b, v57
	v_exp_f32_e32 v63, v63
	v_cndmask_b32_e64 v62, 0, 32, vcc
	v_ldexp_f32 v60, v60, v62
	v_log_f32_e32 v60, v60
	v_add_f32_e32 v63, 1.0, v63
	v_rcp_f32_e32 v63, v63
	v_mul_f32_e32 v62, 0x3f317217, v60
	v_fma_f32 v62, v60, s2, -v62
	v_fmac_f32_e32 v62, 0x3377d1cf, v60
	v_fmac_f32_e32 v62, 0x3f317217, v60
	v_cmp_lt_f32_e64 s[12:13], |v60|, s26
	s_nop 1
	v_cndmask_b32_e64 v60, v60, v62, s[12:13]
	v_cndmask_b32_e32 v62, 0, v226, vcc
	v_sub_f32_e32 v60, v60, v62
	v_sub_f32_e32 v62, 1.0, v61
	v_fmac_f32_e32 v61, v63, v62
	v_cmp_gt_f32_e32 vcc, s7, v61
	s_nop 1
	v_cndmask_b32_e64 v62, 0, 32, vcc
	v_ldexp_f32 v61, v61, v62
	v_log_f32_e32 v61, v61
	s_nop 0
	v_mul_f32_e32 v62, 0x3f317217, v61
	v_fma_f32 v62, v61, s2, -v62
	v_fmac_f32_e32 v62, 0x3377d1cf, v61
	v_fmac_f32_e32 v62, 0x3f317217, v61
	v_cmp_lt_f32_e64 s[12:13], |v61|, s26
	s_nop 1
	v_cndmask_b32_e64 v61, v61, v62, s[12:13]
	v_cndmask_b32_e32 v62, 0, v226, vcc
	v_sub_f32_e32 v61, v61, v62
	s_mov_b64 s[12:13], 0

.LBB0_1297:
	v_cvt_pk_bf16_f32 v54, v58, v59
	v_cvt_pk_bf16_f32 v55, v60, v61
	s_cmp_gt_i32 s40, 1
	s_mov_b64 s[12:13], -1
	v_mov_b32_e32 v140, v54
	v_mov_b32_e32 v141, v55
	s_cbranch_scc0 .LBB0_1299
	global_load_dwordx4 v[54:57], v134, s[22:23] offset:192
	v_mul_f32_e32 v59, 0xbfb8aa3b, v50
	v_exp_f32_e32 v59, v59
	s_mov_b32 s2, 0x3f317217
	s_mov_b32 s26, 0x7f800000
	v_add_f32_e32 v59, 1.0, v59
	v_rcp_f32_e32 v59, v59
	s_waitcnt vmcnt(0)
	v_sub_f32_e32 v58, 1.0, v54
	v_fma_f32 v54, v59, v58, v54
	v_cmp_gt_f32_e32 vcc, s7, v54
	v_mul_f32_e32 v59, 0xbfb8aa3b, v51
	v_exp_f32_e32 v59, v59
	v_cndmask_b32_e64 v58, 0, 32, vcc
	v_ldexp_f32 v54, v54, v58
	v_log_f32_e32 v54, v54
	v_add_f32_e32 v59, 1.0, v59
	v_rcp_f32_e32 v59, v59
	v_mul_f32_e32 v58, 0x3f317217, v54
	v_fma_f32 v58, v54, s2, -v58
	v_fmac_f32_e32 v58, 0x3377d1cf, v54
	v_fmac_f32_e32 v58, 0x3f317217, v54
	v_cmp_lt_f32_e64 s[12:13], |v54|, s26
	s_nop 1
	v_cndmask_b32_e64 v54, v54, v58, s[12:13]
	v_cndmask_b32_e32 v58, 0, v226, vcc
	v_sub_f32_e32 v54, v54, v58
	v_sub_f32_e32 v58, 1.0, v55
	v_fma_f32 v55, v59, v58, v55
	v_cmp_gt_f32_e32 vcc, s7, v55
	v_mul_f32_e32 v59, 0xbfb8aa3b, v52
	v_exp_f32_e32 v59, v59
	v_cndmask_b32_e64 v58, 0, 32, vcc
	v_ldexp_f32 v55, v55, v58
	v_log_f32_e32 v55, v55
	v_add_f32_e32 v59, 1.0, v59
	v_rcp_f32_e32 v59, v59
	v_mul_f32_e32 v58, 0x3f317217, v55
	v_fma_f32 v58, v55, s2, -v58
	v_fmac_f32_e32 v58, 0x3377d1cf, v55
	v_fmac_f32_e32 v58, 0x3f317217, v55
	v_cmp_lt_f32_e64 s[12:13], |v55|, s26
	s_nop 1
	v_cndmask_b32_e64 v55, v55, v58, s[12:13]
	v_cndmask_b32_e32 v58, 0, v226, vcc
	v_sub_f32_e32 v55, v55, v58
	v_sub_f32_e32 v58, 1.0, v56
	v_fma_f32 v56, v59, v58, v56
	v_cmp_gt_f32_e32 vcc, s7, v56
	v_mul_f32_e32 v59, 0xbfb8aa3b, v53
	v_exp_f32_e32 v59, v59
	v_cndmask_b32_e64 v58, 0, 32, vcc
	v_ldexp_f32 v56, v56, v58
	v_log_f32_e32 v56, v56
	v_add_f32_e32 v59, 1.0, v59
	v_rcp_f32_e32 v59, v59
	v_mul_f32_e32 v58, 0x3f317217, v56
	v_fma_f32 v58, v56, s2, -v58
	v_fmac_f32_e32 v58, 0x3377d1cf, v56
	v_fmac_f32_e32 v58, 0x3f317217, v56
	v_cmp_lt_f32_e64 s[12:13], |v56|, s26
	s_nop 1
	v_cndmask_b32_e64 v56, v56, v58, s[12:13]
	v_cndmask_b32_e32 v58, 0, v226, vcc
	v_sub_f32_e32 v56, v56, v58
	v_sub_f32_e32 v58, 1.0, v57
	v_fmac_f32_e32 v57, v59, v58
	v_cmp_gt_f32_e32 vcc, s7, v57
	s_nop 1
	v_cndmask_b32_e64 v58, 0, 32, vcc
	v_ldexp_f32 v57, v57, v58
	v_log_f32_e32 v57, v57
	s_nop 0
	v_mul_f32_e32 v58, 0x3f317217, v57
	v_fma_f32 v58, v57, s2, -v58
	v_fmac_f32_e32 v58, 0x3377d1cf, v57
	v_fmac_f32_e32 v58, 0x3f317217, v57
	v_cmp_lt_f32_e64 s[12:13], |v57|, s26
	s_nop 1
	v_cndmask_b32_e64 v57, v57, v58, s[12:13]
	v_cndmask_b32_e32 v58, 0, v226, vcc
	v_sub_f32_e32 v57, v57, v58
	s_mov_b64 s[12:13], 0

.LBB0_1303:
	v_cvt_pk_bf16_f32 v50, v54, v55
	v_cvt_pk_bf16_f32 v51, v56, v57
	v_mov_b32_e32 v142, v50
	v_mov_b32_e32 v143, v51
	v_bfe_u32 v144, v182, 4, 1
	v_mul_u32_u24_e32 v144, 24, v144
	v_mov_b32_e32 v145, 0
	v_lshl_add_u64 v[146:147], v[66:67], 0, v[144:145]
	v_permlane16_swap_b32_e32 v140, v142
	v_permlane16_swap_b32_e32 v141, v143
	global_store_dwordx4 v[146:147], v[140:143], off offset:64
	s_cmp_gt_i32 s40, 1
	s_mov_b64 s[12:13], -1
	s_cbranch_scc0 .LBB0_1305
	global_load_dwordx4 v[50:53], v134, s[22:23]
	v_mul_f32_e32 v55, 0xbfb8aa3b, v46
	v_exp_f32_e32 v55, v55
	s_mov_b32 s2, 0x3f317217
	s_mov_b32 s26, 0x7f800000
	v_add_f32_e32 v55, 1.0, v55
	v_rcp_f32_e32 v55, v55
	s_waitcnt vmcnt(0)
	v_sub_f32_e32 v54, 1.0, v50
	v_fma_f32 v50, v55, v54, v50
	v_cmp_gt_f32_e32 vcc, s7, v50
	v_mul_f32_e32 v55, 0xbfb8aa3b, v47
	v_exp_f32_e32 v55, v55
	v_cndmask_b32_e64 v54, 0, 32, vcc
	v_ldexp_f32 v50, v50, v54
	v_log_f32_e32 v50, v50
	v_add_f32_e32 v55, 1.0, v55
	v_rcp_f32_e32 v55, v55
	v_mul_f32_e32 v54, 0x3f317217, v50
	v_fma_f32 v54, v50, s2, -v54
	v_fmac_f32_e32 v54, 0x3377d1cf, v50
	v_fmac_f32_e32 v54, 0x3f317217, v50
	v_cmp_lt_f32_e64 s[12:13], |v50|, s26
	s_nop 1
	v_cndmask_b32_e64 v50, v50, v54, s[12:13]
	v_cndmask_b32_e32 v54, 0, v226, vcc
	v_sub_f32_e32 v50, v50, v54
	v_sub_f32_e32 v54, 1.0, v51
	v_fma_f32 v51, v55, v54, v51
	v_cmp_gt_f32_e32 vcc, s7, v51
	v_mul_f32_e32 v55, 0xbfb8aa3b, v48
	v_exp_f32_e32 v55, v55
	v_cndmask_b32_e64 v54, 0, 32, vcc
	v_ldexp_f32 v51, v51, v54
	v_log_f32_e32 v51, v51
	v_add_f32_e32 v55, 1.0, v55
	v_rcp_f32_e32 v55, v55
	v_mul_f32_e32 v54, 0x3f317217, v51
	v_fma_f32 v54, v51, s2, -v54
	v_fmac_f32_e32 v54, 0x3377d1cf, v51
	v_fmac_f32_e32 v54, 0x3f317217, v51
	v_cmp_lt_f32_e64 s[12:13], |v51|, s26
	s_nop 1
	v_cndmask_b32_e64 v51, v51, v54, s[12:13]
	v_cndmask_b32_e32 v54, 0, v226, vcc
	v_sub_f32_e32 v51, v51, v54
	v_sub_f32_e32 v54, 1.0, v52
	v_fma_f32 v52, v55, v54, v52
	v_cmp_gt_f32_e32 vcc, s7, v52
	v_mul_f32_e32 v55, 0xbfb8aa3b, v49
	v_exp_f32_e32 v55, v55
	v_cndmask_b32_e64 v54, 0, 32, vcc
	v_ldexp_f32 v52, v52, v54
	v_log_f32_e32 v52, v52
	v_add_f32_e32 v55, 1.0, v55
	v_rcp_f32_e32 v55, v55
	v_mul_f32_e32 v54, 0x3f317217, v52
	v_fma_f32 v54, v52, s2, -v54
	v_fmac_f32_e32 v54, 0x3377d1cf, v52
	v_fmac_f32_e32 v54, 0x3f317217, v52
	v_cmp_lt_f32_e64 s[12:13], |v52|, s26
	s_nop 1
	v_cndmask_b32_e64 v52, v52, v54, s[12:13]
	v_cndmask_b32_e32 v54, 0, v226, vcc
	v_sub_f32_e32 v52, v52, v54
	v_sub_f32_e32 v54, 1.0, v53
	v_fmac_f32_e32 v53, v55, v54
	v_cmp_gt_f32_e32 vcc, s7, v53
	s_nop 1
	v_cndmask_b32_e64 v54, 0, 32, vcc
	v_ldexp_f32 v53, v53, v54
	v_log_f32_e32 v53, v53
	s_nop 0
	v_mul_f32_e32 v54, 0x3f317217, v53
	v_fma_f32 v54, v53, s2, -v54
	v_fmac_f32_e32 v54, 0x3377d1cf, v53
	v_fmac_f32_e32 v54, 0x3f317217, v53
	v_cmp_lt_f32_e64 s[12:13], |v53|, s26
	s_nop 1
	v_cndmask_b32_e64 v53, v53, v54, s[12:13]
	v_cndmask_b32_e32 v54, 0, v226, vcc
	v_sub_f32_e32 v53, v53, v54
	s_mov_b64 s[12:13], 0

.LBB0_1309:
	v_lshl_add_u64 v[48:49], s[24:25], 0, v[206:207]
	v_cvt_pk_bf16_f32 v46, v50, v51
	v_cvt_pk_bf16_f32 v47, v52, v53
	v_lshl_add_u64 v[50:51], v[48:49], 0, v[0:1]
	s_cmp_gt_i32 s40, 1
	s_mov_b64 s[12:13], -1
	v_mov_b32_e32 v140, v46
	v_mov_b32_e32 v141, v47
	s_cbranch_scc0 .LBB0_1311
	global_load_dwordx4 v[46:49], v134, s[22:23] offset:64
	v_mul_f32_e32 v53, 0xbfb8aa3b, v42
	v_exp_f32_e32 v53, v53
	s_mov_b32 s2, 0x3f317217
	s_mov_b32 s26, 0x7f800000
	v_add_f32_e32 v53, 1.0, v53
	v_rcp_f32_e32 v53, v53
	s_waitcnt vmcnt(0)
	v_sub_f32_e32 v52, 1.0, v46
	v_fma_f32 v46, v53, v52, v46
	v_cmp_gt_f32_e32 vcc, s7, v46
	v_mul_f32_e32 v53, 0xbfb8aa3b, v43
	v_exp_f32_e32 v53, v53
	v_cndmask_b32_e64 v52, 0, 32, vcc
	v_ldexp_f32 v46, v46, v52
	v_log_f32_e32 v46, v46
	v_add_f32_e32 v53, 1.0, v53
	v_rcp_f32_e32 v53, v53
	v_mul_f32_e32 v52, 0x3f317217, v46
	v_fma_f32 v52, v46, s2, -v52
	v_fmac_f32_e32 v52, 0x3377d1cf, v46
	v_fmac_f32_e32 v52, 0x3f317217, v46
	v_cmp_lt_f32_e64 s[12:13], |v46|, s26
	s_nop 1
	v_cndmask_b32_e64 v46, v46, v52, s[12:13]
	v_cndmask_b32_e32 v52, 0, v226, vcc
	v_sub_f32_e32 v46, v46, v52
	v_sub_f32_e32 v52, 1.0, v47
	v_fma_f32 v47, v53, v52, v47
	v_cmp_gt_f32_e32 vcc, s7, v47
	v_mul_f32_e32 v53, 0xbfb8aa3b, v44
	v_exp_f32_e32 v53, v53
	v_cndmask_b32_e64 v52, 0, 32, vcc
	v_ldexp_f32 v47, v47, v52
	v_log_f32_e32 v47, v47
	v_add_f32_e32 v53, 1.0, v53
	v_rcp_f32_e32 v53, v53
	v_mul_f32_e32 v52, 0x3f317217, v47
	v_fma_f32 v52, v47, s2, -v52
	v_fmac_f32_e32 v52, 0x3377d1cf, v47
	v_fmac_f32_e32 v52, 0x3f317217, v47
	v_cmp_lt_f32_e64 s[12:13], |v47|, s26
	s_nop 1
	v_cndmask_b32_e64 v47, v47, v52, s[12:13]
	v_cndmask_b32_e32 v52, 0, v226, vcc
	v_sub_f32_e32 v47, v47, v52
	v_sub_f32_e32 v52, 1.0, v48
	v_fma_f32 v48, v53, v52, v48
	v_cmp_gt_f32_e32 vcc, s7, v48
	v_mul_f32_e32 v53, 0xbfb8aa3b, v45
	v_exp_f32_e32 v53, v53
	v_cndmask_b32_e64 v52, 0, 32, vcc
	v_ldexp_f32 v48, v48, v52
	v_log_f32_e32 v48, v48
	v_add_f32_e32 v53, 1.0, v53
	v_rcp_f32_e32 v53, v53
	v_mul_f32_e32 v52, 0x3f317217, v48
	v_fma_f32 v52, v48, s2, -v52
	v_fmac_f32_e32 v52, 0x3377d1cf, v48
	v_fmac_f32_e32 v52, 0x3f317217, v48
	v_cmp_lt_f32_e64 s[12:13], |v48|, s26
	s_nop 1
	v_cndmask_b32_e64 v48, v48, v52, s[12:13]
	v_cndmask_b32_e32 v52, 0, v226, vcc
	v_sub_f32_e32 v48, v48, v52
	v_sub_f32_e32 v52, 1.0, v49
	v_fmac_f32_e32 v49, v53, v52
	v_cmp_gt_f32_e32 vcc, s7, v49
	s_nop 1
	v_cndmask_b32_e64 v52, 0, 32, vcc
	v_ldexp_f32 v49, v49, v52
	v_log_f32_e32 v49, v49
	s_nop 0
	v_mul_f32_e32 v52, 0x3f317217, v49
	v_fma_f32 v52, v49, s2, -v52
	v_fmac_f32_e32 v52, 0x3377d1cf, v49
	v_fmac_f32_e32 v52, 0x3f317217, v49
	v_cmp_lt_f32_e64 s[12:13], |v49|, s26
	s_nop 1
	v_cndmask_b32_e64 v49, v49, v52, s[12:13]
	v_cndmask_b32_e32 v52, 0, v226, vcc
	v_sub_f32_e32 v49, v49, v52
	s_mov_b64 s[12:13], 0

.LBB0_1315:
	v_cvt_pk_bf16_f32 v42, v46, v47
	v_cvt_pk_bf16_f32 v43, v48, v49
	s_cmp_gt_i32 s40, 1
	s_mov_b64 s[12:13], -1
	v_mov_b32_e32 v142, v42
	v_mov_b32_e32 v143, v43
	v_bfe_u32 v144, v182, 4, 1
	v_mul_u32_u24_e32 v144, 24, v144
	v_mov_b32_e32 v145, 0
	v_lshl_add_u64 v[146:147], v[50:51], 0, v[144:145]
	v_permlane16_swap_b32_e32 v140, v142
	v_permlane16_swap_b32_e32 v141, v143
	global_store_dwordx4 v[146:147], v[140:143], off
	s_cbranch_scc0 .LBB0_1317
	global_load_dwordx4 v[42:45], v134, s[22:23] offset:128
	v_mul_f32_e32 v47, 0xbfb8aa3b, v38
	v_exp_f32_e32 v47, v47
	s_mov_b32 s2, 0x3f317217
	s_mov_b32 s26, 0x7f800000
	v_add_f32_e32 v47, 1.0, v47
	v_rcp_f32_e32 v47, v47
	s_waitcnt vmcnt(0)
	v_sub_f32_e32 v46, 1.0, v42
	v_fma_f32 v42, v47, v46, v42
	v_cmp_gt_f32_e32 vcc, s7, v42
	v_mul_f32_e32 v47, 0xbfb8aa3b, v39
	v_exp_f32_e32 v47, v47
	v_cndmask_b32_e64 v46, 0, 32, vcc
	v_ldexp_f32 v42, v42, v46
	v_log_f32_e32 v42, v42
	v_add_f32_e32 v47, 1.0, v47
	v_rcp_f32_e32 v47, v47
	v_mul_f32_e32 v46, 0x3f317217, v42
	v_fma_f32 v46, v42, s2, -v46
	v_fmac_f32_e32 v46, 0x3377d1cf, v42
	v_fmac_f32_e32 v46, 0x3f317217, v42
	v_cmp_lt_f32_e64 s[12:13], |v42|, s26
	s_nop 1
	v_cndmask_b32_e64 v42, v42, v46, s[12:13]
	v_cndmask_b32_e32 v46, 0, v226, vcc
	v_sub_f32_e32 v42, v42, v46
	v_sub_f32_e32 v46, 1.0, v43
	v_fma_f32 v43, v47, v46, v43
	v_cmp_gt_f32_e32 vcc, s7, v43
	v_mul_f32_e32 v47, 0xbfb8aa3b, v40
	v_exp_f32_e32 v47, v47
	v_cndmask_b32_e64 v46, 0, 32, vcc
	v_ldexp_f32 v43, v43, v46
	v_log_f32_e32 v43, v43
	v_add_f32_e32 v47, 1.0, v47
	v_rcp_f32_e32 v47, v47
	v_mul_f32_e32 v46, 0x3f317217, v43
	v_fma_f32 v46, v43, s2, -v46
	v_fmac_f32_e32 v46, 0x3377d1cf, v43
	v_fmac_f32_e32 v46, 0x3f317217, v43
	v_cmp_lt_f32_e64 s[12:13], |v43|, s26
	s_nop 1
	v_cndmask_b32_e64 v43, v43, v46, s[12:13]
	v_cndmask_b32_e32 v46, 0, v226, vcc
	v_sub_f32_e32 v43, v43, v46
	v_sub_f32_e32 v46, 1.0, v44
	v_fma_f32 v44, v47, v46, v44
	v_cmp_gt_f32_e32 vcc, s7, v44
	v_mul_f32_e32 v47, 0xbfb8aa3b, v41
	v_exp_f32_e32 v47, v47
	v_cndmask_b32_e64 v46, 0, 32, vcc
	v_ldexp_f32 v44, v44, v46
	v_log_f32_e32 v44, v44
	v_add_f32_e32 v47, 1.0, v47
	v_rcp_f32_e32 v47, v47
	v_mul_f32_e32 v46, 0x3f317217, v44
	v_fma_f32 v46, v44, s2, -v46
	v_fmac_f32_e32 v46, 0x3377d1cf, v44
	v_fmac_f32_e32 v46, 0x3f317217, v44
	v_cmp_lt_f32_e64 s[12:13], |v44|, s26
	s_nop 1
	v_cndmask_b32_e64 v44, v44, v46, s[12:13]
	v_cndmask_b32_e32 v46, 0, v226, vcc
	v_sub_f32_e32 v44, v44, v46
	v_sub_f32_e32 v46, 1.0, v45
	v_fmac_f32_e32 v45, v47, v46
	v_cmp_gt_f32_e32 vcc, s7, v45
	s_nop 1
	v_cndmask_b32_e64 v46, 0, 32, vcc
	v_ldexp_f32 v45, v45, v46
	v_log_f32_e32 v45, v45
	s_nop 0
	v_mul_f32_e32 v46, 0x3f317217, v45
	v_fma_f32 v46, v45, s2, -v46
	v_fmac_f32_e32 v46, 0x3377d1cf, v45
	v_fmac_f32_e32 v46, 0x3f317217, v45
	v_cmp_lt_f32_e64 s[12:13], |v45|, s26
	s_nop 1
	v_cndmask_b32_e64 v45, v45, v46, s[12:13]
	v_cndmask_b32_e32 v46, 0, v226, vcc
	v_sub_f32_e32 v45, v45, v46
	s_mov_b64 s[12:13], 0

.LBB0_1321:
	v_cvt_pk_bf16_f32 v38, v42, v43
	v_cvt_pk_bf16_f32 v39, v44, v45
	s_cmp_gt_i32 s40, 1
	s_mov_b64 s[12:13], -1
	v_mov_b32_e32 v140, v38
	v_mov_b32_e32 v141, v39
	s_cbranch_scc0 .LBB0_1323
	global_load_dwordx4 v[38:41], v134, s[22:23] offset:192
	v_mul_f32_e32 v43, 0xbfb8aa3b, v34
	v_exp_f32_e32 v43, v43
	s_mov_b32 s2, 0x3f317217
	s_mov_b32 s26, 0x7f800000
	v_add_f32_e32 v43, 1.0, v43
	v_rcp_f32_e32 v43, v43
	s_waitcnt vmcnt(0)
	v_sub_f32_e32 v42, 1.0, v38
	v_fma_f32 v38, v43, v42, v38
	v_cmp_gt_f32_e32 vcc, s7, v38
	v_mul_f32_e32 v43, 0xbfb8aa3b, v35
	v_exp_f32_e32 v43, v43
	v_cndmask_b32_e64 v42, 0, 32, vcc
	v_ldexp_f32 v38, v38, v42
	v_log_f32_e32 v38, v38
	v_add_f32_e32 v43, 1.0, v43
	v_rcp_f32_e32 v43, v43
	v_mul_f32_e32 v42, 0x3f317217, v38
	v_fma_f32 v42, v38, s2, -v42
	v_fmac_f32_e32 v42, 0x3377d1cf, v38
	v_fmac_f32_e32 v42, 0x3f317217, v38
	v_cmp_lt_f32_e64 s[12:13], |v38|, s26
	s_nop 1
	v_cndmask_b32_e64 v38, v38, v42, s[12:13]
	v_cndmask_b32_e32 v42, 0, v226, vcc
	v_sub_f32_e32 v38, v38, v42
	v_sub_f32_e32 v42, 1.0, v39
	v_fma_f32 v39, v43, v42, v39
	v_cmp_gt_f32_e32 vcc, s7, v39
	v_mul_f32_e32 v43, 0xbfb8aa3b, v36
	v_exp_f32_e32 v43, v43
	v_cndmask_b32_e64 v42, 0, 32, vcc
	v_ldexp_f32 v39, v39, v42
	v_log_f32_e32 v39, v39
	v_add_f32_e32 v43, 1.0, v43
	v_rcp_f32_e32 v43, v43
	v_mul_f32_e32 v42, 0x3f317217, v39
	v_fma_f32 v42, v39, s2, -v42
	v_fmac_f32_e32 v42, 0x3377d1cf, v39
	v_fmac_f32_e32 v42, 0x3f317217, v39
	v_cmp_lt_f32_e64 s[12:13], |v39|, s26
	s_nop 1
	v_cndmask_b32_e64 v39, v39, v42, s[12:13]
	v_cndmask_b32_e32 v42, 0, v226, vcc
	v_sub_f32_e32 v39, v39, v42
	v_sub_f32_e32 v42, 1.0, v40
	v_fma_f32 v40, v43, v42, v40
	v_cmp_gt_f32_e32 vcc, s7, v40
	v_mul_f32_e32 v43, 0xbfb8aa3b, v37
	v_exp_f32_e32 v43, v43
	v_cndmask_b32_e64 v42, 0, 32, vcc
	v_ldexp_f32 v40, v40, v42
	v_log_f32_e32 v40, v40
	v_add_f32_e32 v43, 1.0, v43
	v_rcp_f32_e32 v43, v43
	v_mul_f32_e32 v42, 0x3f317217, v40
	v_fma_f32 v42, v40, s2, -v42
	v_fmac_f32_e32 v42, 0x3377d1cf, v40
	v_fmac_f32_e32 v42, 0x3f317217, v40
	v_cmp_lt_f32_e64 s[12:13], |v40|, s26
	s_nop 1
	v_cndmask_b32_e64 v40, v40, v42, s[12:13]
	v_cndmask_b32_e32 v42, 0, v226, vcc
	v_sub_f32_e32 v40, v40, v42
	v_sub_f32_e32 v42, 1.0, v41
	v_fmac_f32_e32 v41, v43, v42
	v_cmp_gt_f32_e32 vcc, s7, v41
	s_nop 1
	v_cndmask_b32_e64 v42, 0, 32, vcc
	v_ldexp_f32 v41, v41, v42
	v_log_f32_e32 v41, v41
	s_nop 0
	v_mul_f32_e32 v42, 0x3f317217, v41
	v_fma_f32 v42, v41, s2, -v42
	v_fmac_f32_e32 v42, 0x3377d1cf, v41
	v_fmac_f32_e32 v42, 0x3f317217, v41
	v_cmp_lt_f32_e64 s[12:13], |v41|, s26
	s_nop 1
	v_cndmask_b32_e64 v41, v41, v42, s[12:13]
	v_cndmask_b32_e32 v42, 0, v226, vcc
	v_sub_f32_e32 v41, v41, v42
	s_mov_b64 s[12:13], 0

.LBB0_1327:
	v_cvt_pk_bf16_f32 v34, v38, v39
	v_cvt_pk_bf16_f32 v35, v40, v41
	v_mov_b32_e32 v142, v34
	v_mov_b32_e32 v143, v35
	v_bfe_u32 v144, v182, 4, 1
	v_mul_u32_u24_e32 v144, 24, v144
	v_mov_b32_e32 v145, 0
	v_lshl_add_u64 v[146:147], v[50:51], 0, v[144:145]
	v_permlane16_swap_b32_e32 v140, v142
	v_permlane16_swap_b32_e32 v141, v143
	global_store_dwordx4 v[146:147], v[140:143], off offset:64
	s_cmp_gt_i32 s40, 1
	s_mov_b64 s[12:13], -1
	s_cbranch_scc0 .LBB0_1329
	global_load_dwordx4 v[34:37], v134, s[22:23]
	v_mul_f32_e32 v39, 0xbfb8aa3b, v30
	v_exp_f32_e32 v39, v39
	s_mov_b32 s2, 0x3f317217
	s_mov_b32 s26, 0x7f800000
	v_add_f32_e32 v39, 1.0, v39
	v_rcp_f32_e32 v39, v39
	s_waitcnt vmcnt(0)
	v_sub_f32_e32 v38, 1.0, v34
	v_fma_f32 v34, v39, v38, v34
	v_cmp_gt_f32_e32 vcc, s7, v34
	v_mul_f32_e32 v39, 0xbfb8aa3b, v31
	v_exp_f32_e32 v39, v39
	v_cndmask_b32_e64 v38, 0, 32, vcc
	v_ldexp_f32 v34, v34, v38
	v_log_f32_e32 v34, v34
	v_add_f32_e32 v39, 1.0, v39
	v_rcp_f32_e32 v39, v39
	v_mul_f32_e32 v38, 0x3f317217, v34
	v_fma_f32 v38, v34, s2, -v38
	v_fmac_f32_e32 v38, 0x3377d1cf, v34
	v_fmac_f32_e32 v38, 0x3f317217, v34
	v_cmp_lt_f32_e64 s[12:13], |v34|, s26
	s_nop 1
	v_cndmask_b32_e64 v34, v34, v38, s[12:13]
	v_cndmask_b32_e32 v38, 0, v226, vcc
	v_sub_f32_e32 v34, v34, v38
	v_sub_f32_e32 v38, 1.0, v35
	v_fma_f32 v35, v39, v38, v35
	v_cmp_gt_f32_e32 vcc, s7, v35
	v_mul_f32_e32 v39, 0xbfb8aa3b, v32
	v_exp_f32_e32 v39, v39
	v_cndmask_b32_e64 v38, 0, 32, vcc
	v_ldexp_f32 v35, v35, v38
	v_log_f32_e32 v35, v35
	v_add_f32_e32 v39, 1.0, v39
	v_rcp_f32_e32 v39, v39
	v_mul_f32_e32 v38, 0x3f317217, v35
	v_fma_f32 v38, v35, s2, -v38
	v_fmac_f32_e32 v38, 0x3377d1cf, v35
	v_fmac_f32_e32 v38, 0x3f317217, v35
	v_cmp_lt_f32_e64 s[12:13], |v35|, s26
	s_nop 1
	v_cndmask_b32_e64 v35, v35, v38, s[12:13]
	v_cndmask_b32_e32 v38, 0, v226, vcc
	v_sub_f32_e32 v35, v35, v38
	v_sub_f32_e32 v38, 1.0, v36
	v_fma_f32 v36, v39, v38, v36
	v_cmp_gt_f32_e32 vcc, s7, v36
	v_mul_f32_e32 v39, 0xbfb8aa3b, v33
	v_exp_f32_e32 v39, v39
	v_cndmask_b32_e64 v38, 0, 32, vcc
	v_ldexp_f32 v36, v36, v38
	v_log_f32_e32 v36, v36
	v_add_f32_e32 v39, 1.0, v39
	v_rcp_f32_e32 v39, v39
	v_mul_f32_e32 v38, 0x3f317217, v36
	v_fma_f32 v38, v36, s2, -v38
	v_fmac_f32_e32 v38, 0x3377d1cf, v36
	v_fmac_f32_e32 v38, 0x3f317217, v36
	v_cmp_lt_f32_e64 s[12:13], |v36|, s26
	s_nop 1
	v_cndmask_b32_e64 v36, v36, v38, s[12:13]
	v_cndmask_b32_e32 v38, 0, v226, vcc
	v_sub_f32_e32 v36, v36, v38
	v_sub_f32_e32 v38, 1.0, v37
	v_fmac_f32_e32 v37, v39, v38
	v_cmp_gt_f32_e32 vcc, s7, v37
	s_nop 1
	v_cndmask_b32_e64 v38, 0, 32, vcc
	v_ldexp_f32 v37, v37, v38
	v_log_f32_e32 v37, v37
	s_nop 0
	v_mul_f32_e32 v38, 0x3f317217, v37
	v_fma_f32 v38, v37, s2, -v38
	v_fmac_f32_e32 v38, 0x3377d1cf, v37
	v_fmac_f32_e32 v38, 0x3f317217, v37
	v_cmp_lt_f32_e64 s[12:13], |v37|, s26
	s_nop 1
	v_cndmask_b32_e64 v37, v37, v38, s[12:13]
	v_cndmask_b32_e32 v38, 0, v226, vcc
	v_sub_f32_e32 v37, v37, v38
	s_mov_b64 s[12:13], 0

.LBB0_1333:
	v_lshl_add_u64 v[32:33], s[24:25], 0, v[208:209]
	v_cvt_pk_bf16_f32 v30, v34, v35
	v_cvt_pk_bf16_f32 v31, v36, v37
	v_lshl_add_u64 v[34:35], v[32:33], 0, v[0:1]
	s_cmp_gt_i32 s40, 1
	s_mov_b64 s[12:13], -1
	v_mov_b32_e32 v140, v30
	v_mov_b32_e32 v141, v31
	s_cbranch_scc0 .LBB0_1335
	global_load_dwordx4 v[30:33], v134, s[22:23] offset:64
	v_mul_f32_e32 v37, 0xbfb8aa3b, v26
	v_exp_f32_e32 v37, v37
	s_mov_b32 s2, 0x3f317217
	s_mov_b32 s26, 0x7f800000
	v_add_f32_e32 v37, 1.0, v37
	v_rcp_f32_e32 v37, v37
	s_waitcnt vmcnt(0)
	v_sub_f32_e32 v36, 1.0, v30
	v_fma_f32 v30, v37, v36, v30
	v_cmp_gt_f32_e32 vcc, s7, v30
	v_mul_f32_e32 v37, 0xbfb8aa3b, v27
	v_exp_f32_e32 v37, v37
	v_cndmask_b32_e64 v36, 0, 32, vcc
	v_ldexp_f32 v30, v30, v36
	v_log_f32_e32 v30, v30
	v_add_f32_e32 v37, 1.0, v37
	v_rcp_f32_e32 v37, v37
	v_mul_f32_e32 v36, 0x3f317217, v30
	v_fma_f32 v36, v30, s2, -v36
	v_fmac_f32_e32 v36, 0x3377d1cf, v30
	v_fmac_f32_e32 v36, 0x3f317217, v30
	v_cmp_lt_f32_e64 s[12:13], |v30|, s26
	s_nop 1
	v_cndmask_b32_e64 v30, v30, v36, s[12:13]
	v_cndmask_b32_e32 v36, 0, v226, vcc
	v_sub_f32_e32 v30, v30, v36
	v_sub_f32_e32 v36, 1.0, v31
	v_fma_f32 v31, v37, v36, v31
	v_cmp_gt_f32_e32 vcc, s7, v31
	v_mul_f32_e32 v37, 0xbfb8aa3b, v28
	v_exp_f32_e32 v37, v37
	v_cndmask_b32_e64 v36, 0, 32, vcc
	v_ldexp_f32 v31, v31, v36
	v_log_f32_e32 v31, v31
	v_add_f32_e32 v37, 1.0, v37
	v_rcp_f32_e32 v37, v37
	v_mul_f32_e32 v36, 0x3f317217, v31
	v_fma_f32 v36, v31, s2, -v36
	v_fmac_f32_e32 v36, 0x3377d1cf, v31
	v_fmac_f32_e32 v36, 0x3f317217, v31
	v_cmp_lt_f32_e64 s[12:13], |v31|, s26
	s_nop 1
	v_cndmask_b32_e64 v31, v31, v36, s[12:13]
	v_cndmask_b32_e32 v36, 0, v226, vcc
	v_sub_f32_e32 v31, v31, v36
	v_sub_f32_e32 v36, 1.0, v32
	v_fma_f32 v32, v37, v36, v32
	v_cmp_gt_f32_e32 vcc, s7, v32
	v_mul_f32_e32 v37, 0xbfb8aa3b, v29
	v_exp_f32_e32 v37, v37
	v_cndmask_b32_e64 v36, 0, 32, vcc
	v_ldexp_f32 v32, v32, v36
	v_log_f32_e32 v32, v32
	v_add_f32_e32 v37, 1.0, v37
	v_rcp_f32_e32 v37, v37
	v_mul_f32_e32 v36, 0x3f317217, v32
	v_fma_f32 v36, v32, s2, -v36
	v_fmac_f32_e32 v36, 0x3377d1cf, v32
	v_fmac_f32_e32 v36, 0x3f317217, v32
	v_cmp_lt_f32_e64 s[12:13], |v32|, s26
	s_nop 1
	v_cndmask_b32_e64 v32, v32, v36, s[12:13]
	v_cndmask_b32_e32 v36, 0, v226, vcc
	v_sub_f32_e32 v32, v32, v36
	v_sub_f32_e32 v36, 1.0, v33
	v_fmac_f32_e32 v33, v37, v36
	v_cmp_gt_f32_e32 vcc, s7, v33
	s_nop 1
	v_cndmask_b32_e64 v36, 0, 32, vcc
	v_ldexp_f32 v33, v33, v36
	v_log_f32_e32 v33, v33
	s_nop 0
	v_mul_f32_e32 v36, 0x3f317217, v33
	v_fma_f32 v36, v33, s2, -v36
	v_fmac_f32_e32 v36, 0x3377d1cf, v33
	v_fmac_f32_e32 v36, 0x3f317217, v33
	v_cmp_lt_f32_e64 s[12:13], |v33|, s26
	s_nop 1
	v_cndmask_b32_e64 v33, v33, v36, s[12:13]
	v_cndmask_b32_e32 v36, 0, v226, vcc
	v_sub_f32_e32 v33, v33, v36
	s_mov_b64 s[12:13], 0

.LBB0_1339:
	v_cvt_pk_bf16_f32 v26, v30, v31
	v_cvt_pk_bf16_f32 v27, v32, v33
	s_cmp_gt_i32 s40, 1
	s_mov_b64 s[12:13], -1
	v_mov_b32_e32 v142, v26
	v_mov_b32_e32 v143, v27
	v_bfe_u32 v144, v182, 4, 1
	v_mul_u32_u24_e32 v144, 24, v144
	v_mov_b32_e32 v145, 0
	v_lshl_add_u64 v[146:147], v[34:35], 0, v[144:145]
	v_permlane16_swap_b32_e32 v140, v142
	v_permlane16_swap_b32_e32 v141, v143
	global_store_dwordx4 v[146:147], v[140:143], off
	s_cbranch_scc0 .LBB0_1341
	global_load_dwordx4 v[26:29], v134, s[22:23] offset:128
	v_mul_f32_e32 v31, 0xbfb8aa3b, v22
	v_exp_f32_e32 v31, v31
	s_mov_b32 s2, 0x3f317217
	s_mov_b32 s26, 0x7f800000
	v_add_f32_e32 v31, 1.0, v31
	v_rcp_f32_e32 v31, v31
	s_waitcnt vmcnt(0)
	v_sub_f32_e32 v30, 1.0, v26
	v_fma_f32 v26, v31, v30, v26
	v_cmp_gt_f32_e32 vcc, s7, v26
	v_mul_f32_e32 v31, 0xbfb8aa3b, v23
	v_exp_f32_e32 v31, v31
	v_cndmask_b32_e64 v30, 0, 32, vcc
	v_ldexp_f32 v26, v26, v30
	v_log_f32_e32 v26, v26
	v_add_f32_e32 v31, 1.0, v31
	v_rcp_f32_e32 v31, v31
	v_mul_f32_e32 v30, 0x3f317217, v26
	v_fma_f32 v30, v26, s2, -v30
	v_fmac_f32_e32 v30, 0x3377d1cf, v26
	v_fmac_f32_e32 v30, 0x3f317217, v26
	v_cmp_lt_f32_e64 s[12:13], |v26|, s26
	s_nop 1
	v_cndmask_b32_e64 v26, v26, v30, s[12:13]
	v_cndmask_b32_e32 v30, 0, v226, vcc
	v_sub_f32_e32 v26, v26, v30
	v_sub_f32_e32 v30, 1.0, v27
	v_fma_f32 v27, v31, v30, v27
	v_cmp_gt_f32_e32 vcc, s7, v27
	v_mul_f32_e32 v31, 0xbfb8aa3b, v24
	v_exp_f32_e32 v31, v31
	v_cndmask_b32_e64 v30, 0, 32, vcc
	v_ldexp_f32 v27, v27, v30
	v_log_f32_e32 v27, v27
	v_add_f32_e32 v31, 1.0, v31
	v_rcp_f32_e32 v31, v31
	v_mul_f32_e32 v30, 0x3f317217, v27
	v_fma_f32 v30, v27, s2, -v30
	v_fmac_f32_e32 v30, 0x3377d1cf, v27
	v_fmac_f32_e32 v30, 0x3f317217, v27
	v_cmp_lt_f32_e64 s[12:13], |v27|, s26
	s_nop 1
	v_cndmask_b32_e64 v27, v27, v30, s[12:13]
	v_cndmask_b32_e32 v30, 0, v226, vcc
	v_sub_f32_e32 v27, v27, v30
	v_sub_f32_e32 v30, 1.0, v28
	v_fma_f32 v28, v31, v30, v28
	v_cmp_gt_f32_e32 vcc, s7, v28
	v_mul_f32_e32 v31, 0xbfb8aa3b, v25
	v_exp_f32_e32 v31, v31
	v_cndmask_b32_e64 v30, 0, 32, vcc
	v_ldexp_f32 v28, v28, v30
	v_log_f32_e32 v28, v28
	v_add_f32_e32 v31, 1.0, v31
	v_rcp_f32_e32 v31, v31
	v_mul_f32_e32 v30, 0x3f317217, v28
	v_fma_f32 v30, v28, s2, -v30
	v_fmac_f32_e32 v30, 0x3377d1cf, v28
	v_fmac_f32_e32 v30, 0x3f317217, v28
	v_cmp_lt_f32_e64 s[12:13], |v28|, s26
	s_nop 1
	v_cndmask_b32_e64 v28, v28, v30, s[12:13]
	v_cndmask_b32_e32 v30, 0, v226, vcc
	v_sub_f32_e32 v28, v28, v30
	v_sub_f32_e32 v30, 1.0, v29
	v_fmac_f32_e32 v29, v31, v30
	v_cmp_gt_f32_e32 vcc, s7, v29
	s_nop 1
	v_cndmask_b32_e64 v30, 0, 32, vcc
	v_ldexp_f32 v29, v29, v30
	v_log_f32_e32 v29, v29
	s_nop 0
	v_mul_f32_e32 v30, 0x3f317217, v29
	v_fma_f32 v30, v29, s2, -v30
	v_fmac_f32_e32 v30, 0x3377d1cf, v29
	v_fmac_f32_e32 v30, 0x3f317217, v29
	v_cmp_lt_f32_e64 s[12:13], |v29|, s26
	s_nop 1
	v_cndmask_b32_e64 v29, v29, v30, s[12:13]
	v_cndmask_b32_e32 v30, 0, v226, vcc
	v_sub_f32_e32 v29, v29, v30
	s_mov_b64 s[12:13], 0

.LBB0_1345:
	v_cvt_pk_bf16_f32 v22, v26, v27
	v_cvt_pk_bf16_f32 v23, v28, v29
	s_cmp_gt_i32 s40, 1
	s_mov_b64 s[12:13], -1
	v_mov_b32_e32 v140, v22
	v_mov_b32_e32 v141, v23
	s_cbranch_scc0 .LBB0_1347
	global_load_dwordx4 v[22:25], v134, s[22:23] offset:192
	v_mul_f32_e32 v27, 0xbfb8aa3b, v18
	v_exp_f32_e32 v27, v27
	s_mov_b32 s2, 0x3f317217
	s_mov_b32 s26, 0x7f800000
	v_add_f32_e32 v27, 1.0, v27
	v_rcp_f32_e32 v27, v27
	s_waitcnt vmcnt(0)
	v_sub_f32_e32 v26, 1.0, v22
	v_fma_f32 v22, v27, v26, v22
	v_cmp_gt_f32_e32 vcc, s7, v22
	v_mul_f32_e32 v27, 0xbfb8aa3b, v19
	v_exp_f32_e32 v27, v27
	v_cndmask_b32_e64 v26, 0, 32, vcc
	v_ldexp_f32 v22, v22, v26
	v_log_f32_e32 v22, v22
	v_add_f32_e32 v27, 1.0, v27
	v_rcp_f32_e32 v27, v27
	v_mul_f32_e32 v26, 0x3f317217, v22
	v_fma_f32 v26, v22, s2, -v26
	v_fmac_f32_e32 v26, 0x3377d1cf, v22
	v_fmac_f32_e32 v26, 0x3f317217, v22
	v_cmp_lt_f32_e64 s[12:13], |v22|, s26
	s_nop 1
	v_cndmask_b32_e64 v22, v22, v26, s[12:13]
	v_cndmask_b32_e32 v26, 0, v226, vcc
	v_sub_f32_e32 v22, v22, v26
	v_sub_f32_e32 v26, 1.0, v23
	v_fma_f32 v23, v27, v26, v23
	v_cmp_gt_f32_e32 vcc, s7, v23
	v_mul_f32_e32 v27, 0xbfb8aa3b, v20
	v_exp_f32_e32 v27, v27
	v_cndmask_b32_e64 v26, 0, 32, vcc
	v_ldexp_f32 v23, v23, v26
	v_log_f32_e32 v23, v23
	v_add_f32_e32 v27, 1.0, v27
	v_rcp_f32_e32 v27, v27
	v_mul_f32_e32 v26, 0x3f317217, v23
	v_fma_f32 v26, v23, s2, -v26
	v_fmac_f32_e32 v26, 0x3377d1cf, v23
	v_fmac_f32_e32 v26, 0x3f317217, v23
	v_cmp_lt_f32_e64 s[12:13], |v23|, s26
	s_nop 1
	v_cndmask_b32_e64 v23, v23, v26, s[12:13]
	v_cndmask_b32_e32 v26, 0, v226, vcc
	v_sub_f32_e32 v23, v23, v26
	v_sub_f32_e32 v26, 1.0, v24
	v_fma_f32 v24, v27, v26, v24
	v_cmp_gt_f32_e32 vcc, s7, v24
	v_mul_f32_e32 v27, 0xbfb8aa3b, v21
	v_exp_f32_e32 v27, v27
	v_cndmask_b32_e64 v26, 0, 32, vcc
	v_ldexp_f32 v24, v24, v26
	v_log_f32_e32 v24, v24
	v_add_f32_e32 v27, 1.0, v27
	v_rcp_f32_e32 v27, v27
	v_mul_f32_e32 v26, 0x3f317217, v24
	v_fma_f32 v26, v24, s2, -v26
	v_fmac_f32_e32 v26, 0x3377d1cf, v24
	v_fmac_f32_e32 v26, 0x3f317217, v24
	v_cmp_lt_f32_e64 s[12:13], |v24|, s26
	s_nop 1
	v_cndmask_b32_e64 v24, v24, v26, s[12:13]
	v_cndmask_b32_e32 v26, 0, v226, vcc
	v_sub_f32_e32 v24, v24, v26
	v_sub_f32_e32 v26, 1.0, v25
	v_fmac_f32_e32 v25, v27, v26
	v_cmp_gt_f32_e32 vcc, s7, v25
	s_nop 1
	v_cndmask_b32_e64 v26, 0, 32, vcc
	v_ldexp_f32 v25, v25, v26
	v_log_f32_e32 v25, v25
	s_nop 0
	v_mul_f32_e32 v26, 0x3f317217, v25
	v_fma_f32 v26, v25, s2, -v26
	v_fmac_f32_e32 v26, 0x3377d1cf, v25
	v_fmac_f32_e32 v26, 0x3f317217, v25
	v_cmp_lt_f32_e64 s[12:13], |v25|, s26
	s_nop 1
	v_cndmask_b32_e64 v25, v25, v26, s[12:13]
	v_cndmask_b32_e32 v26, 0, v226, vcc
	v_sub_f32_e32 v25, v25, v26
	s_mov_b64 s[12:13], 0

.LBB0_1351:
	v_cvt_pk_bf16_f32 v18, v22, v23
	v_cvt_pk_bf16_f32 v19, v24, v25
	v_mov_b32_e32 v142, v18
	v_mov_b32_e32 v143, v19
	v_bfe_u32 v144, v182, 4, 1
	v_mul_u32_u24_e32 v144, 24, v144
	v_mov_b32_e32 v145, 0
	v_lshl_add_u64 v[146:147], v[34:35], 0, v[144:145]
	v_permlane16_swap_b32_e32 v140, v142
	v_permlane16_swap_b32_e32 v141, v143
	global_store_dwordx4 v[146:147], v[140:143], off offset:64
	s_cmp_gt_i32 s40, 1
	s_mov_b64 s[12:13], -1
	s_cbranch_scc0 .LBB0_1353
	global_load_dwordx4 v[18:21], v134, s[22:23]
	v_mul_f32_e32 v23, 0xbfb8aa3b, v14
	v_exp_f32_e32 v23, v23
	s_mov_b32 s2, 0x3f317217
	s_mov_b32 s26, 0x7f800000
	v_add_f32_e32 v23, 1.0, v23
	v_rcp_f32_e32 v23, v23
	s_waitcnt vmcnt(0)
	v_sub_f32_e32 v22, 1.0, v18
	v_fma_f32 v18, v23, v22, v18
	v_cmp_gt_f32_e32 vcc, s7, v18
	v_mul_f32_e32 v23, 0xbfb8aa3b, v15
	v_exp_f32_e32 v23, v23
	v_cndmask_b32_e64 v22, 0, 32, vcc
	v_ldexp_f32 v18, v18, v22
	v_log_f32_e32 v18, v18
	v_add_f32_e32 v23, 1.0, v23
	v_rcp_f32_e32 v23, v23
	v_mul_f32_e32 v22, 0x3f317217, v18
	v_fma_f32 v22, v18, s2, -v22
	v_fmac_f32_e32 v22, 0x3377d1cf, v18
	v_fmac_f32_e32 v22, 0x3f317217, v18
	v_cmp_lt_f32_e64 s[12:13], |v18|, s26
	s_nop 1
	v_cndmask_b32_e64 v18, v18, v22, s[12:13]
	v_cndmask_b32_e32 v22, 0, v226, vcc
	v_sub_f32_e32 v18, v18, v22
	v_sub_f32_e32 v22, 1.0, v19
	v_fma_f32 v19, v23, v22, v19
	v_cmp_gt_f32_e32 vcc, s7, v19
	v_mul_f32_e32 v23, 0xbfb8aa3b, v16
	v_exp_f32_e32 v23, v23
	v_cndmask_b32_e64 v22, 0, 32, vcc
	v_ldexp_f32 v19, v19, v22
	v_log_f32_e32 v19, v19
	v_add_f32_e32 v23, 1.0, v23
	v_rcp_f32_e32 v23, v23
	v_mul_f32_e32 v22, 0x3f317217, v19
	v_fma_f32 v22, v19, s2, -v22
	v_fmac_f32_e32 v22, 0x3377d1cf, v19
	v_fmac_f32_e32 v22, 0x3f317217, v19
	v_cmp_lt_f32_e64 s[12:13], |v19|, s26
	s_nop 1
	v_cndmask_b32_e64 v19, v19, v22, s[12:13]
	v_cndmask_b32_e32 v22, 0, v226, vcc
	v_sub_f32_e32 v19, v19, v22
	v_sub_f32_e32 v22, 1.0, v20
	v_fma_f32 v20, v23, v22, v20
	v_cmp_gt_f32_e32 vcc, s7, v20
	v_mul_f32_e32 v23, 0xbfb8aa3b, v17
	v_exp_f32_e32 v23, v23
	v_cndmask_b32_e64 v22, 0, 32, vcc
	v_ldexp_f32 v20, v20, v22
	v_log_f32_e32 v20, v20
	v_add_f32_e32 v23, 1.0, v23
	v_rcp_f32_e32 v23, v23
	v_mul_f32_e32 v22, 0x3f317217, v20
	v_fma_f32 v22, v20, s2, -v22
	v_fmac_f32_e32 v22, 0x3377d1cf, v20
	v_fmac_f32_e32 v22, 0x3f317217, v20
	v_cmp_lt_f32_e64 s[12:13], |v20|, s26
	s_nop 1
	v_cndmask_b32_e64 v20, v20, v22, s[12:13]
	v_cndmask_b32_e32 v22, 0, v226, vcc
	v_sub_f32_e32 v20, v20, v22
	v_sub_f32_e32 v22, 1.0, v21
	v_fmac_f32_e32 v21, v23, v22
	v_cmp_gt_f32_e32 vcc, s7, v21
	s_nop 1
	v_cndmask_b32_e64 v22, 0, 32, vcc
	v_ldexp_f32 v21, v21, v22
	v_log_f32_e32 v21, v21
	s_nop 0
	v_mul_f32_e32 v22, 0x3f317217, v21
	v_fma_f32 v22, v21, s2, -v22
	v_fmac_f32_e32 v22, 0x3377d1cf, v21
	v_fmac_f32_e32 v22, 0x3f317217, v21
	v_cmp_lt_f32_e64 s[12:13], |v21|, s26
	s_nop 1
	v_cndmask_b32_e64 v21, v21, v22, s[12:13]
	v_cndmask_b32_e32 v22, 0, v226, vcc
	v_sub_f32_e32 v21, v21, v22
	s_mov_b64 s[12:13], 0

.LBB0_1357:
	v_lshl_add_u64 v[16:17], s[24:25], 0, v[210:211]
	v_cvt_pk_bf16_f32 v14, v18, v19
	v_cvt_pk_bf16_f32 v15, v20, v21
	v_lshl_add_u64 v[18:19], v[16:17], 0, v[0:1]
	s_cmp_gt_i32 s40, 1
	s_mov_b64 s[12:13], -1
	v_mov_b32_e32 v140, v14
	v_mov_b32_e32 v141, v15
	s_cbranch_scc0 .LBB0_1359
	global_load_dwordx4 v[14:17], v134, s[22:23] offset:64
	v_mul_f32_e32 v21, 0xbfb8aa3b, v10
	v_exp_f32_e32 v21, v21
	s_mov_b32 s2, 0x3f317217
	s_mov_b32 s24, 0x7f800000
	v_add_f32_e32 v21, 1.0, v21
	v_rcp_f32_e32 v21, v21
	s_waitcnt vmcnt(0)
	v_sub_f32_e32 v20, 1.0, v14
	v_fma_f32 v14, v21, v20, v14
	v_cmp_gt_f32_e32 vcc, s7, v14
	v_mul_f32_e32 v21, 0xbfb8aa3b, v11
	v_exp_f32_e32 v21, v21
	v_cndmask_b32_e64 v20, 0, 32, vcc
	v_ldexp_f32 v14, v14, v20
	v_log_f32_e32 v14, v14
	v_add_f32_e32 v21, 1.0, v21
	v_rcp_f32_e32 v21, v21
	v_mul_f32_e32 v20, 0x3f317217, v14
	v_fma_f32 v20, v14, s2, -v20
	v_fmac_f32_e32 v20, 0x3377d1cf, v14
	v_fmac_f32_e32 v20, 0x3f317217, v14
	v_cmp_lt_f32_e64 s[12:13], |v14|, s24
	s_nop 1
	v_cndmask_b32_e64 v14, v14, v20, s[12:13]
	v_cndmask_b32_e32 v20, 0, v226, vcc
	v_sub_f32_e32 v14, v14, v20
	v_sub_f32_e32 v20, 1.0, v15
	v_fma_f32 v15, v21, v20, v15
	v_cmp_gt_f32_e32 vcc, s7, v15
	v_mul_f32_e32 v21, 0xbfb8aa3b, v12
	v_exp_f32_e32 v21, v21
	v_cndmask_b32_e64 v20, 0, 32, vcc
	v_ldexp_f32 v15, v15, v20
	v_log_f32_e32 v15, v15
	v_add_f32_e32 v21, 1.0, v21
	v_rcp_f32_e32 v21, v21
	v_mul_f32_e32 v20, 0x3f317217, v15
	v_fma_f32 v20, v15, s2, -v20
	v_fmac_f32_e32 v20, 0x3377d1cf, v15
	v_fmac_f32_e32 v20, 0x3f317217, v15
	v_cmp_lt_f32_e64 s[12:13], |v15|, s24
	s_nop 1
	v_cndmask_b32_e64 v15, v15, v20, s[12:13]
	v_cndmask_b32_e32 v20, 0, v226, vcc
	v_sub_f32_e32 v15, v15, v20
	v_sub_f32_e32 v20, 1.0, v16
	v_fma_f32 v16, v21, v20, v16
	v_cmp_gt_f32_e32 vcc, s7, v16
	v_mul_f32_e32 v21, 0xbfb8aa3b, v13
	v_exp_f32_e32 v21, v21
	v_cndmask_b32_e64 v20, 0, 32, vcc
	v_ldexp_f32 v16, v16, v20
	v_log_f32_e32 v16, v16
	v_add_f32_e32 v21, 1.0, v21
	v_rcp_f32_e32 v21, v21
	v_mul_f32_e32 v20, 0x3f317217, v16
	v_fma_f32 v20, v16, s2, -v20
	v_fmac_f32_e32 v20, 0x3377d1cf, v16
	v_fmac_f32_e32 v20, 0x3f317217, v16
	v_cmp_lt_f32_e64 s[12:13], |v16|, s24
	s_nop 1
	v_cndmask_b32_e64 v16, v16, v20, s[12:13]
	v_cndmask_b32_e32 v20, 0, v226, vcc
	v_sub_f32_e32 v16, v16, v20
	v_sub_f32_e32 v20, 1.0, v17
	v_fmac_f32_e32 v17, v21, v20
	v_cmp_gt_f32_e32 vcc, s7, v17
	s_nop 1
	v_cndmask_b32_e64 v20, 0, 32, vcc
	v_ldexp_f32 v17, v17, v20
	v_log_f32_e32 v17, v17
	s_nop 0
	v_mul_f32_e32 v20, 0x3f317217, v17
	v_fma_f32 v20, v17, s2, -v20
	v_fmac_f32_e32 v20, 0x3377d1cf, v17
	v_fmac_f32_e32 v20, 0x3f317217, v17
	v_cmp_lt_f32_e64 s[12:13], |v17|, s24
	s_nop 1
	v_cndmask_b32_e64 v17, v17, v20, s[12:13]
	v_cndmask_b32_e32 v20, 0, v226, vcc
	v_sub_f32_e32 v17, v17, v20
	s_mov_b64 s[12:13], 0

.LBB0_1363:
	v_cvt_pk_bf16_f32 v10, v14, v15
	v_cvt_pk_bf16_f32 v11, v16, v17
	s_cmp_gt_i32 s40, 1
	s_mov_b64 s[12:13], -1
	v_mov_b32_e32 v142, v10
	v_mov_b32_e32 v143, v11
	v_bfe_u32 v144, v182, 4, 1
	v_mul_u32_u24_e32 v144, 24, v144
	v_mov_b32_e32 v145, 0
	v_lshl_add_u64 v[146:147], v[18:19], 0, v[144:145]
	v_permlane16_swap_b32_e32 v140, v142
	v_permlane16_swap_b32_e32 v141, v143
	global_store_dwordx4 v[146:147], v[140:143], off
	s_cbranch_scc0 .LBB0_1365
	global_load_dwordx4 v[10:13], v134, s[22:23] offset:128
	v_mul_f32_e32 v15, 0xbfb8aa3b, v6
	v_exp_f32_e32 v15, v15
	s_mov_b32 s2, 0x3f317217
	s_mov_b32 s24, 0x7f800000
	v_add_f32_e32 v15, 1.0, v15
	v_rcp_f32_e32 v15, v15
	s_waitcnt vmcnt(0)
	v_sub_f32_e32 v14, 1.0, v10
	v_fma_f32 v10, v15, v14, v10
	v_cmp_gt_f32_e32 vcc, s7, v10
	v_mul_f32_e32 v15, 0xbfb8aa3b, v7
	v_exp_f32_e32 v15, v15
	v_cndmask_b32_e64 v14, 0, 32, vcc
	v_ldexp_f32 v10, v10, v14
	v_log_f32_e32 v10, v10
	v_add_f32_e32 v15, 1.0, v15
	v_rcp_f32_e32 v15, v15
	v_mul_f32_e32 v14, 0x3f317217, v10
	v_fma_f32 v14, v10, s2, -v14
	v_fmac_f32_e32 v14, 0x3377d1cf, v10
	v_fmac_f32_e32 v14, 0x3f317217, v10
	v_cmp_lt_f32_e64 s[12:13], |v10|, s24
	s_nop 1
	v_cndmask_b32_e64 v10, v10, v14, s[12:13]
	v_cndmask_b32_e32 v14, 0, v226, vcc
	v_sub_f32_e32 v10, v10, v14
	v_sub_f32_e32 v14, 1.0, v11
	v_fma_f32 v11, v15, v14, v11
	v_cmp_gt_f32_e32 vcc, s7, v11
	v_mul_f32_e32 v15, 0xbfb8aa3b, v8
	v_exp_f32_e32 v15, v15
	v_cndmask_b32_e64 v14, 0, 32, vcc
	v_ldexp_f32 v11, v11, v14
	v_log_f32_e32 v11, v11
	v_add_f32_e32 v15, 1.0, v15
	v_rcp_f32_e32 v15, v15
	v_mul_f32_e32 v14, 0x3f317217, v11
	v_fma_f32 v14, v11, s2, -v14
	v_fmac_f32_e32 v14, 0x3377d1cf, v11
	v_fmac_f32_e32 v14, 0x3f317217, v11
	v_cmp_lt_f32_e64 s[12:13], |v11|, s24
	s_nop 1
	v_cndmask_b32_e64 v11, v11, v14, s[12:13]
	v_cndmask_b32_e32 v14, 0, v226, vcc
	v_sub_f32_e32 v11, v11, v14
	v_sub_f32_e32 v14, 1.0, v12
	v_fma_f32 v12, v15, v14, v12
	v_cmp_gt_f32_e32 vcc, s7, v12
	v_mul_f32_e32 v15, 0xbfb8aa3b, v9
	v_exp_f32_e32 v15, v15
	v_cndmask_b32_e64 v14, 0, 32, vcc
	v_ldexp_f32 v12, v12, v14
	v_log_f32_e32 v12, v12
	v_add_f32_e32 v15, 1.0, v15
	v_rcp_f32_e32 v15, v15
	v_mul_f32_e32 v14, 0x3f317217, v12
	v_fma_f32 v14, v12, s2, -v14
	v_fmac_f32_e32 v14, 0x3377d1cf, v12
	v_fmac_f32_e32 v14, 0x3f317217, v12
	v_cmp_lt_f32_e64 s[12:13], |v12|, s24
	s_nop 1
	v_cndmask_b32_e64 v12, v12, v14, s[12:13]
	v_cndmask_b32_e32 v14, 0, v226, vcc
	v_sub_f32_e32 v12, v12, v14
	v_sub_f32_e32 v14, 1.0, v13
	v_fmac_f32_e32 v13, v15, v14
	v_cmp_gt_f32_e32 vcc, s7, v13
	s_nop 1
	v_cndmask_b32_e64 v14, 0, 32, vcc
	v_ldexp_f32 v13, v13, v14
	v_log_f32_e32 v13, v13
	s_nop 0
	v_mul_f32_e32 v14, 0x3f317217, v13
	v_fma_f32 v14, v13, s2, -v14
	v_fmac_f32_e32 v14, 0x3377d1cf, v13
	v_fmac_f32_e32 v14, 0x3f317217, v13
	v_cmp_lt_f32_e64 s[12:13], |v13|, s24
	s_nop 1
	v_cndmask_b32_e64 v13, v13, v14, s[12:13]
	v_cndmask_b32_e32 v14, 0, v226, vcc
	v_sub_f32_e32 v13, v13, v14
	s_mov_b64 s[12:13], 0

.LBB0_1369:
	v_cvt_pk_bf16_f32 v6, v10, v11
	v_cvt_pk_bf16_f32 v7, v12, v13
	s_cmp_gt_i32 s40, 1
	s_mov_b64 s[12:13], -1
	v_mov_b32_e32 v140, v6
	v_mov_b32_e32 v141, v7
	s_cbranch_scc0 .LBB0_1371
	global_load_dwordx4 v[6:9], v134, s[22:23] offset:192
	v_mul_f32_e32 v11, 0xbfb8aa3b, v2
	v_exp_f32_e32 v11, v11
	s_mov_b32 s2, 0x3f317217
	s_mov_b32 s22, 0x7f800000
	v_add_f32_e32 v11, 1.0, v11
	v_rcp_f32_e32 v11, v11
	s_waitcnt vmcnt(0)
	v_sub_f32_e32 v10, 1.0, v6
	v_fma_f32 v6, v11, v10, v6
	v_cmp_gt_f32_e32 vcc, s7, v6
	v_mul_f32_e32 v11, 0xbfb8aa3b, v3
	v_exp_f32_e32 v11, v11
	v_cndmask_b32_e64 v10, 0, 32, vcc
	v_ldexp_f32 v6, v6, v10
	v_log_f32_e32 v6, v6
	v_add_f32_e32 v11, 1.0, v11
	v_rcp_f32_e32 v11, v11
	v_mul_f32_e32 v10, 0x3f317217, v6
	v_fma_f32 v10, v6, s2, -v10
	v_fmac_f32_e32 v10, 0x3377d1cf, v6
	v_fmac_f32_e32 v10, 0x3f317217, v6
	v_cmp_lt_f32_e64 s[12:13], |v6|, s22
	s_nop 1
	v_cndmask_b32_e64 v6, v6, v10, s[12:13]
	v_cndmask_b32_e32 v10, 0, v226, vcc
	v_sub_f32_e32 v6, v6, v10
	v_sub_f32_e32 v10, 1.0, v7
	v_fma_f32 v7, v11, v10, v7
	v_cmp_gt_f32_e32 vcc, s7, v7
	v_mul_f32_e32 v11, 0xbfb8aa3b, v4
	v_exp_f32_e32 v11, v11
	v_cndmask_b32_e64 v10, 0, 32, vcc
	v_ldexp_f32 v7, v7, v10
	v_log_f32_e32 v7, v7
	v_add_f32_e32 v11, 1.0, v11
	v_rcp_f32_e32 v11, v11
	v_mul_f32_e32 v10, 0x3f317217, v7
	v_fma_f32 v10, v7, s2, -v10
	v_fmac_f32_e32 v10, 0x3377d1cf, v7
	v_fmac_f32_e32 v10, 0x3f317217, v7
	v_cmp_lt_f32_e64 s[12:13], |v7|, s22
	s_nop 1
	v_cndmask_b32_e64 v7, v7, v10, s[12:13]
	v_cndmask_b32_e32 v10, 0, v226, vcc
	v_sub_f32_e32 v7, v7, v10
	v_sub_f32_e32 v10, 1.0, v8
	v_fma_f32 v8, v11, v10, v8
	v_cmp_gt_f32_e32 vcc, s7, v8
	v_mul_f32_e32 v11, 0xbfb8aa3b, v5
	v_exp_f32_e32 v11, v11
	v_cndmask_b32_e64 v10, 0, 32, vcc
	v_ldexp_f32 v8, v8, v10
	v_log_f32_e32 v8, v8
	v_add_f32_e32 v11, 1.0, v11
	v_rcp_f32_e32 v11, v11
	v_mul_f32_e32 v10, 0x3f317217, v8
	v_fma_f32 v10, v8, s2, -v10
	v_fmac_f32_e32 v10, 0x3377d1cf, v8
	v_fmac_f32_e32 v10, 0x3f317217, v8
	v_cmp_lt_f32_e64 s[12:13], |v8|, s22
	s_nop 1
	v_cndmask_b32_e64 v8, v8, v10, s[12:13]
	v_cndmask_b32_e32 v10, 0, v226, vcc
	v_sub_f32_e32 v8, v8, v10
	v_sub_f32_e32 v10, 1.0, v9
	v_fmac_f32_e32 v9, v11, v10
	v_cmp_gt_f32_e32 vcc, s7, v9
	s_nop 1
	v_cndmask_b32_e64 v10, 0, 32, vcc
	v_ldexp_f32 v9, v9, v10
	v_log_f32_e32 v9, v9
	s_nop 0
	v_mul_f32_e32 v10, 0x3f317217, v9
	v_fma_f32 v10, v9, s2, -v10
	v_fmac_f32_e32 v10, 0x3377d1cf, v9
	v_fmac_f32_e32 v10, 0x3f317217, v9
	v_cmp_lt_f32_e64 s[12:13], |v9|, s22
	s_nop 1
	v_cndmask_b32_e64 v9, v9, v10, s[12:13]
	v_cndmask_b32_e32 v10, 0, v226, vcc
	v_sub_f32_e32 v9, v9, v10
	s_mov_b64 s[12:13], 0

.LBB0_1375:
	v_cvt_pk_bf16_f32 v2, v6, v7
	v_cvt_pk_bf16_f32 v3, v8, v9
	v_mov_b32_e32 v142, v2
	v_mov_b32_e32 v143, v3
	v_bfe_u32 v144, v182, 4, 1
	v_mul_u32_u24_e32 v144, 24, v144
	v_mov_b32_e32 v145, 0
	v_lshl_add_u64 v[146:147], v[18:19], 0, v[144:145]
	v_permlane16_swap_b32_e32 v140, v142
	v_permlane16_swap_b32_e32 v141, v143
	global_store_dwordx4 v[146:147], v[140:143], off offset:64
	s_andn2_b64 vcc, exec, s[20:21]
	s_mov_b64 s[12:13], -1
	s_cbranch_vccnz .LBB0_1162
	s_mov_b64 s[12:13], 0
	s_branch .LBB0_1162

; __device__ __forceinline__ void run_op(int layer, int op) {
;     ...
;         [&](int pm, int pn) { const int bg = pm >> 2, rt = pm & 3; return EpiBF{(bfr*)(R + R_S5_X) + ((long)bg * 1024 + rt * 256) * 256, 256, 0, nullptr}; }); break;
.LBB0_1479:
	s_ashr_i32 s18, s34, 2
	s_ashr_i32 s19, s18, 31
	s_lshl_b64 s[18:19], s[18:19], 19
	s_add_u32 s2, s29, s18
	s_addc_u32 s19, s30, s19
	s_lshl_b32 s18, s34, 17
	s_and_b32 s18, s18, 0x60000
	s_add_u32 s18, s2, s18
	s_addc_u32 s19, s19, 0
	v_cvt_pk_bf16_f32 v126, v126, v127
	v_cvt_pk_bf16_f32 v127, v128, v129
	v_lshl_add_u64 v[128:129], s[18:19], 0, v[196:197]
	v_lshl_add_u64 v[128:129], v[128:129], 0, v[0:1]
	v_mov_b32_e32 v150, v126
	v_mov_b32_e32 v151, v127
	v_cvt_pk_bf16_f32 v122, v122, v123
	v_cvt_pk_bf16_f32 v123, v124, v125
	v_mov_b32_e32 v152, v122
	v_mov_b32_e32 v153, v123
	v_bfe_u32 v154, v182, 4, 1
	v_mul_u32_u24_e32 v154, 24, v154
	v_mov_b32_e32 v155, 0
	v_lshl_add_u64 v[156:157], v[128:129], 0, v[154:155]
	v_permlane16_swap_b32_e32 v150, v152
	v_permlane16_swap_b32_e32 v151, v153
	global_store_dwordx4 v[156:157], v[150:153], off
	v_cvt_pk_bf16_f32 v118, v118, v119
	v_cvt_pk_bf16_f32 v119, v120, v121
	v_mov_b32_e32 v150, v118
	v_mov_b32_e32 v151, v119
	v_cvt_pk_bf16_f32 v114, v114, v115
	v_cvt_pk_bf16_f32 v115, v116, v117
	v_mov_b32_e32 v152, v114
	v_mov_b32_e32 v153, v115
	v_bfe_u32 v154, v182, 4, 1
	v_mul_u32_u24_e32 v154, 24, v154
	v_mov_b32_e32 v155, 0
	v_lshl_add_u64 v[156:157], v[128:129], 0, v[154:155]
	v_permlane16_swap_b32_e32 v150, v152
	v_permlane16_swap_b32_e32 v151, v153
	global_store_dwordx4 v[156:157], v[150:153], off offset:64
	v_cvt_pk_bf16_f32 v110, v110, v111
	v_cvt_pk_bf16_f32 v111, v112, v113
	v_lshl_add_u64 v[112:113], s[18:19], 0, v[198:199]
	v_lshl_add_u64 v[112:113], v[112:113], 0, v[0:1]
	v_mov_b32_e32 v150, v110
	v_mov_b32_e32 v151, v111
	v_cvt_pk_bf16_f32 v106, v106, v107
	v_cvt_pk_bf16_f32 v107, v108, v109
	v_mov_b32_e32 v152, v106
	v_mov_b32_e32 v153, v107
	v_bfe_u32 v154, v182, 4, 1
	v_mul_u32_u24_e32 v154, 24, v154
	v_mov_b32_e32 v155, 0
	v_lshl_add_u64 v[156:157], v[112:113], 0, v[154:155]
	v_permlane16_swap_b32_e32 v150, v152
	v_permlane16_swap_b32_e32 v151, v153
	global_store_dwordx4 v[156:157], v[150:153], off
	v_cvt_pk_bf16_f32 v102, v102, v103
	v_cvt_pk_bf16_f32 v103, v104, v105
	v_mov_b32_e32 v150, v102
	v_mov_b32_e32 v151, v103
	v_cvt_pk_bf16_f32 v98, v98, v99
	v_cvt_pk_bf16_f32 v99, v100, v101
	v_mov_b32_e32 v152, v98
	v_mov_b32_e32 v153, v99
	v_bfe_u32 v154, v182, 4, 1
	v_mul_u32_u24_e32 v154, 24, v154
	v_mov_b32_e32 v155, 0
	v_lshl_add_u64 v[156:157], v[112:113], 0, v[154:155]
	v_permlane16_swap_b32_e32 v150, v152
	v_permlane16_swap_b32_e32 v151, v153
	global_store_dwordx4 v[156:157], v[150:153], off offset:64
	v_cvt_pk_bf16_f32 v94, v94, v95
	v_cvt_pk_bf16_f32 v95, v96, v97
	v_lshl_add_u64 v[96:97], s[18:19], 0, v[200:201]
	v_lshl_add_u64 v[96:97], v[96:97], 0, v[0:1]
	v_mov_b32_e32 v150, v94
	v_mov_b32_e32 v151, v95
	v_cvt_pk_bf16_f32 v90, v90, v91
	v_cvt_pk_bf16_f32 v91, v92, v93
	v_mov_b32_e32 v152, v90
	v_mov_b32_e32 v153, v91
	v_bfe_u32 v154, v182, 4, 1
	v_mul_u32_u24_e32 v154, 24, v154
	v_mov_b32_e32 v155, 0
	v_lshl_add_u64 v[156:157], v[96:97], 0, v[154:155]
	v_permlane16_swap_b32_e32 v150, v152
	v_permlane16_swap_b32_e32 v151, v153
	global_store_dwordx4 v[156:157], v[150:153], off
	v_cvt_pk_bf16_f32 v86, v86, v87
	v_cvt_pk_bf16_f32 v87, v88, v89
	v_mov_b32_e32 v150, v86
	v_mov_b32_e32 v151, v87
	v_cvt_pk_bf16_f32 v82, v82, v83
	v_cvt_pk_bf16_f32 v83, v84, v85
	v_mov_b32_e32 v152, v82
	v_mov_b32_e32 v153, v83
	v_bfe_u32 v154, v182, 4, 1
	v_mul_u32_u24_e32 v154, 24, v154
	v_mov_b32_e32 v155, 0
	v_lshl_add_u64 v[156:157], v[96:97], 0, v[154:155]
	v_permlane16_swap_b32_e32 v150, v152
	v_permlane16_swap_b32_e32 v151, v153
	global_store_dwordx4 v[156:157], v[150:153], off offset:64
	v_cvt_pk_bf16_f32 v78, v78, v79
	v_cvt_pk_bf16_f32 v79, v80, v81
	v_lshl_add_u64 v[80:81], s[18:19], 0, v[202:203]
	v_lshl_add_u64 v[80:81], v[80:81], 0, v[0:1]
	v_mov_b32_e32 v150, v78
	v_mov_b32_e32 v151, v79
	v_cvt_pk_bf16_f32 v74, v74, v75
	v_cvt_pk_bf16_f32 v75, v76, v77
	v_mov_b32_e32 v152, v74
	v_mov_b32_e32 v153, v75
	v_bfe_u32 v154, v182, 4, 1
	v_mul_u32_u24_e32 v154, 24, v154
	v_mov_b32_e32 v155, 0
	v_lshl_add_u64 v[156:157], v[80:81], 0, v[154:155]
	v_permlane16_swap_b32_e32 v150, v152
	v_permlane16_swap_b32_e32 v151, v153
	global_store_dwordx4 v[156:157], v[150:153], off
	v_cvt_pk_bf16_f32 v70, v70, v71
	v_cvt_pk_bf16_f32 v71, v72, v73
	v_mov_b32_e32 v150, v70
	v_mov_b32_e32 v151, v71
	v_cvt_pk_bf16_f32 v66, v66, v67
	v_cvt_pk_bf16_f32 v67, v68, v69
	v_mov_b32_e32 v152, v66
	v_mov_b32_e32 v153, v67
	v_bfe_u32 v154, v182, 4, 1
	v_mul_u32_u24_e32 v154, 24, v154
	v_mov_b32_e32 v155, 0
	v_lshl_add_u64 v[156:157], v[80:81], 0, v[154:155]
	v_permlane16_swap_b32_e32 v150, v152
; __device__ __forceinline__ void run_op(int layer, int op) {
;     ...
;         [&](int pm, int pn) { const int bg = pm >> 2, rt = pm & 3; return EpiBF{(bfr*)(R + R_S5_X) + ((long)bg * 1024 + rt * 256) * 256, 256, 0, nullptr}; }); break;
	v_permlane16_swap_b32_e32 v151, v153
	global_store_dwordx4 v[156:157], v[150:153], off offset:64
	v_cvt_pk_bf16_f32 v62, v62, v63
	v_cvt_pk_bf16_f32 v63, v64, v65
	v_lshl_add_u64 v[64:65], s[18:19], 0, v[204:205]
	v_lshl_add_u64 v[64:65], v[64:65], 0, v[0:1]
	v_mov_b32_e32 v150, v62
	v_mov_b32_e32 v151, v63
	v_cvt_pk_bf16_f32 v58, v58, v59
	v_cvt_pk_bf16_f32 v59, v60, v61
	v_mov_b32_e32 v152, v58
	v_mov_b32_e32 v153, v59
	v_bfe_u32 v154, v182, 4, 1
	v_mul_u32_u24_e32 v154, 24, v154
	v_mov_b32_e32 v155, 0
	v_lshl_add_u64 v[156:157], v[64:65], 0, v[154:155]
	v_permlane16_swap_b32_e32 v150, v152
	v_permlane16_swap_b32_e32 v151, v153
	global_store_dwordx4 v[156:157], v[150:153], off
	v_cvt_pk_bf16_f32 v54, v54, v55
	v_cvt_pk_bf16_f32 v55, v56, v57
	v_mov_b32_e32 v150, v54
	v_mov_b32_e32 v151, v55
	v_cvt_pk_bf16_f32 v50, v50, v51
	v_cvt_pk_bf16_f32 v51, v52, v53
	v_mov_b32_e32 v152, v50
	v_mov_b32_e32 v153, v51
	v_bfe_u32 v154, v182, 4, 1
	v_mul_u32_u24_e32 v154, 24, v154
	v_mov_b32_e32 v155, 0
	v_lshl_add_u64 v[156:157], v[64:65], 0, v[154:155]
	v_permlane16_swap_b32_e32 v150, v152
	v_permlane16_swap_b32_e32 v151, v153
	global_store_dwordx4 v[156:157], v[150:153], off offset:64
	v_cvt_pk_bf16_f32 v46, v46, v47
	v_cvt_pk_bf16_f32 v47, v48, v49
	v_lshl_add_u64 v[48:49], s[18:19], 0, v[206:207]
	v_lshl_add_u64 v[48:49], v[48:49], 0, v[0:1]
	v_mov_b32_e32 v150, v46
	v_mov_b32_e32 v151, v47
	v_cvt_pk_bf16_f32 v42, v42, v43
	v_cvt_pk_bf16_f32 v43, v44, v45
	v_mov_b32_e32 v152, v42
	v_mov_b32_e32 v153, v43
	v_bfe_u32 v154, v182, 4, 1
	v_mul_u32_u24_e32 v154, 24, v154
	v_mov_b32_e32 v155, 0
	v_lshl_add_u64 v[156:157], v[48:49], 0, v[154:155]
	v_permlane16_swap_b32_e32 v150, v152
	v_permlane16_swap_b32_e32 v151, v153
	global_store_dwordx4 v[156:157], v[150:153], off
	v_cvt_pk_bf16_f32 v38, v38, v39
	v_cvt_pk_bf16_f32 v39, v40, v41
	v_mov_b32_e32 v150, v38
	v_mov_b32_e32 v151, v39
	v_cvt_pk_bf16_f32 v34, v34, v35
	v_cvt_pk_bf16_f32 v35, v36, v37
	v_mov_b32_e32 v152, v34
	v_mov_b32_e32 v153, v35
	v_bfe_u32 v154, v182, 4, 1
	v_mul_u32_u24_e32 v154, 24, v154
	v_mov_b32_e32 v155, 0
	v_lshl_add_u64 v[156:157], v[48:49], 0, v[154:155]
	v_permlane16_swap_b32_e32 v150, v152
	v_permlane16_swap_b32_e32 v151, v153
	global_store_dwordx4 v[156:157], v[150:153], off offset:64
	v_cvt_pk_bf16_f32 v30, v30, v31
	v_cvt_pk_bf16_f32 v31, v32, v33
	v_lshl_add_u64 v[32:33], s[18:19], 0, v[208:209]
	v_lshl_add_u64 v[32:33], v[32:33], 0, v[0:1]
	v_mov_b32_e32 v150, v30
	v_mov_b32_e32 v151, v31
	v_cvt_pk_bf16_f32 v26, v26, v27
	v_cvt_pk_bf16_f32 v27, v28, v29
	v_mov_b32_e32 v152, v26
	v_mov_b32_e32 v153, v27
	v_bfe_u32 v154, v182, 4, 1
	v_mul_u32_u24_e32 v154, 24, v154
	v_mov_b32_e32 v155, 0
	v_lshl_add_u64 v[156:157], v[32:33], 0, v[154:155]
	v_permlane16_swap_b32_e32 v150, v152
	v_permlane16_swap_b32_e32 v151, v153
	global_store_dwordx4 v[156:157], v[150:153], off
	v_cvt_pk_bf16_f32 v22, v22, v23
	v_cvt_pk_bf16_f32 v23, v24, v25
	v_mov_b32_e32 v150, v22
	v_mov_b32_e32 v151, v23
	v_cvt_pk_bf16_f32 v18, v18, v19
	v_cvt_pk_bf16_f32 v19, v20, v21
	v_mov_b32_e32 v152, v18
	v_mov_b32_e32 v153, v19
	v_bfe_u32 v154, v182, 4, 1
	v_mul_u32_u24_e32 v154, 24, v154
	v_mov_b32_e32 v155, 0
	v_lshl_add_u64 v[156:157], v[32:33], 0, v[154:155]
	v_permlane16_swap_b32_e32 v150, v152
	v_permlane16_swap_b32_e32 v151, v153
	global_store_dwordx4 v[156:157], v[150:153], off offset:64
	v_cvt_pk_bf16_f32 v14, v14, v15
	v_cvt_pk_bf16_f32 v15, v16, v17
	v_lshl_add_u64 v[16:17], s[18:19], 0, v[210:211]
	v_lshl_add_u64 v[16:17], v[16:17], 0, v[0:1]
	v_mov_b32_e32 v150, v14
	v_mov_b32_e32 v151, v15
	v_cvt_pk_bf16_f32 v10, v10, v11
	v_cvt_pk_bf16_f32 v11, v12, v13
	v_mov_b32_e32 v152, v10
	v_mov_b32_e32 v153, v11
	v_bfe_u32 v154, v182, 4, 1
	v_mul_u32_u24_e32 v154, 24, v154
	v_mov_b32_e32 v155, 0
	v_lshl_add_u64 v[156:157], v[16:17], 0, v[154:155]
	v_permlane16_swap_b32_e32 v150, v152
	v_permlane16_swap_b32_e32 v151, v153
	global_store_dwordx4 v[156:157], v[150:153], off
	v_cvt_pk_bf16_f32 v6, v6, v7
	v_cvt_pk_bf16_f32 v7, v8, v9
	v_mov_b32_e32 v150, v6
	v_mov_b32_e32 v151, v7
	v_cvt_pk_bf16_f32 v2, v2, v3
	v_cvt_pk_bf16_f32 v3, v4, v5
	v_mov_b32_e32 v152, v2
	v_mov_b32_e32 v153, v3
	v_bfe_u32 v154, v182, 4, 1
	v_mul_u32_u24_e32 v154, 24, v154
	v_mov_b32_e32 v155, 0
	v_lshl_add_u64 v[156:157], v[16:17], 0, v[154:155]
	v_permlane16_swap_b32_e32 v150, v152
	v_permlane16_swap_b32_e32 v151, v153
	global_store_dwordx4 v[156:157], v[150:153], off offset:64
	s_andn2_b64 vcc, exec, s[16:17]
	s_mov_b64 s[16:17], -1
	s_cbranch_vccnz .LBB0_1458
	s_mov_b64 s[16:17], 0
	s_branch .LBB0_1458
